# speedup vs baseline: 1.0098x; 1.0098x over previous
; #define PG8_STAGE(bufoff, gbase, voff) do { _Pragma("unroll") for (int _i = 0; _i < 2; ++_i) \
;         __builtin_amdgcn_global_load_lds((const unsigned*)((const char*)(gbase) + (voff)[_i]), (LAS unsigned*)(lds + (bufoff) + ldsw + _i * 8192), 16, 0, 0); } while (0)
; #define PG8_LDA(dst, b, h) do { _Pragma("unroll") for (int m = 0; m < 4; ++m) _Pragma("unroll") for (int k = 0; k < 2; ++k) dst[m][k] = *(const LAS bf16x8*)(lds + PG8_SA(b, h) + aoff + m * 2048 + k * 1024); } while (0)
; #define PG8_LDB(dst, b, h) do { _Pragma("unroll") for (int n = 0; n < 2; ++n) _Pragma("unroll") for (int k = 0; k < 2; ++k) dst[n][k] = *(const LAS bf16x8*)(lds + PG8_SB(b, h) + boff + n * 2048 + k * 1024); } while (0)
; #define PG8_MMA(ai, bj, At, Bt) do { __builtin_amdgcn_s_setprio(1); _Pragma("unroll") for (int m = 0; m < 4; ++m) _Pragma("unroll") for (int n = 0; n < 2; ++n) _Pragma("unroll") for (int k = 0; k < 2; ++k) \
;         acc[ai][bj][m][n] = __builtin_amdgcn_mfma_f32_16x16x32_bf16(Bt[n][k], At[m][k], acc[ai][bj][m][n], 0, 0, 0); __builtin_amdgcn_s_setprio(0); } while (0)
; #define PG8_WAIT_L(n) asm volatile("s_waitcnt lgkmcnt(" #n ")" ::: "memory")
; #define PG8_BAR __builtin_amdgcn_s_barrier()
; #define PG8_SCHED __builtin_amdgcn_sched_barrier(0)
; template <class Epi>
; __device__ __forceinline__ void gemm_phase(LAS unsigned char* lds, const Gemm g, const StaticOrder& S, const Epi& E) {
;     ...
;             PG8_LDB(B0, 0, 0); PG8_SCHED; PG8_LDA(At, 0, 0); PG8_STAGE(PG8_SA(1, 1), a1 + hstep, voffA);
;             PG8_WAIT_L(8); PG8_BAR; PG8_WAIT_L(0); PG8_MMA(0, 0, At, B0); PG8_BAR; PG8_SCHED;
;             PG8_LDB(B1, 0, 1); PG8_STAGE(PG8_SB(0, 0), b2, voffB);
;             PG8_BAR; PG8_WAIT_L(0); PG8_MMA(0, 1, At, B1); PG8_BAR;
;             PG8_LDA(At, 0, 1); PG8_STAGE(PG8_SA(0, 0), a2, voffA);
;             PG8_BAR; PG8_WAIT_L(0); PG8_MMA(1, 0, At, B0); PG8_BAR; PG8_SCHED;
.LBB0_155:
	s_add_u32 s16, s8, 0xfff80080
	s_addc_u32 s17, s9, -1
	s_add_i32 s37, 0, 0x10000
	v_add_u32_e32 v0, s37, v149
	ds_read_b128 v[142:145], v0
	ds_read_b128 v[152:155], v0 offset:1024
	ds_read_b128 v[156:159], v0 offset:2048
	ds_read_b128 v[160:163], v0 offset:3072
	s_cmp_eq_u32 s36, 28
	s_cselect_b32 s19, s11, s17
	s_cselect_b32 s18, s30, s16
	s_cselect_b32 s17, s1, s35
	s_cselect_b32 s16, s31, s34
	v_lshl_add_u64 v[146:147], s[8:9], 0, v[138:139]
	s_add_i32 m0, s21, 0xc000
	ds_read_b128 v[164:167], v151
	ds_read_b128 v[168:171], v151 offset:1024
	ds_read_b128 v[172:175], v151 offset:2048
	ds_read_b128 v[176:179], v151 offset:3072
	ds_read_b128 v[180:183], v151 offset:4096
	ds_read_b128 v[184:187], v151 offset:5120
	ds_read_b128 v[188:191], v151 offset:6144
	ds_read_b128 v[192:195], v151 offset:7168
	global_load_lds_dwordx4 v[146:147], off
	v_lshl_add_u64 v[146:147], s[8:9], 0, v[140:141]
	s_add_i32 m0, s21, 0xe000
	s_nop 0
	global_load_lds_dwordx4 v[146:147], off
	s_waitcnt lgkmcnt(8)
	s_barrier
	s_waitcnt lgkmcnt(0)
	s_waitcnt lgkmcnt(0)
	v_mfma_f32_16x16x32_bf16 v[126:129], v[142:145], v[164:167], v[126:129]
	v_mfma_f32_16x16x32_bf16 v[122:125], v[156:159], v[164:167], v[122:125]
	v_mfma_f32_16x16x32_bf16 v[110:113], v[142:145], v[172:175], v[110:113]
	v_mfma_f32_16x16x32_bf16 v[106:109], v[156:159], v[172:175], v[106:109]
	v_mfma_f32_16x16x32_bf16 v[94:97], v[142:145], v[180:183], v[94:97]
	v_mfma_f32_16x16x32_bf16 v[90:93], v[156:159], v[180:183], v[90:93]
	v_mfma_f32_16x16x32_bf16 v[78:81], v[142:145], v[188:191], v[78:81]
	v_mfma_f32_16x16x32_bf16 v[74:77], v[156:159], v[188:191], v[74:77]
	v_mfma_f32_16x16x32_bf16 v[126:129], v[152:155], v[168:171], v[126:129]
	v_mfma_f32_16x16x32_bf16 v[122:125], v[160:163], v[168:171], v[122:125]
	v_mfma_f32_16x16x32_bf16 v[110:113], v[152:155], v[176:179], v[110:113]
	v_mfma_f32_16x16x32_bf16 v[106:109], v[160:163], v[176:179], v[106:109]
	v_mfma_f32_16x16x32_bf16 v[94:97], v[152:155], v[184:187], v[94:97]
	v_mfma_f32_16x16x32_bf16 v[90:93], v[160:163], v[184:187], v[90:93]
	v_mfma_f32_16x16x32_bf16 v[78:81], v[152:155], v[192:195], v[78:81]
	v_mfma_f32_16x16x32_bf16 v[74:77], v[160:163], v[192:195], v[74:77]
	s_barrier
	s_add_i32 s40, 0, 0x14000
	s_add_i32 s37, s37, s20
	v_add_u32_e32 v0, s40, v149
	v_lshl_add_u64 v[146:147], s[16:17], 0, v[134:135]
	s_mov_b32 m0, s37
	ds_read_b128 v[196:199], v0
	ds_read_b128 v[200:203], v0 offset:1024
	ds_read_b128 v[204:207], v0 offset:2048
	ds_read_b128 v[218:221], v0 offset:3072
	global_load_lds_dwordx4 v[146:147], off
	v_lshl_add_u64 v[208:209], s[16:17], 0, v[130:131]
	s_add_i32 m0, s37, 0x2000
	s_nop 0
	global_load_lds_dwordx4 v[208:209], off
	s_barrier
	s_waitcnt lgkmcnt(0)
	s_waitcnt lgkmcnt(0)
	v_mfma_f32_16x16x32_bf16 v[118:121], v[196:199], v[164:167], v[118:121]
	v_mfma_f32_16x16x32_bf16 v[114:117], v[204:207], v[164:167], v[114:117]
	v_mfma_f32_16x16x32_bf16 v[102:105], v[196:199], v[172:175], v[102:105]
	v_mfma_f32_16x16x32_bf16 v[98:101], v[204:207], v[172:175], v[98:101]
	v_mfma_f32_16x16x32_bf16 v[86:89], v[196:199], v[180:183], v[86:89]
	v_mfma_f32_16x16x32_bf16 v[82:85], v[204:207], v[180:183], v[82:85]
	v_mfma_f32_16x16x32_bf16 v[70:73], v[196:199], v[188:191], v[70:73]
	v_mfma_f32_16x16x32_bf16 v[66:69], v[204:207], v[188:191], v[66:69]
	v_mfma_f32_16x16x32_bf16 v[118:121], v[200:203], v[168:171], v[118:121]
	v_mfma_f32_16x16x32_bf16 v[114:117], v[218:221], v[168:171], v[114:117]
	v_mfma_f32_16x16x32_bf16 v[102:105], v[200:203], v[176:179], v[102:105]
	v_mfma_f32_16x16x32_bf16 v[98:101], v[218:221], v[176:179], v[98:101]
	v_mfma_f32_16x16x32_bf16 v[86:89], v[200:203], v[184:187], v[86:89]
	v_mfma_f32_16x16x32_bf16 v[82:85], v[218:221], v[184:187], v[82:85]
	v_mfma_f32_16x16x32_bf16 v[70:73], v[200:203], v[192:195], v[70:73]
	v_mfma_f32_16x16x32_bf16 v[66:69], v[218:221], v[192:195], v[66:69]
	s_mov_b32 m0, s21
	v_lshl_add_u64 v[214:215], s[18:19], 0, v[136:137]
	s_barrier
	ds_read_b128 v[164:167], v151 offset:16384
	ds_read_b128 v[168:171], v151 offset:17408
	ds_read_b128 v[172:175], v151 offset:18432
	ds_read_b128 v[176:179], v151 offset:19456
	ds_read_b128 v[180:183], v151 offset:20480
	ds_read_b128 v[184:187], v151 offset:21504
	ds_read_b128 v[188:191], v151 offset:22528
	ds_read_b128 v[192:195], v151 offset:23552
	global_load_lds_dwordx4 v[214:215], off
	v_lshl_add_u64 v[216:217], s[18:19], 0, v[132:133]
	s_mov_b32 m0, s22
	s_nop 0
	global_load_lds_dwordx4 v[216:217], off
	s_barrier
	s_waitcnt lgkmcnt(0)
	s_waitcnt lgkmcnt(0)
	v_mfma_f32_16x16x32_bf16 v[62:65], v[142:145], v[164:167], v[62:65]
	v_mfma_f32_16x16x32_bf16 v[58:61], v[156:159], v[164:167], v[58:61]
	v_mfma_f32_16x16x32_bf16 v[46:49], v[142:145], v[172:175], v[46:49]
	v_mfma_f32_16x16x32_bf16 v[42:45], v[156:159], v[172:175], v[42:45]
	v_mfma_f32_16x16x32_bf16 v[30:33], v[142:145], v[180:183], v[30:33]
	v_mfma_f32_16x16x32_bf16 v[26:29], v[156:159], v[180:183], v[26:29]
	v_mfma_f32_16x16x32_bf16 v[14:17], v[142:145], v[188:191], v[14:17]
	v_mfma_f32_16x16x32_bf16 v[10:13], v[156:159], v[188:191], v[10:13]
	v_mfma_f32_16x16x32_bf16 v[62:65], v[152:155], v[168:171], v[62:65]
	v_mfma_f32_16x16x32_bf16 v[58:61], v[160:163], v[168:171], v[58:61]
	v_mfma_f32_16x16x32_bf16 v[46:49], v[152:155], v[176:179], v[46:49]
	v_mfma_f32_16x16x32_bf16 v[42:45], v[160:163], v[176:179], v[42:45]
	v_mfma_f32_16x16x32_bf16 v[30:33], v[152:155], v[184:187], v[30:33]
	v_mfma_f32_16x16x32_bf16 v[26:29], v[160:163], v[184:187], v[26:29]
	v_mfma_f32_16x16x32_bf16 v[14:17], v[152:155], v[192:195], v[14:17]
	v_mfma_f32_16x16x32_bf16 v[10:13], v[160:163], v[192:195], v[10:13]
	s_barrier
; #define PG8_STAGE(bufoff, gbase, voff) do { _Pragma("unroll") for (int _i = 0; _i < 2; ++_i) \
;         __builtin_amdgcn_global_load_lds((const unsigned*)((const char*)(gbase) + (voff)[_i]), (LAS unsigned*)(lds + (bufoff) + ldsw + _i * 8192), 16, 0, 0); } while (0)
; #define PG8_LDA(dst, b, h) do { _Pragma("unroll") for (int m = 0; m < 4; ++m) _Pragma("unroll") for (int k = 0; k < 2; ++k) dst[m][k] = *(const LAS bf16x8*)(lds + PG8_SA(b, h) + aoff + m * 2048 + k * 1024); } while (0)
; #define PG8_LDB(dst, b, h) do { _Pragma("unroll") for (int n = 0; n < 2; ++n) _Pragma("unroll") for (int k = 0; k < 2; ++k) dst[n][k] = *(const LAS bf16x8*)(lds + PG8_SB(b, h) + boff + n * 2048 + k * 1024); } while (0)
; #define PG8_MMA(ai, bj, At, Bt) do { __builtin_amdgcn_s_setprio(1); _Pragma("unroll") for (int m = 0; m < 4; ++m) _Pragma("unroll") for (int n = 0; n < 2; ++n) _Pragma("unroll") for (int k = 0; k < 2; ++k) \
;         acc[ai][bj][m][n] = __builtin_amdgcn_mfma_f32_16x16x32_bf16(Bt[n][k], At[m][k], acc[ai][bj][m][n], 0, 0, 0); __builtin_amdgcn_s_setprio(0); } while (0)
; #define PG8_WAIT_V(n) asm volatile("s_waitcnt vmcnt(" #n ")" ::: "memory")
; #define PG8_WAIT_L(n) asm volatile("s_waitcnt lgkmcnt(" #n ")" ::: "memory")
; #define PG8_BAR __builtin_amdgcn_s_barrier()
; #define PG8_SCHED __builtin_amdgcn_sched_barrier(0)
; template <class Epi>
; __device__ __forceinline__ void gemm_phase(LAS unsigned char* lds, const Gemm g, const StaticOrder& S, const Epi& E) {
;     ...
;             PG8_STAGE(PG8_SB(0, 1), b2 + hstep, voffB);
;             PG8_WAIT_V(6); PG8_BAR; PG8_MMA(1, 1, At, B1); PG8_BAR;
;             PG8_LDB(B0, 1, 0); PG8_SCHED; PG8_LDA(At, 1, 0); PG8_STAGE(PG8_SA(0, 1), a2 + hstep, voffA);
;             PG8_WAIT_L(8); PG8_BAR; PG8_WAIT_L(0); PG8_MMA(0, 0, At, B0); PG8_BAR; PG8_SCHED;
;             PG8_LDB(B1, 1, 1); PG8_STAGE(PG8_SB(1, 0), b3, voffB);
;             PG8_BAR; PG8_WAIT_L(0); PG8_MMA(0, 1, At, B1); PG8_BAR;
	s_add_u32 s38, s16, 0x80000
	s_addc_u32 s39, s17, 0
	s_add_i32 s37, s40, s20
	v_lshl_add_u64 v[142:143], s[38:39], 0, v[134:135]
	s_mov_b32 m0, s37
	s_nop 0
	global_load_lds_dwordx4 v[142:143], off
	v_lshl_add_u64 v[142:143], s[38:39], 0, v[130:131]
	s_add_i32 m0, s37, 0x2000
	s_nop 0
	global_load_lds_dwordx4 v[142:143], off
	s_waitcnt vmcnt(6)
	s_barrier
	v_mfma_f32_16x16x32_bf16 v[54:57], v[196:199], v[164:167], v[54:57]
	v_mfma_f32_16x16x32_bf16 v[50:53], v[204:207], v[164:167], v[50:53]
	v_mfma_f32_16x16x32_bf16 v[38:41], v[196:199], v[172:175], v[38:41]
	v_mfma_f32_16x16x32_bf16 v[34:37], v[204:207], v[172:175], v[34:37]
	v_mfma_f32_16x16x32_bf16 v[22:25], v[196:199], v[180:183], v[22:25]
	v_mfma_f32_16x16x32_bf16 v[18:21], v[204:207], v[180:183], v[18:21]
	v_mfma_f32_16x16x32_bf16 v[6:9], v[196:199], v[188:191], v[6:9]
	v_mfma_f32_16x16x32_bf16 v[2:5], v[204:207], v[188:191], v[2:5]
	v_mfma_f32_16x16x32_bf16 v[54:57], v[200:203], v[168:171], v[54:57]
	v_mfma_f32_16x16x32_bf16 v[50:53], v[218:221], v[168:171], v[50:53]
	v_mfma_f32_16x16x32_bf16 v[38:41], v[200:203], v[176:179], v[38:41]
	v_mfma_f32_16x16x32_bf16 v[34:37], v[218:221], v[176:179], v[34:37]
	v_mfma_f32_16x16x32_bf16 v[22:25], v[200:203], v[184:187], v[22:25]
	v_mfma_f32_16x16x32_bf16 v[18:21], v[218:221], v[184:187], v[18:21]
	v_mfma_f32_16x16x32_bf16 v[6:9], v[200:203], v[192:195], v[6:9]
	v_mfma_f32_16x16x32_bf16 v[2:5], v[218:221], v[192:195], v[2:5]
	s_add_i32 s37, 0, 0x18000
	v_add_u32_e32 v0, s37, v149
	s_barrier
	ds_read_b128 v[142:145], v0
	ds_read_b128 v[152:155], v0 offset:1024
	ds_read_b128 v[156:159], v0 offset:2048
	ds_read_b128 v[160:163], v0 offset:3072
	s_add_u32 s18, s18, 0x80000
	s_addc_u32 s19, s19, 0
	s_mov_b32 m0, s23
	v_lshl_add_u64 v[196:197], s[18:19], 0, v[136:137]
	ds_read_b128 v[164:167], v151 offset:32768
	ds_read_b128 v[168:171], v151 offset:33792
	ds_read_b128 v[172:175], v151 offset:34816
	ds_read_b128 v[176:179], v151 offset:35840
	ds_read_b128 v[180:183], v151 offset:36864
	ds_read_b128 v[184:187], v151 offset:37888
	ds_read_b128 v[188:191], v151 offset:38912
	ds_read_b128 v[192:195], v151 offset:39936
	global_load_lds_dwordx4 v[196:197], off
	v_lshl_add_u64 v[196:197], s[18:19], 0, v[132:133]
	s_mov_b32 m0, s24
	s_nop 0
	global_load_lds_dwordx4 v[196:197], off
	s_waitcnt lgkmcnt(8)
	s_barrier
	s_waitcnt lgkmcnt(0)
	s_waitcnt lgkmcnt(0)
	v_mfma_f32_16x16x32_bf16 v[126:129], v[142:145], v[164:167], v[126:129]
	v_mfma_f32_16x16x32_bf16 v[122:125], v[156:159], v[164:167], v[122:125]
	v_mfma_f32_16x16x32_bf16 v[110:113], v[142:145], v[172:175], v[110:113]
	v_mfma_f32_16x16x32_bf16 v[106:109], v[156:159], v[172:175], v[106:109]
	v_mfma_f32_16x16x32_bf16 v[94:97], v[142:145], v[180:183], v[94:97]
	v_mfma_f32_16x16x32_bf16 v[90:93], v[156:159], v[180:183], v[90:93]
	v_mfma_f32_16x16x32_bf16 v[78:81], v[142:145], v[188:191], v[78:81]
	v_mfma_f32_16x16x32_bf16 v[74:77], v[156:159], v[188:191], v[74:77]
	v_mfma_f32_16x16x32_bf16 v[126:129], v[152:155], v[168:171], v[126:129]
	v_mfma_f32_16x16x32_bf16 v[122:125], v[160:163], v[168:171], v[122:125]
	v_mfma_f32_16x16x32_bf16 v[110:113], v[152:155], v[176:179], v[110:113]
	v_mfma_f32_16x16x32_bf16 v[106:109], v[160:163], v[176:179], v[106:109]
	v_mfma_f32_16x16x32_bf16 v[94:97], v[152:155], v[184:187], v[94:97]
	v_mfma_f32_16x16x32_bf16 v[90:93], v[160:163], v[184:187], v[90:93]
	v_mfma_f32_16x16x32_bf16 v[78:81], v[152:155], v[192:195], v[78:81]
	v_mfma_f32_16x16x32_bf16 v[74:77], v[160:163], v[192:195], v[74:77]
	s_barrier
	s_add_i32 s18, 0, 0x1c000
	s_add_i32 s19, s37, s20
	v_add_u32_e32 v0, s18, v149
	v_lshl_add_u64 v[146:147], v[146:147], 0, s[66:67]
	s_mov_b32 m0, s19
	ds_read_b128 v[196:199], v0
	ds_read_b128 v[200:203], v0 offset:1024
	ds_read_b128 v[204:207], v0 offset:2048
	ds_read_b128 v[218:221], v0 offset:3072
	global_load_lds_dwordx4 v[146:147], off
	v_lshl_add_u64 v[146:147], v[208:209], 0, s[66:67]
	s_add_i32 m0, s19, 0x2000
	s_nop 0
	global_load_lds_dwordx4 v[146:147], off
	s_barrier
	s_waitcnt lgkmcnt(0)
	s_waitcnt lgkmcnt(0)
	v_mfma_f32_16x16x32_bf16 v[118:121], v[196:199], v[164:167], v[118:121]
	v_mfma_f32_16x16x32_bf16 v[114:117], v[204:207], v[164:167], v[114:117]
	v_mfma_f32_16x16x32_bf16 v[102:105], v[196:199], v[172:175], v[102:105]
	v_mfma_f32_16x16x32_bf16 v[98:101], v[204:207], v[172:175], v[98:101]
	v_mfma_f32_16x16x32_bf16 v[86:89], v[196:199], v[180:183], v[86:89]
	v_mfma_f32_16x16x32_bf16 v[82:85], v[204:207], v[180:183], v[82:85]
	v_mfma_f32_16x16x32_bf16 v[70:73], v[196:199], v[188:191], v[70:73]
	v_mfma_f32_16x16x32_bf16 v[66:69], v[204:207], v[188:191], v[66:69]
	v_mfma_f32_16x16x32_bf16 v[118:121], v[200:203], v[168:171], v[118:121]
	v_mfma_f32_16x16x32_bf16 v[114:117], v[218:221], v[168:171], v[114:117]
	v_mfma_f32_16x16x32_bf16 v[102:105], v[200:203], v[176:179], v[102:105]
	v_mfma_f32_16x16x32_bf16 v[98:101], v[218:221], v[176:179], v[98:101]
	v_mfma_f32_16x16x32_bf16 v[86:89], v[200:203], v[184:187], v[86:89]
	v_mfma_f32_16x16x32_bf16 v[82:85], v[218:221], v[184:187], v[82:85]
	v_mfma_f32_16x16x32_bf16 v[70:73], v[200:203], v[192:195], v[70:73]
	v_mfma_f32_16x16x32_bf16 v[66:69], v[218:221], v[192:195], v[66:69]
	s_mov_b32 m0, s25
	v_lshl_add_u64 v[146:147], v[214:215], 0, s[66:67]
	s_barrier
; __device__ __forceinline__ float silu_f(float x) { return x * __builtin_amdgcn_rcpf(1.f + __expf(-x)); }
; #define PG8_STAGE(bufoff, gbase, voff) do { _Pragma("unroll") for (int _i = 0; _i < 2; ++_i) \
;         __builtin_amdgcn_global_load_lds((const unsigned*)((const char*)(gbase) + (voff)[_i]), (LAS unsigned*)(lds + (bufoff) + ldsw + _i * 8192), 16, 0, 0); } while (0)
; #define PG8_LDA(dst, b, h) do { _Pragma("unroll") for (int m = 0; m < 4; ++m) _Pragma("unroll") for (int k = 0; k < 2; ++k) dst[m][k] = *(const LAS bf16x8*)(lds + PG8_SA(b, h) + aoff + m * 2048 + k * 1024); } while (0)
; #define PG8_MMA(ai, bj, At, Bt) do { __builtin_amdgcn_s_setprio(1); _Pragma("unroll") for (int m = 0; m < 4; ++m) _Pragma("unroll") for (int n = 0; n < 2; ++n) _Pragma("unroll") for (int k = 0; k < 2; ++k) \
;         acc[ai][bj][m][n] = __builtin_amdgcn_mfma_f32_16x16x32_bf16(Bt[n][k], At[m][k], acc[ai][bj][m][n], 0, 0, 0); __builtin_amdgcn_s_setprio(0); } while (0)
; #define PG8_WAIT_V(n) asm volatile("s_waitcnt vmcnt(" #n ")" ::: "memory")
; #define PG8_BAR __builtin_amdgcn_s_barrier()
; template <class Epi>
; __device__ __forceinline__ void gemm_phase(LAS unsigned char* lds, const Gemm g, const StaticOrder& S, const Epi& E) {
;     ...
;             PG8_LDA(At, 1, 1); PG8_STAGE(PG8_SA(1, 0), a3, voffA);
;             PG8_BAR; PG8_WAIT_L(0); PG8_MMA(1, 0, At, B0); PG8_BAR; PG8_SCHED;
;             PG8_STAGE(PG8_SB(1, 1), b3 + hstep, voffB);
;             PG8_WAIT_V(6); PG8_BAR; PG8_MMA(1, 1, At, B1); PG8_BAR;
;     __device__ __forceinline__ void operator()(const f32x4 (&acc)[2][2][4][2], const Unit& u, int wr, int wc, int fr, int fq) const {
;         const int sect = u.pn >> 3;
;         bf16_t* base = R + (size_t)sect * ((size_t)T_TOK * DM);
;         const int row0 = u.pm * BM + wr * 64 + fr, col0 = (u.pn & 7) * BM + wc * 32 + 8 * fq;
; #pragma unroll
;         for (int ai = 0; ai < 2; ++ai)
; #pragma unroll
;             for (int m = 0; m < 4; ++m) { bf16_t* rowp = base + (size_t)(row0 + ai * HALF + m * 16) * DM + col0;
; #pragma unroll
;                 for (int bj = 0; bj < 2; ++bj) { f32x4 v0 = acc[ai][bj][m][0], v1 = acc[ai][bj][m][1];
;                     if (sect == 0) {
; #pragma unroll
;                         for (int j = 0; j < 4; ++j) { v0[j] = silu_f(v0[j]) * 0.08838834764831845f; v1[j] = silu_f(v1[j]) * 0.08838834764831845f; } }
	ds_read_b128 v[164:167], v151 offset:49152
	ds_read_b128 v[168:171], v151 offset:50176
	ds_read_b128 v[172:175], v151 offset:51200
	ds_read_b128 v[176:179], v151 offset:52224
	ds_read_b128 v[180:183], v151 offset:53248
	ds_read_b128 v[184:187], v151 offset:54272
	ds_read_b128 v[188:191], v151 offset:55296
	ds_read_b128 v[192:195], v151 offset:56320
	global_load_lds_dwordx4 v[146:147], off
	v_lshl_add_u64 v[146:147], v[216:217], 0, s[66:67]
	s_mov_b32 m0, s26
	s_nop 0
	global_load_lds_dwordx4 v[146:147], off
	s_barrier
	s_waitcnt lgkmcnt(0)
	s_waitcnt lgkmcnt(0)
	v_mfma_f32_16x16x32_bf16 v[62:65], v[142:145], v[164:167], v[62:65]
	v_mfma_f32_16x16x32_bf16 v[58:61], v[156:159], v[164:167], v[58:61]
	v_mfma_f32_16x16x32_bf16 v[46:49], v[142:145], v[172:175], v[46:49]
	v_mfma_f32_16x16x32_bf16 v[42:45], v[156:159], v[172:175], v[42:45]
	v_mfma_f32_16x16x32_bf16 v[30:33], v[142:145], v[180:183], v[30:33]
	v_mfma_f32_16x16x32_bf16 v[26:29], v[156:159], v[180:183], v[26:29]
	v_mfma_f32_16x16x32_bf16 v[14:17], v[142:145], v[188:191], v[14:17]
	v_mfma_f32_16x16x32_bf16 v[10:13], v[156:159], v[188:191], v[10:13]
	v_mfma_f32_16x16x32_bf16 v[62:65], v[152:155], v[168:171], v[62:65]
	v_mfma_f32_16x16x32_bf16 v[58:61], v[160:163], v[168:171], v[58:61]
	v_mfma_f32_16x16x32_bf16 v[46:49], v[152:155], v[176:179], v[46:49]
	v_mfma_f32_16x16x32_bf16 v[42:45], v[160:163], v[176:179], v[42:45]
	v_mfma_f32_16x16x32_bf16 v[30:33], v[152:155], v[184:187], v[30:33]
	v_mfma_f32_16x16x32_bf16 v[26:29], v[160:163], v[184:187], v[26:29]
	v_mfma_f32_16x16x32_bf16 v[14:17], v[152:155], v[192:195], v[14:17]
	v_mfma_f32_16x16x32_bf16 v[10:13], v[160:163], v[192:195], v[10:13]
	s_barrier
	s_add_u32 s16, s16, 0x80080
	s_addc_u32 s17, s17, 0
	s_add_i32 s18, s18, s20
	v_lshl_add_u64 v[142:143], s[16:17], 0, v[134:135]
	s_mov_b32 m0, s18
	s_nop 0
	global_load_lds_dwordx4 v[142:143], off
	v_lshl_add_u64 v[142:143], s[16:17], 0, v[130:131]
	s_add_i32 m0, s18, 0x2000
	s_nop 0
	global_load_lds_dwordx4 v[142:143], off
	s_waitcnt vmcnt(6)
	s_barrier
	v_mfma_f32_16x16x32_bf16 v[54:57], v[196:199], v[164:167], v[54:57]
	v_mfma_f32_16x16x32_bf16 v[50:53], v[204:207], v[164:167], v[50:53]
	v_mfma_f32_16x16x32_bf16 v[38:41], v[196:199], v[172:175], v[38:41]
	v_mfma_f32_16x16x32_bf16 v[34:37], v[204:207], v[172:175], v[34:37]
	v_mfma_f32_16x16x32_bf16 v[22:25], v[196:199], v[180:183], v[22:25]
	v_mfma_f32_16x16x32_bf16 v[18:21], v[204:207], v[180:183], v[18:21]
	v_mfma_f32_16x16x32_bf16 v[6:9], v[196:199], v[188:191], v[6:9]
	v_mfma_f32_16x16x32_bf16 v[2:5], v[204:207], v[188:191], v[2:5]
	v_mfma_f32_16x16x32_bf16 v[54:57], v[200:203], v[168:171], v[54:57]
	v_mfma_f32_16x16x32_bf16 v[50:53], v[218:221], v[168:171], v[50:53]
	v_mfma_f32_16x16x32_bf16 v[38:41], v[200:203], v[176:179], v[38:41]
	v_mfma_f32_16x16x32_bf16 v[34:37], v[218:221], v[176:179], v[34:37]
	v_mfma_f32_16x16x32_bf16 v[22:25], v[200:203], v[184:187], v[22:25]
	v_mfma_f32_16x16x32_bf16 v[18:21], v[218:221], v[184:187], v[18:21]
	v_mfma_f32_16x16x32_bf16 v[6:9], v[200:203], v[192:195], v[6:9]
	v_mfma_f32_16x16x32_bf16 v[2:5], v[218:221], v[192:195], v[2:5]
	s_add_i32 s36, s36, 2
	s_add_u32 s8, s8, 0x100
	s_addc_u32 s9, s9, 0
	s_add_u32 s34, s34, 0x100
	s_addc_u32 s35, s35, 0
	s_cmp_gt_u32 s36, 29
	s_barrier
	s_cbranch_scc0 .LBB0_155
	s_cmp_lt_u32 s28, 8
	s_cselect_b64 s[16:17], -1, 0
	s_cmp_gt_u32 s28, 7
	s_cbranch_scc1 .LBB0_158
	v_mul_f32_e32 v0, 0xbfb8aa3b, v126
	v_exp_f32_e32 v0, v0
	s_nop 0
	v_add_f32_e32 v0, 1.0, v0
	v_rcp_f32_e32 v142, v0
	v_mul_f32_e32 v0, 0xbfb8aa3b, v122
	v_exp_f32_e32 v0, v0
	s_nop 0
	v_add_f32_e32 v0, 1.0, v0
	v_rcp_f32_e32 v144, v0
	v_mul_f32_e32 v0, 0xbfb8aa3b, v127
	v_exp_f32_e32 v0, v0
	s_nop 0
	v_add_f32_e32 v0, 1.0, v0
	v_rcp_f32_e32 v143, v0
	v_mul_f32_e32 v0, 0xbfb8aa3b, v123
	v_exp_f32_e32 v0, v0
	v_pk_mul_f32 v[126:127], v[126:127], v[142:143]
	s_nop 0
	v_pk_mul_f32 v[126:127], v[126:127], s[64:65] op_sel_hi:[1,0]
	v_add_f32_e32 v0, 1.0, v0
	v_rcp_f32_e32 v145, v0
	v_mul_f32_e32 v0, 0xbfb8aa3b, v128
	v_exp_f32_e32 v0, v0
	v_pk_mul_f32 v[122:123], v[122:123], v[144:145]
	s_nop 0
	v_pk_mul_f32 v[122:123], v[122:123], s[64:65] op_sel_hi:[1,0]
	v_add_f32_e32 v0, 1.0, v0
	v_rcp_f32_e32 v146, v0
	v_mul_f32_e32 v0, 0xbfb8aa3b, v124
	v_exp_f32_e32 v0, v0
	s_nop 0
	v_add_f32_e32 v0, 1.0, v0
	v_rcp_f32_e32 v152, v0
	v_mul_f32_e32 v0, 0xbfb8aa3b, v129
	v_exp_f32_e32 v0, v0
	s_nop 0
	v_add_f32_e32 v0, 1.0, v0
	v_rcp_f32_e32 v147, v0
	v_mul_f32_e32 v0, 0xbfb8aa3b, v125
	v_exp_f32_e32 v0, v0
	v_pk_mul_f32 v[128:129], v[128:129], v[146:147]
	s_nop 0
	v_pk_mul_f32 v[128:129], v[128:129], s[64:65] op_sel_hi:[1,0]
	v_add_f32_e32 v0, 1.0, v0
	v_rcp_f32_e32 v153, v0
	s_nop 0
	v_pk_mul_f32 v[124:125], v[124:125], v[152:153]
	s_nop 0
	v_pk_mul_f32 v[124:125], v[124:125], s[64:65] op_sel_hi:[1,0]

; #define PG8_STAGE(bufoff, gbase, voff) do { _Pragma("unroll") for (int _i = 0; _i < 2; ++_i) \
;         __builtin_amdgcn_global_load_lds((const unsigned*)((const char*)(gbase) + (voff)[_i]), (LAS unsigned*)(lds + (bufoff) + ldsw + _i * 8192), 16, 0, 0); } while (0)
; #define PG8_LDA(dst, b, h) do { _Pragma("unroll") for (int m = 0; m < 4; ++m) _Pragma("unroll") for (int k = 0; k < 2; ++k) dst[m][k] = *(const LAS bf16x8*)(lds + PG8_SA(b, h) + aoff + m * 2048 + k * 1024); } while (0)
; #define PG8_LDB(dst, b, h) do { _Pragma("unroll") for (int n = 0; n < 2; ++n) _Pragma("unroll") for (int k = 0; k < 2; ++k) dst[n][k] = *(const LAS bf16x8*)(lds + PG8_SB(b, h) + boff + n * 2048 + k * 1024); } while (0)
; #define PG8_MMA(ai, bj, At, Bt) do { __builtin_amdgcn_s_setprio(1); _Pragma("unroll") for (int m = 0; m < 4; ++m) _Pragma("unroll") for (int n = 0; n < 2; ++n) _Pragma("unroll") for (int k = 0; k < 2; ++k) \
;         acc[ai][bj][m][n] = __builtin_amdgcn_mfma_f32_16x16x32_bf16(Bt[n][k], At[m][k], acc[ai][bj][m][n], 0, 0, 0); __builtin_amdgcn_s_setprio(0); } while (0)
; #define PG8_WAIT_L(n) asm volatile("s_waitcnt lgkmcnt(" #n ")" ::: "memory")
; #define PG8_BAR __builtin_amdgcn_s_barrier()
; #define PG8_SCHED __builtin_amdgcn_sched_barrier(0)
; template <class Epi>
; __device__ __forceinline__ void gemm_phase(LAS unsigned char* lds, const Gemm g, const StaticOrder& S, const Epi& E) {
;     ...
;             PG8_LDB(B0, 0, 0); PG8_SCHED; PG8_LDA(At, 0, 0); PG8_STAGE(PG8_SA(1, 1), a1 + hstep, voffA);
;             PG8_WAIT_L(8); PG8_BAR; PG8_WAIT_L(0); PG8_MMA(0, 0, At, B0); PG8_BAR; PG8_SCHED;
;             PG8_LDB(B1, 0, 1); PG8_STAGE(PG8_SB(0, 0), b2, voffB);
;             PG8_BAR; PG8_WAIT_L(0); PG8_MMA(0, 1, At, B1); PG8_BAR;
;             PG8_LDA(At, 0, 1); PG8_STAGE(PG8_SA(0, 0), a2, voffA);
;             PG8_BAR; PG8_WAIT_L(0); PG8_MMA(1, 0, At, B0); PG8_BAR; PG8_SCHED;
.LBB0_469:
	s_add_u32 s18, s10, 0xfff80080
	s_addc_u32 s19, s11, -1
	s_add_i32 s40, 0, 0x10000
	v_add_u32_e32 v142, s40, v219
	ds_read_b128 v[130:133], v142
	ds_read_b128 v[134:137], v142 offset:1024
	ds_read_b128 v[138:141], v142 offset:2048
	ds_read_b128 v[142:145], v142 offset:3072
	s_cmp_eq_u32 s39, 28
	s_cselect_b32 s21, s13, s19
	s_cselect_b32 s20, s35, s18
	s_cselect_b32 s19, s1, s38
	s_cselect_b32 s18, s36, s37
	v_lshl_add_u64 v[178:179], s[10:11], 0, v[192:193]
	s_add_i32 m0, s23, 0xc000
	ds_read_b128 v[146:149], v221
	ds_read_b128 v[150:153], v221 offset:1024
	ds_read_b128 v[154:157], v221 offset:2048
	ds_read_b128 v[158:161], v221 offset:3072
	ds_read_b128 v[162:165], v221 offset:4096
	ds_read_b128 v[166:169], v221 offset:5120
	ds_read_b128 v[170:173], v221 offset:6144
	ds_read_b128 v[174:177], v221 offset:7168
	global_load_lds_dwordx4 v[178:179], off
	v_lshl_add_u64 v[178:179], s[10:11], 0, v[194:195]
	s_add_i32 m0, s23, 0xe000
	s_nop 0
	global_load_lds_dwordx4 v[178:179], off
	s_waitcnt lgkmcnt(8)
	s_barrier
	s_waitcnt lgkmcnt(0)
	s_waitcnt lgkmcnt(0)
	v_mfma_f32_16x16x32_bf16 v[126:129], v[130:133], v[146:149], v[126:129]
	v_mfma_f32_16x16x32_bf16 v[122:125], v[138:141], v[146:149], v[122:125]
	v_mfma_f32_16x16x32_bf16 v[110:113], v[130:133], v[154:157], v[110:113]
	v_mfma_f32_16x16x32_bf16 v[106:109], v[138:141], v[154:157], v[106:109]
	v_mfma_f32_16x16x32_bf16 v[94:97], v[130:133], v[162:165], v[94:97]
	v_mfma_f32_16x16x32_bf16 v[90:93], v[138:141], v[162:165], v[90:93]
	v_mfma_f32_16x16x32_bf16 v[78:81], v[130:133], v[170:173], v[78:81]
	v_mfma_f32_16x16x32_bf16 v[74:77], v[138:141], v[170:173], v[74:77]
	v_mfma_f32_16x16x32_bf16 v[126:129], v[134:137], v[150:153], v[126:129]
	v_mfma_f32_16x16x32_bf16 v[122:125], v[142:145], v[150:153], v[122:125]
	v_mfma_f32_16x16x32_bf16 v[110:113], v[134:137], v[158:161], v[110:113]
	v_mfma_f32_16x16x32_bf16 v[106:109], v[142:145], v[158:161], v[106:109]
	v_mfma_f32_16x16x32_bf16 v[94:97], v[134:137], v[166:169], v[94:97]
	v_mfma_f32_16x16x32_bf16 v[90:93], v[142:145], v[166:169], v[90:93]
	v_mfma_f32_16x16x32_bf16 v[78:81], v[134:137], v[174:177], v[78:81]
	v_mfma_f32_16x16x32_bf16 v[74:77], v[142:145], v[174:177], v[74:77]
	s_barrier
	s_add_i32 s42, 0, 0x14000
	s_add_i32 s40, s40, s22
	v_add_u32_e32 v200, s42, v219
	v_lshl_add_u64 v[204:205], s[18:19], 0, v[0:1]
	s_mov_b32 m0, s40
	ds_read_b128 v[178:181], v200
	ds_read_b128 v[182:185], v200 offset:1024
	ds_read_b128 v[196:199], v200 offset:2048
	ds_read_b128 v[200:203], v200 offset:3072
	global_load_lds_dwordx4 v[204:205], off
	v_lshl_add_u64 v[206:207], s[18:19], 0, v[186:187]
	s_add_i32 m0, s40, 0x2000
	s_nop 0
	global_load_lds_dwordx4 v[206:207], off
	s_barrier
	s_waitcnt lgkmcnt(0)
	s_waitcnt lgkmcnt(0)
	v_mfma_f32_16x16x32_bf16 v[118:121], v[178:181], v[146:149], v[118:121]
	v_mfma_f32_16x16x32_bf16 v[114:117], v[196:199], v[146:149], v[114:117]
	v_mfma_f32_16x16x32_bf16 v[102:105], v[178:181], v[154:157], v[102:105]
	v_mfma_f32_16x16x32_bf16 v[98:101], v[196:199], v[154:157], v[98:101]
	v_mfma_f32_16x16x32_bf16 v[86:89], v[178:181], v[162:165], v[86:89]
	v_mfma_f32_16x16x32_bf16 v[82:85], v[196:199], v[162:165], v[82:85]
	v_mfma_f32_16x16x32_bf16 v[70:73], v[178:181], v[170:173], v[70:73]
	v_mfma_f32_16x16x32_bf16 v[66:69], v[196:199], v[170:173], v[66:69]
	v_mfma_f32_16x16x32_bf16 v[118:121], v[182:185], v[150:153], v[118:121]
	v_mfma_f32_16x16x32_bf16 v[114:117], v[200:203], v[150:153], v[114:117]
	v_mfma_f32_16x16x32_bf16 v[102:105], v[182:185], v[158:161], v[102:105]
	v_mfma_f32_16x16x32_bf16 v[98:101], v[200:203], v[158:161], v[98:101]
	v_mfma_f32_16x16x32_bf16 v[86:89], v[182:185], v[166:169], v[86:89]
	v_mfma_f32_16x16x32_bf16 v[82:85], v[200:203], v[166:169], v[82:85]
	v_mfma_f32_16x16x32_bf16 v[70:73], v[182:185], v[174:177], v[70:73]
	v_mfma_f32_16x16x32_bf16 v[66:69], v[200:203], v[174:177], v[66:69]
	s_mov_b32 m0, s23
	v_lshl_add_u64 v[208:209], s[20:21], 0, v[190:191]
	s_barrier
	ds_read_b128 v[146:149], v221 offset:16384
	ds_read_b128 v[150:153], v221 offset:17408
	ds_read_b128 v[154:157], v221 offset:18432
	ds_read_b128 v[158:161], v221 offset:19456
	ds_read_b128 v[162:165], v221 offset:20480
	ds_read_b128 v[166:169], v221 offset:21504
	ds_read_b128 v[170:173], v221 offset:22528
	ds_read_b128 v[174:177], v221 offset:23552
	global_load_lds_dwordx4 v[208:209], off
	v_lshl_add_u64 v[214:215], s[20:21], 0, v[188:189]
	s_mov_b32 m0, s24
	s_nop 0
	global_load_lds_dwordx4 v[214:215], off
	s_barrier
	s_waitcnt lgkmcnt(0)
	s_waitcnt lgkmcnt(0)
	v_mfma_f32_16x16x32_bf16 v[62:65], v[130:133], v[146:149], v[62:65]
	v_mfma_f32_16x16x32_bf16 v[58:61], v[138:141], v[146:149], v[58:61]
	v_mfma_f32_16x16x32_bf16 v[46:49], v[130:133], v[154:157], v[46:49]
	v_mfma_f32_16x16x32_bf16 v[42:45], v[138:141], v[154:157], v[42:45]
	v_mfma_f32_16x16x32_bf16 v[30:33], v[130:133], v[162:165], v[30:33]
	v_mfma_f32_16x16x32_bf16 v[26:29], v[138:141], v[162:165], v[26:29]
	v_mfma_f32_16x16x32_bf16 v[14:17], v[130:133], v[170:173], v[14:17]
	v_mfma_f32_16x16x32_bf16 v[10:13], v[138:141], v[170:173], v[10:13]
	v_mfma_f32_16x16x32_bf16 v[62:65], v[134:137], v[150:153], v[62:65]
	v_mfma_f32_16x16x32_bf16 v[58:61], v[142:145], v[150:153], v[58:61]
	v_mfma_f32_16x16x32_bf16 v[46:49], v[134:137], v[158:161], v[46:49]
	v_mfma_f32_16x16x32_bf16 v[42:45], v[142:145], v[158:161], v[42:45]
	v_mfma_f32_16x16x32_bf16 v[30:33], v[134:137], v[166:169], v[30:33]
	v_mfma_f32_16x16x32_bf16 v[26:29], v[142:145], v[166:169], v[26:29]
	v_mfma_f32_16x16x32_bf16 v[14:17], v[134:137], v[174:177], v[14:17]
	v_mfma_f32_16x16x32_bf16 v[10:13], v[142:145], v[174:177], v[10:13]
	s_barrier
; #define PG8_STAGE(bufoff, gbase, voff) do { _Pragma("unroll") for (int _i = 0; _i < 2; ++_i) \
;         __builtin_amdgcn_global_load_lds((const unsigned*)((const char*)(gbase) + (voff)[_i]), (LAS unsigned*)(lds + (bufoff) + ldsw + _i * 8192), 16, 0, 0); } while (0)
; #define PG8_LDA(dst, b, h) do { _Pragma("unroll") for (int m = 0; m < 4; ++m) _Pragma("unroll") for (int k = 0; k < 2; ++k) dst[m][k] = *(const LAS bf16x8*)(lds + PG8_SA(b, h) + aoff + m * 2048 + k * 1024); } while (0)
; #define PG8_LDB(dst, b, h) do { _Pragma("unroll") for (int n = 0; n < 2; ++n) _Pragma("unroll") for (int k = 0; k < 2; ++k) dst[n][k] = *(const LAS bf16x8*)(lds + PG8_SB(b, h) + boff + n * 2048 + k * 1024); } while (0)
; #define PG8_MMA(ai, bj, At, Bt) do { __builtin_amdgcn_s_setprio(1); _Pragma("unroll") for (int m = 0; m < 4; ++m) _Pragma("unroll") for (int n = 0; n < 2; ++n) _Pragma("unroll") for (int k = 0; k < 2; ++k) \
;         acc[ai][bj][m][n] = __builtin_amdgcn_mfma_f32_16x16x32_bf16(Bt[n][k], At[m][k], acc[ai][bj][m][n], 0, 0, 0); __builtin_amdgcn_s_setprio(0); } while (0)
; #define PG8_WAIT_V(n) asm volatile("s_waitcnt vmcnt(" #n ")" ::: "memory")
; #define PG8_WAIT_L(n) asm volatile("s_waitcnt lgkmcnt(" #n ")" ::: "memory")
; #define PG8_BAR __builtin_amdgcn_s_barrier()
; #define PG8_SCHED __builtin_amdgcn_sched_barrier(0)
; template <class Epi>
; __device__ __forceinline__ void gemm_phase(LAS unsigned char* lds, const Gemm g, const StaticOrder& S, const Epi& E) {
;     ...
;             PG8_STAGE(PG8_SB(0, 1), b2 + hstep, voffB);
;             PG8_WAIT_V(6); PG8_BAR; PG8_MMA(1, 1, At, B1); PG8_BAR;
;             PG8_LDB(B0, 1, 0); PG8_SCHED; PG8_LDA(At, 1, 0); PG8_STAGE(PG8_SA(0, 1), a2 + hstep, voffA);
;             PG8_WAIT_L(8); PG8_BAR; PG8_WAIT_L(0); PG8_MMA(0, 0, At, B0); PG8_BAR; PG8_SCHED;
;             PG8_LDB(B1, 1, 1); PG8_STAGE(PG8_SB(1, 0), b3, voffB);
;             PG8_BAR; PG8_WAIT_L(0); PG8_MMA(0, 1, At, B1); PG8_BAR;
;             PG8_LDA(At, 1, 1); PG8_STAGE(PG8_SA(1, 0), a3, voffA);
	s_add_u32 s40, s18, 0x80000
	s_addc_u32 s41, s19, 0
	s_add_i32 s42, s42, s22
	v_lshl_add_u64 v[130:131], s[40:41], 0, v[0:1]
	s_mov_b32 m0, s42
	s_nop 0
	global_load_lds_dwordx4 v[130:131], off
	v_lshl_add_u64 v[130:131], s[40:41], 0, v[186:187]
	s_add_i32 m0, s42, 0x2000
	s_nop 0
	global_load_lds_dwordx4 v[130:131], off
	s_waitcnt vmcnt(6)
	s_barrier
	v_mfma_f32_16x16x32_bf16 v[54:57], v[178:181], v[146:149], v[54:57]
	v_mfma_f32_16x16x32_bf16 v[50:53], v[196:199], v[146:149], v[50:53]
	v_mfma_f32_16x16x32_bf16 v[38:41], v[178:181], v[154:157], v[38:41]
	v_mfma_f32_16x16x32_bf16 v[34:37], v[196:199], v[154:157], v[34:37]
	v_mfma_f32_16x16x32_bf16 v[22:25], v[178:181], v[162:165], v[22:25]
	v_mfma_f32_16x16x32_bf16 v[18:21], v[196:199], v[162:165], v[18:21]
	v_mfma_f32_16x16x32_bf16 v[6:9], v[178:181], v[170:173], v[6:9]
	v_mfma_f32_16x16x32_bf16 v[2:5], v[196:199], v[170:173], v[2:5]
	v_mfma_f32_16x16x32_bf16 v[54:57], v[182:185], v[150:153], v[54:57]
	v_mfma_f32_16x16x32_bf16 v[50:53], v[200:203], v[150:153], v[50:53]
	v_mfma_f32_16x16x32_bf16 v[38:41], v[182:185], v[158:161], v[38:41]
	v_mfma_f32_16x16x32_bf16 v[34:37], v[200:203], v[158:161], v[34:37]
	v_mfma_f32_16x16x32_bf16 v[22:25], v[182:185], v[166:169], v[22:25]
	v_mfma_f32_16x16x32_bf16 v[18:21], v[200:203], v[166:169], v[18:21]
	v_mfma_f32_16x16x32_bf16 v[6:9], v[182:185], v[174:177], v[6:9]
	v_mfma_f32_16x16x32_bf16 v[2:5], v[200:203], v[174:177], v[2:5]
	s_add_i32 s40, 0, 0x18000
	v_add_u32_e32 v142, s40, v219
	s_barrier
	ds_read_b128 v[130:133], v142
	ds_read_b128 v[134:137], v142 offset:1024
	ds_read_b128 v[138:141], v142 offset:2048
	ds_read_b128 v[142:145], v142 offset:3072
	s_add_u32 s20, s20, 0x80000
	s_addc_u32 s21, s21, 0
	s_mov_b32 m0, s25
	v_lshl_add_u64 v[178:179], s[20:21], 0, v[190:191]
	ds_read_b128 v[146:149], v221 offset:32768
	ds_read_b128 v[150:153], v221 offset:33792
	ds_read_b128 v[154:157], v221 offset:34816
	ds_read_b128 v[158:161], v221 offset:35840
	ds_read_b128 v[162:165], v221 offset:36864
	ds_read_b128 v[166:169], v221 offset:37888
	ds_read_b128 v[170:173], v221 offset:38912
	ds_read_b128 v[174:177], v221 offset:39936
	global_load_lds_dwordx4 v[178:179], off
	v_lshl_add_u64 v[178:179], s[20:21], 0, v[188:189]
	s_mov_b32 m0, s26
	s_nop 0
	global_load_lds_dwordx4 v[178:179], off
	s_waitcnt lgkmcnt(8)
	s_barrier
	s_waitcnt lgkmcnt(0)
	s_waitcnt lgkmcnt(0)
	v_mfma_f32_16x16x32_bf16 v[126:129], v[130:133], v[146:149], v[126:129]
	v_mfma_f32_16x16x32_bf16 v[122:125], v[138:141], v[146:149], v[122:125]
	v_mfma_f32_16x16x32_bf16 v[110:113], v[130:133], v[154:157], v[110:113]
	v_mfma_f32_16x16x32_bf16 v[106:109], v[138:141], v[154:157], v[106:109]
	v_mfma_f32_16x16x32_bf16 v[94:97], v[130:133], v[162:165], v[94:97]
	v_mfma_f32_16x16x32_bf16 v[90:93], v[138:141], v[162:165], v[90:93]
	v_mfma_f32_16x16x32_bf16 v[78:81], v[130:133], v[170:173], v[78:81]
	v_mfma_f32_16x16x32_bf16 v[74:77], v[138:141], v[170:173], v[74:77]
	v_mfma_f32_16x16x32_bf16 v[126:129], v[134:137], v[150:153], v[126:129]
	v_mfma_f32_16x16x32_bf16 v[122:125], v[142:145], v[150:153], v[122:125]
	v_mfma_f32_16x16x32_bf16 v[110:113], v[134:137], v[158:161], v[110:113]
	v_mfma_f32_16x16x32_bf16 v[106:109], v[142:145], v[158:161], v[106:109]
	v_mfma_f32_16x16x32_bf16 v[94:97], v[134:137], v[166:169], v[94:97]
	v_mfma_f32_16x16x32_bf16 v[90:93], v[142:145], v[166:169], v[90:93]
	v_mfma_f32_16x16x32_bf16 v[78:81], v[134:137], v[174:177], v[78:81]
	v_mfma_f32_16x16x32_bf16 v[74:77], v[142:145], v[174:177], v[74:77]
	s_barrier
	s_add_i32 s20, 0, 0x1c000
	s_add_i32 s21, s40, s22
	v_add_u32_e32 v200, s20, v219
	v_lshl_add_u64 v[204:205], v[204:205], 0, s[66:67]
	s_mov_b32 m0, s21
	ds_read_b128 v[178:181], v200
	ds_read_b128 v[182:185], v200 offset:1024
	ds_read_b128 v[196:199], v200 offset:2048
	ds_read_b128 v[200:203], v200 offset:3072
	global_load_lds_dwordx4 v[204:205], off
	v_lshl_add_u64 v[204:205], v[206:207], 0, s[66:67]
	s_add_i32 m0, s21, 0x2000
	s_nop 0
	global_load_lds_dwordx4 v[204:205], off
	s_barrier
	s_waitcnt lgkmcnt(0)
	s_waitcnt lgkmcnt(0)
	v_mfma_f32_16x16x32_bf16 v[118:121], v[178:181], v[146:149], v[118:121]
	v_mfma_f32_16x16x32_bf16 v[114:117], v[196:199], v[146:149], v[114:117]
	v_mfma_f32_16x16x32_bf16 v[102:105], v[178:181], v[154:157], v[102:105]
	v_mfma_f32_16x16x32_bf16 v[98:101], v[196:199], v[154:157], v[98:101]
	v_mfma_f32_16x16x32_bf16 v[86:89], v[178:181], v[162:165], v[86:89]
	v_mfma_f32_16x16x32_bf16 v[82:85], v[196:199], v[162:165], v[82:85]
	v_mfma_f32_16x16x32_bf16 v[70:73], v[178:181], v[170:173], v[70:73]
	v_mfma_f32_16x16x32_bf16 v[66:69], v[196:199], v[170:173], v[66:69]
	v_mfma_f32_16x16x32_bf16 v[118:121], v[182:185], v[150:153], v[118:121]
	v_mfma_f32_16x16x32_bf16 v[114:117], v[200:203], v[150:153], v[114:117]
	v_mfma_f32_16x16x32_bf16 v[102:105], v[182:185], v[158:161], v[102:105]
	v_mfma_f32_16x16x32_bf16 v[98:101], v[200:203], v[158:161], v[98:101]
	v_mfma_f32_16x16x32_bf16 v[86:89], v[182:185], v[166:169], v[86:89]
	v_mfma_f32_16x16x32_bf16 v[82:85], v[200:203], v[166:169], v[82:85]
	v_mfma_f32_16x16x32_bf16 v[70:73], v[182:185], v[174:177], v[70:73]
	v_mfma_f32_16x16x32_bf16 v[66:69], v[200:203], v[174:177], v[66:69]
	s_mov_b32 m0, s28
	v_lshl_add_u64 v[204:205], v[208:209], 0, s[66:67]
	s_barrier
	ds_read_b128 v[146:149], v221 offset:49152
	ds_read_b128 v[150:153], v221 offset:50176
	ds_read_b128 v[154:157], v221 offset:51200
	ds_read_b128 v[158:161], v221 offset:52224
	ds_read_b128 v[162:165], v221 offset:53248
	ds_read_b128 v[166:169], v221 offset:54272
	ds_read_b128 v[170:173], v221 offset:55296
	ds_read_b128 v[174:177], v221 offset:56320
	global_load_lds_dwordx4 v[204:205], off
	v_lshl_add_u64 v[204:205], v[214:215], 0, s[66:67]
	s_mov_b32 m0, s29
	s_nop 0
	global_load_lds_dwordx4 v[204:205], off
	s_barrier
; #define PG8_STAGE(bufoff, gbase, voff) do { _Pragma("unroll") for (int _i = 0; _i < 2; ++_i) \
;         __builtin_amdgcn_global_load_lds((const unsigned*)((const char*)(gbase) + (voff)[_i]), (LAS unsigned*)(lds + (bufoff) + ldsw + _i * 8192), 16, 0, 0); } while (0)
; #define PG8_MMA(ai, bj, At, Bt) do { __builtin_amdgcn_s_setprio(1); _Pragma("unroll") for (int m = 0; m < 4; ++m) _Pragma("unroll") for (int n = 0; n < 2; ++n) _Pragma("unroll") for (int k = 0; k < 2; ++k) \
;         acc[ai][bj][m][n] = __builtin_amdgcn_mfma_f32_16x16x32_bf16(Bt[n][k], At[m][k], acc[ai][bj][m][n], 0, 0, 0); __builtin_amdgcn_s_setprio(0); } while (0)
; #define PG8_WAIT_V(n) asm volatile("s_waitcnt vmcnt(" #n ")" ::: "memory")
; #define PG8_WAIT_L(n) asm volatile("s_waitcnt lgkmcnt(" #n ")" ::: "memory")
; #define PG8_BAR __builtin_amdgcn_s_barrier()
; #define PG8_SCHED __builtin_amdgcn_sched_barrier(0)
; template <class Epi>
; __device__ __forceinline__ void gemm_phase(LAS unsigned char* lds, const Gemm g, const StaticOrder& S, const Epi& E) {
;     ...
;             PG8_BAR; PG8_WAIT_L(0); PG8_MMA(1, 0, At, B0); PG8_BAR; PG8_SCHED;
;             PG8_STAGE(PG8_SB(1, 1), b3 + hstep, voffB);
;             PG8_WAIT_V(6); PG8_BAR; PG8_MMA(1, 1, At, B1); PG8_BAR;
	s_waitcnt lgkmcnt(0)
	s_waitcnt lgkmcnt(0)
	v_mfma_f32_16x16x32_bf16 v[62:65], v[130:133], v[146:149], v[62:65]
	v_mfma_f32_16x16x32_bf16 v[58:61], v[138:141], v[146:149], v[58:61]
	v_mfma_f32_16x16x32_bf16 v[46:49], v[130:133], v[154:157], v[46:49]
	v_mfma_f32_16x16x32_bf16 v[42:45], v[138:141], v[154:157], v[42:45]
	v_mfma_f32_16x16x32_bf16 v[30:33], v[130:133], v[162:165], v[30:33]
	v_mfma_f32_16x16x32_bf16 v[26:29], v[138:141], v[162:165], v[26:29]
	v_mfma_f32_16x16x32_bf16 v[14:17], v[130:133], v[170:173], v[14:17]
	v_mfma_f32_16x16x32_bf16 v[10:13], v[138:141], v[170:173], v[10:13]
	v_mfma_f32_16x16x32_bf16 v[62:65], v[134:137], v[150:153], v[62:65]
	v_mfma_f32_16x16x32_bf16 v[58:61], v[142:145], v[150:153], v[58:61]
	v_mfma_f32_16x16x32_bf16 v[46:49], v[134:137], v[158:161], v[46:49]
	v_mfma_f32_16x16x32_bf16 v[42:45], v[142:145], v[158:161], v[42:45]
	v_mfma_f32_16x16x32_bf16 v[30:33], v[134:137], v[166:169], v[30:33]
	v_mfma_f32_16x16x32_bf16 v[26:29], v[142:145], v[166:169], v[26:29]
	v_mfma_f32_16x16x32_bf16 v[14:17], v[134:137], v[174:177], v[14:17]
	v_mfma_f32_16x16x32_bf16 v[10:13], v[142:145], v[174:177], v[10:13]
	s_barrier
	s_add_u32 s18, s18, 0x80080
	s_addc_u32 s19, s19, 0
	s_add_i32 s20, s20, s22
	v_lshl_add_u64 v[130:131], s[18:19], 0, v[0:1]
	s_mov_b32 m0, s20
	s_nop 0
	global_load_lds_dwordx4 v[130:131], off
	v_lshl_add_u64 v[130:131], s[18:19], 0, v[186:187]
	s_add_i32 m0, s20, 0x2000
	s_nop 0
	global_load_lds_dwordx4 v[130:131], off
	s_waitcnt vmcnt(6)
	s_barrier
	v_mfma_f32_16x16x32_bf16 v[54:57], v[178:181], v[146:149], v[54:57]
	v_mfma_f32_16x16x32_bf16 v[50:53], v[196:199], v[146:149], v[50:53]
	v_mfma_f32_16x16x32_bf16 v[38:41], v[178:181], v[154:157], v[38:41]
	v_mfma_f32_16x16x32_bf16 v[34:37], v[196:199], v[154:157], v[34:37]
	v_mfma_f32_16x16x32_bf16 v[22:25], v[178:181], v[162:165], v[22:25]
	v_mfma_f32_16x16x32_bf16 v[18:21], v[196:199], v[162:165], v[18:21]
	v_mfma_f32_16x16x32_bf16 v[6:9], v[178:181], v[170:173], v[6:9]
	v_mfma_f32_16x16x32_bf16 v[2:5], v[196:199], v[170:173], v[2:5]
	v_mfma_f32_16x16x32_bf16 v[54:57], v[182:185], v[150:153], v[54:57]
	v_mfma_f32_16x16x32_bf16 v[50:53], v[200:203], v[150:153], v[50:53]
	v_mfma_f32_16x16x32_bf16 v[38:41], v[182:185], v[158:161], v[38:41]
	v_mfma_f32_16x16x32_bf16 v[34:37], v[200:203], v[158:161], v[34:37]
	v_mfma_f32_16x16x32_bf16 v[22:25], v[182:185], v[166:169], v[22:25]
	v_mfma_f32_16x16x32_bf16 v[18:21], v[200:203], v[166:169], v[18:21]
	v_mfma_f32_16x16x32_bf16 v[6:9], v[182:185], v[174:177], v[6:9]
	v_mfma_f32_16x16x32_bf16 v[2:5], v[200:203], v[174:177], v[2:5]
	s_add_i32 s39, s39, 2
	s_add_u32 s10, s10, 0x100
	s_addc_u32 s11, s11, 0
	s_add_u32 s37, s37, 0x100
	s_addc_u32 s38, s38, 0
	s_cmp_gt_u32 s39, 29
	s_barrier
	s_cbranch_scc0 .LBB0_469
;     __device__ __forceinline__ void operator()(const f32x4 (&acc)[2][2][4][2], const Unit& u, int wr, int wc, int fr, int fq) const {
;         const int row0 = u.pm * BM + wr * 64 + fr, col0 = u.pn * BM + wc * 32 + 8 * fq;
;         if (INF32) {
; #pragma unroll
;             for (int ai = 0; ai < 2; ++ai) { f32x4 rin[4][2][2];
; #pragma unroll
;                 for (int m = 0; m < 4; ++m) { const int row = row0 + ai * HALF + m * 16;
;                     const float* rp = (row < TP ? r0 + (size_t)row * DM : r1 + (size_t)(row - TP) * DM) + col0;
; #pragma unroll
;                     for (int bj = 0; bj < 2; ++bj) { rin[m][bj][0] = *(const f32x4*)(rp + bj * HALF); rin[m][bj][1] = *(const f32x4*)(rp + bj * HALF + 4); } }
; #pragma unroll
;                 for (int m = 0; m < 4; ++m) { const int row = row0 + ai * HALF + m * 16; bf16_t* op = Xb + (size_t)row * DM + col0; float ps = 0.f;
; #pragma unroll
;                     for (int bj = 0; bj < 2; ++bj) finish(acc[ai][bj][m][0], acc[ai][bj][m][1], rin[m][bj][0], rin[m][bj][1], op + bj * HALF, ps);
;                     if (part) { ps += __shfl_xor(ps, 16, 64); ps += __shfl_xor(ps, 32, 64); if (fq == 0) part[(size_t)(u.pn * 4 + wc) * T_TOK + row] = ps; } } }
	v_lshl_add_u32 v196, s34, 8, v218
	s_movk_i32 s1, 0x4000
	v_readlane_b32 s72, v252, 6
	v_add_u32_e32 v130, 0xffffc000, v196
	v_ashrrev_i32_e32 v197, 31, v196
	v_cmp_gt_i32_e32 vcc, s1, v196
	v_readlane_b32 s73, v252, 7
	v_readlane_b32 s74, v252, 8
	v_readlane_b32 s75, v252, 9
	v_lshl_or_b32 v198, s31, 8, v220
	v_cndmask_b32_e32 v131, 0, v197, vcc
	v_cndmask_b32_e32 v130, v130, v196, vcc
	v_mov_b32_e32 v134, s75
	v_mov_b32_e32 v135, s73
	v_mov_b32_e32 v136, s74
	v_mov_b32_e32 v137, s72
	v_ashrrev_i32_e32 v199, 31, v198
	v_cndmask_b32_e32 v133, v134, v135, vcc
	v_cndmask_b32_e32 v132, v136, v137, vcc
	v_lshlrev_b64 v[130:131], 13, v[130:131]
	v_lshl_add_u64 v[130:131], v[132:133], 0, v[130:131]
	v_lshlrev_b64 v[200:201], 2, v[198:199]
	v_lshl_add_u64 v[130:131], v[130:131], 0, v[200:201]
	v_or_b32_e32 v206, 16, v196
	global_load_dwordx4 v[222:225], v[130:131], off offset:16
	global_load_dwordx4 v[226:229], v[130:131], off
	global_load_dwordx4 v[178:181], v[130:131], off offset:528
	global_load_dwordx4 v[182:185], v[130:131], off offset:512
	v_ashrrev_i32_e32 v207, 31, v206
	v_add_u32_e32 v130, 0xffffc010, v196
	v_cmp_gt_i32_e32 vcc, s1, v206
	v_or_b32_e32 v204, 32, v196
	v_ashrrev_i32_e32 v205, 31, v204
	v_cndmask_b32_e32 v131, 0, v207, vcc
	v_cndmask_b32_e32 v130, v130, v206, vcc
	v_cndmask_b32_e32 v133, v134, v135, vcc
	v_cndmask_b32_e32 v132, v136, v137, vcc
	v_lshlrev_b64 v[130:131], 13, v[130:131]
	v_lshl_add_u64 v[130:131], v[132:133], 0, v[130:131]
	v_lshl_add_u64 v[130:131], v[130:131], 0, v[200:201]
	global_load_dwordx4 v[170:173], v[130:131], off offset:16
	global_load_dwordx4 v[174:177], v[130:131], off
	global_load_dwordx4 v[162:165], v[130:131], off offset:528
	global_load_dwordx4 v[166:169], v[130:131], off offset:512
	v_add_u32_e32 v130, 0xffffc020, v196
	v_cmp_gt_i32_e32 vcc, s1, v204
	v_or_b32_e32 v202, 48, v196
	v_ashrrev_i32_e32 v203, 31, v202
	v_cndmask_b32_e32 v131, 0, v205, vcc
	v_cndmask_b32_e32 v130, v130, v204, vcc
	v_cndmask_b32_e32 v133, v134, v135, vcc
	v_cndmask_b32_e32 v132, v136, v137, vcc
	v_lshlrev_b64 v[130:131], 13, v[130:131]
	v_lshl_add_u64 v[130:131], v[132:133], 0, v[130:131]
	v_lshl_add_u64 v[130:131], v[130:131], 0, v[200:201]
	global_load_dwordx4 v[154:157], v[130:131], off offset:16
	global_load_dwordx4 v[158:161], v[130:131], off
	global_load_dwordx4 v[146:149], v[130:131], off offset:528
	global_load_dwordx4 v[150:153], v[130:131], off offset:512
	v_add_u32_e32 v130, 0xffffc030, v196
	v_cmp_gt_i32_e32 vcc, s1, v202
	v_readlane_b32 s18, v253, 35
	v_readlane_b32 s19, v253, 36
	v_cndmask_b32_e32 v131, 0, v203, vcc
	v_cndmask_b32_e32 v130, v130, v202, vcc
	v_cndmask_b32_e32 v133, v134, v135, vcc
	v_cndmask_b32_e32 v132, v136, v137, vcc
	v_lshlrev_b64 v[130:131], 13, v[130:131]
	v_lshl_add_u64 v[130:131], v[132:133], 0, v[130:131]
	v_lshl_add_u64 v[134:135], v[130:131], 0, v[200:201]
	global_load_dwordx4 v[138:141], v[134:135], off offset:16
	global_load_dwordx4 v[142:145], v[134:135], off
	global_load_dwordx4 v[130:133], v[134:135], off offset:528
	s_nop 0
	global_load_dwordx4 v[134:137], v[134:135], off offset:512
	v_cndmask_b32_e64 v208, 0, 1, s[18:19]
	v_cmp_ne_u32_e64 s[10:11], 1, v208
	v_lshlrev_b64 v[208:209], 12, v[196:197]
	v_lshl_add_u64 v[208:209], s[94:95], 0, v[208:209]
	s_andn2_b64 vcc, exec, s[18:19]
	v_lshl_add_u64 v[208:209], v[198:199], 1, v[208:209]
	v_readlane_b32 s76, v252, 10
	v_readlane_b32 s77, v252, 11
	v_readlane_b32 s78, v252, 12
	v_readlane_b32 s79, v252, 13
	v_readlane_b32 s80, v252, 14
	v_readlane_b32 s81, v252, 15
	v_readlane_b32 s82, v252, 16
	v_readlane_b32 s83, v252, 17
	v_readlane_b32 s84, v252, 18
	v_readlane_b32 s85, v252, 19
	v_readlane_b32 s86, v252, 20
	v_readlane_b32 s87, v252, 21
	s_waitcnt vmcnt(0)
	v_pk_add_f32 v[214:215], v[124:125], v[224:225]
	v_pk_add_f32 v[128:129], v[128:129], v[228:229]
	v_pk_add_f32 v[126:127], v[126:127], v[226:227]
	v_pk_add_f32 v[124:125], v[122:123], v[222:223]
	v_cvt_pk_bf16_f32 v122, v126, v127
	v_cvt_pk_bf16_f32 v123, v128, v129
	v_cvt_pk_bf16_f32 v124, v124, v125
	v_cvt_pk_bf16_f32 v125, v214, v215
	v_mov_b32_e32 v126, 0
	global_store_dwordx4 v[208:209], v[122:125], off
	s_cbranch_vccnz .LBB0_472
	v_lshlrev_b32_e32 v126, 16, v122
	v_and_b32_e32 v127, 0xffff0000, v122
	v_pk_mul_f32 v[126:127], v[126:127], v[126:127]
	v_and_b32_e32 v122, 0xffff0000, v123
	v_lshlrev_b32_e32 v123, 16, v123
	v_pk_mul_f32 v[122:123], v[122:123], v[122:123]
	v_add_f32_e32 v126, v126, v127
	v_and_b32_e32 v128, 0xffff0000, v124
	v_lshlrev_b32_e32 v129, 16, v124
	v_add_f32_e32 v123, v123, v126
	v_pk_mul_f32 v[128:129], v[128:129], v[128:129]
	v_add_f32_e32 v122, v122, v123
	v_and_b32_e32 v124, 0xffff0000, v125
	v_lshlrev_b32_e32 v125, 16, v125
	v_add_f32_e32 v122, v129, v122
	v_pk_mul_f32 v[124:125], v[124:125], v[124:125]
	v_add_f32_e32 v122, v128, v122
	v_add_f32_e32 v122, v125, v122
	v_add_f32_e32 v126, v124, v122

; #define PG8_STAGE(bufoff, gbase, voff) do { _Pragma("unroll") for (int _i = 0; _i < 2; ++_i) \
;         __builtin_amdgcn_global_load_lds((const unsigned*)((const char*)(gbase) + (voff)[_i]), (LAS unsigned*)(lds + (bufoff) + ldsw + _i * 8192), 16, 0, 0); } while (0)
; #define PG8_LDA(dst, b, h) do { _Pragma("unroll") for (int m = 0; m < 4; ++m) _Pragma("unroll") for (int k = 0; k < 2; ++k) dst[m][k] = *(const LAS bf16x8*)(lds + PG8_SA(b, h) + aoff + m * 2048 + k * 1024); } while (0)
; #define PG8_LDB(dst, b, h) do { _Pragma("unroll") for (int n = 0; n < 2; ++n) _Pragma("unroll") for (int k = 0; k < 2; ++k) dst[n][k] = *(const LAS bf16x8*)(lds + PG8_SB(b, h) + boff + n * 2048 + k * 1024); } while (0)
; #define PG8_MMA(ai, bj, At, Bt) do { __builtin_amdgcn_s_setprio(1); _Pragma("unroll") for (int m = 0; m < 4; ++m) _Pragma("unroll") for (int n = 0; n < 2; ++n) _Pragma("unroll") for (int k = 0; k < 2; ++k) \
;         acc[ai][bj][m][n] = __builtin_amdgcn_mfma_f32_16x16x32_bf16(Bt[n][k], At[m][k], acc[ai][bj][m][n], 0, 0, 0); __builtin_amdgcn_s_setprio(0); } while (0)
; #define PG8_WAIT_L(n) asm volatile("s_waitcnt lgkmcnt(" #n ")" ::: "memory")
; #define PG8_BAR __builtin_amdgcn_s_barrier()
; #define PG8_SCHED __builtin_amdgcn_sched_barrier(0)
; template <class Epi>
; __device__ __forceinline__ void gemm_phase(LAS unsigned char* lds, const Gemm g, const StaticOrder& S, const Epi& E) {
;     ...
;             PG8_LDB(B0, 0, 0); PG8_SCHED; PG8_LDA(At, 0, 0); PG8_STAGE(PG8_SA(1, 1), a1 + hstep, voffA);
;             PG8_WAIT_L(8); PG8_BAR; PG8_WAIT_L(0); PG8_MMA(0, 0, At, B0); PG8_BAR; PG8_SCHED;
;             PG8_LDB(B1, 0, 1); PG8_STAGE(PG8_SB(0, 0), b2, voffB);
;             PG8_BAR; PG8_WAIT_L(0); PG8_MMA(0, 1, At, B1); PG8_BAR;
;             PG8_LDA(At, 0, 1); PG8_STAGE(PG8_SA(0, 0), a2, voffA);
;             PG8_BAR; PG8_WAIT_L(0); PG8_MMA(1, 0, At, B0); PG8_BAR; PG8_SCHED;
.LBB0_582:
	s_add_u32 s16, s8, 0xfff80080
	s_addc_u32 s17, s9, -1
	s_add_i32 s37, 0, 0x10000
	v_add_u32_e32 v0, s37, v221
	ds_read_b128 v[102:105], v0
	ds_read_b128 v[110:113], v0 offset:1024
	ds_read_b128 v[114:117], v0 offset:2048
	ds_read_b128 v[118:121], v0 offset:3072
	s_cmp_eq_u32 s36, 28
	s_cselect_b32 s19, s11, s17
	s_cselect_b32 s18, s30, s16
	s_cselect_b32 s17, s1, s35
	s_cselect_b32 s16, s31, s34
	v_lshl_add_u64 v[170:171], s[8:9], 0, v[206:207]
	s_add_i32 m0, s21, 0xc000
	ds_read_b128 v[130:133], v225
	ds_read_b128 v[134:137], v225 offset:1024
	ds_read_b128 v[138:141], v225 offset:2048
	ds_read_b128 v[142:145], v225 offset:3072
	ds_read_b128 v[146:149], v225 offset:4096
	ds_read_b128 v[150:153], v225 offset:5120
	ds_read_b128 v[158:161], v225 offset:6144
	ds_read_b128 v[162:165], v225 offset:7168
	global_load_lds_dwordx4 v[170:171], off
	v_lshl_add_u64 v[170:171], s[8:9], 0, v[208:209]
	s_add_i32 m0, s21, 0xe000
	s_nop 0
	global_load_lds_dwordx4 v[170:171], off
	s_waitcnt lgkmcnt(8)
	s_barrier
	s_waitcnt lgkmcnt(0)
	s_waitcnt lgkmcnt(0)
	v_mfma_f32_16x16x32_bf16 v[126:129], v[102:105], v[138:141], v[126:129]
	v_mfma_f32_16x16x32_bf16 v[122:125], v[114:117], v[138:141], v[122:125]
	v_mfma_f32_16x16x32_bf16 v[94:97], v[102:105], v[146:149], v[94:97]
	v_mfma_f32_16x16x32_bf16 v[90:93], v[114:117], v[146:149], v[90:93]
	v_mfma_f32_16x16x32_bf16 v[78:81], v[102:105], v[158:161], v[78:81]
	v_mfma_f32_16x16x32_bf16 v[74:77], v[114:117], v[158:161], v[74:77]
	v_mfma_f32_16x16x32_bf16 v[170:173], v[102:105], v[130:133], v[186:189]
	v_mfma_f32_16x16x32_bf16 v[174:177], v[114:117], v[130:133], v[178:181]
	v_mfma_f32_16x16x32_bf16 v[126:129], v[110:113], v[142:145], v[126:129]
	v_mfma_f32_16x16x32_bf16 v[122:125], v[118:121], v[142:145], v[122:125]
	v_mfma_f32_16x16x32_bf16 v[94:97], v[110:113], v[150:153], v[94:97]
	v_mfma_f32_16x16x32_bf16 v[90:93], v[118:121], v[150:153], v[90:93]
	v_mfma_f32_16x16x32_bf16 v[78:81], v[110:113], v[162:165], v[78:81]
	v_mfma_f32_16x16x32_bf16 v[74:77], v[118:121], v[162:165], v[74:77]
	v_mfma_f32_16x16x32_bf16 v[170:173], v[110:113], v[134:137], v[170:173]
	v_mfma_f32_16x16x32_bf16 v[174:177], v[118:121], v[134:137], v[174:177]
	s_barrier
	s_add_i32 s40, 0, 0x14000
	s_add_i32 s37, s37, s20
	v_add_u32_e32 v0, s40, v221
	v_lshl_add_u64 v[226:227], s[16:17], 0, v[198:199]
	s_mov_b32 m0, s37
	ds_read_b128 v[178:181], v0
	ds_read_b128 v[182:185], v0 offset:1024
	ds_read_b128 v[186:189], v0 offset:2048
	ds_read_b128 v[190:193], v0 offset:3072
	global_load_lds_dwordx4 v[226:227], off
	v_lshl_add_u64 v[228:229], s[16:17], 0, v[194:195]
	s_add_i32 m0, s37, 0x2000
	s_nop 0
	global_load_lds_dwordx4 v[228:229], off
	s_barrier
	s_waitcnt lgkmcnt(0)
	s_waitcnt lgkmcnt(0)
	v_mfma_f32_16x16x32_bf16 v[166:169], v[178:181], v[130:133], v[166:169]
	v_mfma_f32_16x16x32_bf16 v[106:109], v[178:181], v[138:141], v[106:109]
	v_mfma_f32_16x16x32_bf16 v[98:101], v[186:189], v[138:141], v[98:101]
	v_mfma_f32_16x16x32_bf16 v[86:89], v[178:181], v[146:149], v[86:89]
	v_mfma_f32_16x16x32_bf16 v[82:85], v[186:189], v[146:149], v[82:85]
	v_mfma_f32_16x16x32_bf16 v[70:73], v[178:181], v[158:161], v[70:73]
	v_mfma_f32_16x16x32_bf16 v[66:69], v[186:189], v[158:161], v[66:69]
	v_mfma_f32_16x16x32_bf16 v[166:169], v[182:185], v[134:137], v[166:169]
	v_mfma_f32_16x16x32_bf16 v[130:133], v[186:189], v[130:133], v[154:157]
	v_mfma_f32_16x16x32_bf16 v[106:109], v[182:185], v[142:145], v[106:109]
	v_mfma_f32_16x16x32_bf16 v[98:101], v[190:193], v[142:145], v[98:101]
	v_mfma_f32_16x16x32_bf16 v[86:89], v[182:185], v[150:153], v[86:89]
	v_mfma_f32_16x16x32_bf16 v[82:85], v[190:193], v[150:153], v[82:85]
	v_mfma_f32_16x16x32_bf16 v[70:73], v[182:185], v[162:165], v[70:73]
	v_mfma_f32_16x16x32_bf16 v[66:69], v[190:193], v[162:165], v[66:69]
	v_mfma_f32_16x16x32_bf16 v[130:133], v[190:193], v[134:137], v[130:133]
	s_mov_b32 m0, s21
	v_lshl_add_u64 v[232:233], s[18:19], 0, v[200:201]
	s_barrier
	ds_read_b128 v[134:137], v225 offset:16384
	ds_read_b128 v[138:141], v225 offset:17408
	ds_read_b128 v[142:145], v225 offset:18432
	ds_read_b128 v[146:149], v225 offset:19456
	ds_read_b128 v[150:153], v225 offset:20480
	ds_read_b128 v[154:157], v225 offset:21504
	ds_read_b128 v[158:161], v225 offset:22528
	ds_read_b128 v[162:165], v225 offset:23552
	global_load_lds_dwordx4 v[232:233], off
	v_lshl_add_u64 v[236:237], s[18:19], 0, v[196:197]
	s_mov_b32 m0, s22
	s_nop 0
	global_load_lds_dwordx4 v[236:237], off
	s_barrier
	s_waitcnt lgkmcnt(0)
	s_waitcnt lgkmcnt(0)
	v_mfma_f32_16x16x32_bf16 v[62:65], v[102:105], v[134:137], v[62:65]
	v_mfma_f32_16x16x32_bf16 v[58:61], v[114:117], v[134:137], v[58:61]
	v_mfma_f32_16x16x32_bf16 v[46:49], v[102:105], v[142:145], v[46:49]
	v_mfma_f32_16x16x32_bf16 v[42:45], v[114:117], v[142:145], v[42:45]
	v_mfma_f32_16x16x32_bf16 v[30:33], v[102:105], v[150:153], v[30:33]
	v_mfma_f32_16x16x32_bf16 v[26:29], v[114:117], v[150:153], v[26:29]
	v_mfma_f32_16x16x32_bf16 v[14:17], v[102:105], v[158:161], v[14:17]
	v_mfma_f32_16x16x32_bf16 v[10:13], v[114:117], v[158:161], v[10:13]
	v_mfma_f32_16x16x32_bf16 v[62:65], v[110:113], v[138:141], v[62:65]
	v_mfma_f32_16x16x32_bf16 v[58:61], v[118:121], v[138:141], v[58:61]
	v_mfma_f32_16x16x32_bf16 v[46:49], v[110:113], v[146:149], v[46:49]
	v_mfma_f32_16x16x32_bf16 v[42:45], v[118:121], v[146:149], v[42:45]
	v_mfma_f32_16x16x32_bf16 v[30:33], v[110:113], v[154:157], v[30:33]
	v_mfma_f32_16x16x32_bf16 v[26:29], v[118:121], v[154:157], v[26:29]
	v_mfma_f32_16x16x32_bf16 v[14:17], v[110:113], v[162:165], v[14:17]
	v_mfma_f32_16x16x32_bf16 v[10:13], v[118:121], v[162:165], v[10:13]
	s_barrier
; #define PG8_STAGE(bufoff, gbase, voff) do { _Pragma("unroll") for (int _i = 0; _i < 2; ++_i) \
;         __builtin_amdgcn_global_load_lds((const unsigned*)((const char*)(gbase) + (voff)[_i]), (LAS unsigned*)(lds + (bufoff) + ldsw + _i * 8192), 16, 0, 0); } while (0)
; #define PG8_LDA(dst, b, h) do { _Pragma("unroll") for (int m = 0; m < 4; ++m) _Pragma("unroll") for (int k = 0; k < 2; ++k) dst[m][k] = *(const LAS bf16x8*)(lds + PG8_SA(b, h) + aoff + m * 2048 + k * 1024); } while (0)
; #define PG8_LDB(dst, b, h) do { _Pragma("unroll") for (int n = 0; n < 2; ++n) _Pragma("unroll") for (int k = 0; k < 2; ++k) dst[n][k] = *(const LAS bf16x8*)(lds + PG8_SB(b, h) + boff + n * 2048 + k * 1024); } while (0)
; #define PG8_MMA(ai, bj, At, Bt) do { __builtin_amdgcn_s_setprio(1); _Pragma("unroll") for (int m = 0; m < 4; ++m) _Pragma("unroll") for (int n = 0; n < 2; ++n) _Pragma("unroll") for (int k = 0; k < 2; ++k) \
;         acc[ai][bj][m][n] = __builtin_amdgcn_mfma_f32_16x16x32_bf16(Bt[n][k], At[m][k], acc[ai][bj][m][n], 0, 0, 0); __builtin_amdgcn_s_setprio(0); } while (0)
; #define PG8_WAIT_V(n) asm volatile("s_waitcnt vmcnt(" #n ")" ::: "memory")
; #define PG8_WAIT_L(n) asm volatile("s_waitcnt lgkmcnt(" #n ")" ::: "memory")
; #define PG8_BAR __builtin_amdgcn_s_barrier()
; #define PG8_SCHED __builtin_amdgcn_sched_barrier(0)
; template <class Epi>
; __device__ __forceinline__ void gemm_phase(LAS unsigned char* lds, const Gemm g, const StaticOrder& S, const Epi& E) {
;     ...
;             PG8_STAGE(PG8_SB(0, 1), b2 + hstep, voffB);
;             PG8_WAIT_V(6); PG8_BAR; PG8_MMA(1, 1, At, B1); PG8_BAR;
;             PG8_LDB(B0, 1, 0); PG8_SCHED; PG8_LDA(At, 1, 0); PG8_STAGE(PG8_SA(0, 1), a2 + hstep, voffA);
;             PG8_WAIT_L(8); PG8_BAR; PG8_WAIT_L(0); PG8_MMA(0, 0, At, B0); PG8_BAR; PG8_SCHED;
;             PG8_LDB(B1, 1, 1); PG8_STAGE(PG8_SB(1, 0), b3, voffB);
;             PG8_BAR; PG8_WAIT_L(0); PG8_MMA(0, 1, At, B1); PG8_BAR;
	s_add_u32 s38, s16, 0x80000
	s_addc_u32 s39, s17, 0
	s_add_i32 s37, s40, s20
	v_lshl_add_u64 v[102:103], s[38:39], 0, v[198:199]
	s_mov_b32 m0, s37
	s_nop 0
	global_load_lds_dwordx4 v[102:103], off
	v_lshl_add_u64 v[102:103], s[38:39], 0, v[194:195]
	s_add_i32 m0, s37, 0x2000
	s_nop 0
	global_load_lds_dwordx4 v[102:103], off
	s_waitcnt vmcnt(6)
	s_barrier
	v_mfma_f32_16x16x32_bf16 v[54:57], v[178:181], v[134:137], v[54:57]
	v_mfma_f32_16x16x32_bf16 v[50:53], v[186:189], v[134:137], v[50:53]
	v_mfma_f32_16x16x32_bf16 v[38:41], v[178:181], v[142:145], v[38:41]
	v_mfma_f32_16x16x32_bf16 v[34:37], v[186:189], v[142:145], v[34:37]
	v_mfma_f32_16x16x32_bf16 v[22:25], v[178:181], v[150:153], v[22:25]
	v_mfma_f32_16x16x32_bf16 v[18:21], v[186:189], v[150:153], v[18:21]
	v_mfma_f32_16x16x32_bf16 v[6:9], v[178:181], v[158:161], v[6:9]
	v_mfma_f32_16x16x32_bf16 v[2:5], v[186:189], v[158:161], v[2:5]
	v_mfma_f32_16x16x32_bf16 v[54:57], v[182:185], v[138:141], v[54:57]
	v_mfma_f32_16x16x32_bf16 v[50:53], v[190:193], v[138:141], v[50:53]
	v_mfma_f32_16x16x32_bf16 v[38:41], v[182:185], v[146:149], v[38:41]
	v_mfma_f32_16x16x32_bf16 v[34:37], v[190:193], v[146:149], v[34:37]
	v_mfma_f32_16x16x32_bf16 v[22:25], v[182:185], v[154:157], v[22:25]
	v_mfma_f32_16x16x32_bf16 v[18:21], v[190:193], v[154:157], v[18:21]
	v_mfma_f32_16x16x32_bf16 v[6:9], v[182:185], v[162:165], v[6:9]
	v_mfma_f32_16x16x32_bf16 v[2:5], v[190:193], v[162:165], v[2:5]
	s_add_i32 s37, 0, 0x18000
	v_add_u32_e32 v0, s37, v221
	s_barrier
	ds_read_b128 v[102:105], v0
	ds_read_b128 v[110:113], v0 offset:1024
	ds_read_b128 v[114:117], v0 offset:2048
	ds_read_b128 v[118:121], v0 offset:3072
	s_add_u32 s18, s18, 0x80000
	s_addc_u32 s19, s19, 0
	s_mov_b32 m0, s23
	v_lshl_add_u64 v[154:155], s[18:19], 0, v[200:201]
	ds_read_b128 v[134:137], v225 offset:32768
	ds_read_b128 v[138:141], v225 offset:33792
	ds_read_b128 v[142:145], v225 offset:34816
	ds_read_b128 v[146:149], v225 offset:35840
	ds_read_b128 v[150:153], v225 offset:36864
	ds_read_b128 v[158:161], v225 offset:37888
	ds_read_b128 v[162:165], v225 offset:38912
	ds_read_b128 v[182:185], v225 offset:39936
	global_load_lds_dwordx4 v[154:155], off
	v_lshl_add_u64 v[154:155], s[18:19], 0, v[196:197]
	s_mov_b32 m0, s24
	s_nop 0
	global_load_lds_dwordx4 v[154:155], off
	s_waitcnt lgkmcnt(8)
	s_barrier
	s_waitcnt lgkmcnt(0)
	s_waitcnt lgkmcnt(0)
	v_mfma_f32_16x16x32_bf16 v[154:157], v[102:105], v[134:137], v[170:173]
	v_mfma_f32_16x16x32_bf16 v[186:189], v[110:113], v[138:141], v[154:157]
	v_mfma_f32_16x16x32_bf16 v[154:157], v[114:117], v[134:137], v[174:177]
	v_mfma_f32_16x16x32_bf16 v[126:129], v[102:105], v[142:145], v[126:129]
	v_mfma_f32_16x16x32_bf16 v[122:125], v[114:117], v[142:145], v[122:125]
	v_mfma_f32_16x16x32_bf16 v[94:97], v[102:105], v[150:153], v[94:97]
	v_mfma_f32_16x16x32_bf16 v[90:93], v[114:117], v[150:153], v[90:93]
	v_mfma_f32_16x16x32_bf16 v[78:81], v[102:105], v[162:165], v[78:81]
	v_mfma_f32_16x16x32_bf16 v[74:77], v[114:117], v[162:165], v[74:77]
	v_mfma_f32_16x16x32_bf16 v[178:181], v[118:121], v[138:141], v[154:157]
	v_mfma_f32_16x16x32_bf16 v[126:129], v[110:113], v[146:149], v[126:129]
	v_mfma_f32_16x16x32_bf16 v[122:125], v[118:121], v[146:149], v[122:125]
	v_mfma_f32_16x16x32_bf16 v[94:97], v[110:113], v[158:161], v[94:97]
	v_mfma_f32_16x16x32_bf16 v[90:93], v[118:121], v[158:161], v[90:93]
	v_mfma_f32_16x16x32_bf16 v[78:81], v[110:113], v[182:185], v[78:81]
	v_mfma_f32_16x16x32_bf16 v[74:77], v[118:121], v[182:185], v[74:77]
	s_barrier
	s_add_i32 s18, 0, 0x1c000
	s_add_i32 s19, s37, s20
	v_add_u32_e32 v0, s18, v221
	v_lshl_add_u64 v[154:155], v[226:227], 0, s[66:67]
	s_mov_b32 m0, s19
	ds_read_b128 v[170:173], v0
	ds_read_b128 v[174:177], v0 offset:1024
	ds_read_b128 v[190:193], v0 offset:2048
	ds_read_b128 v[214:217], v0 offset:3072
	global_load_lds_dwordx4 v[154:155], off
	v_lshl_add_u64 v[154:155], v[228:229], 0, s[66:67]
	s_add_i32 m0, s19, 0x2000
	s_nop 0
	global_load_lds_dwordx4 v[154:155], off
	s_barrier
	s_waitcnt lgkmcnt(0)
	s_waitcnt lgkmcnt(0)
	v_mfma_f32_16x16x32_bf16 v[154:157], v[170:173], v[134:137], v[166:169]
	v_mfma_f32_16x16x32_bf16 v[130:133], v[190:193], v[134:137], v[130:133]
	v_mfma_f32_16x16x32_bf16 v[106:109], v[170:173], v[142:145], v[106:109]
	v_mfma_f32_16x16x32_bf16 v[98:101], v[190:193], v[142:145], v[98:101]
	v_mfma_f32_16x16x32_bf16 v[86:89], v[170:173], v[150:153], v[86:89]
	v_mfma_f32_16x16x32_bf16 v[82:85], v[190:193], v[150:153], v[82:85]
	v_mfma_f32_16x16x32_bf16 v[70:73], v[170:173], v[162:165], v[70:73]
	v_mfma_f32_16x16x32_bf16 v[66:69], v[190:193], v[162:165], v[66:69]
	v_mfma_f32_16x16x32_bf16 v[166:169], v[174:177], v[138:141], v[154:157]
	v_mfma_f32_16x16x32_bf16 v[154:157], v[214:217], v[138:141], v[130:133]
	v_mfma_f32_16x16x32_bf16 v[106:109], v[174:177], v[146:149], v[106:109]
	v_mfma_f32_16x16x32_bf16 v[98:101], v[214:217], v[146:149], v[98:101]
	v_mfma_f32_16x16x32_bf16 v[86:89], v[174:177], v[158:161], v[86:89]
	v_mfma_f32_16x16x32_bf16 v[82:85], v[214:217], v[158:161], v[82:85]
	v_mfma_f32_16x16x32_bf16 v[70:73], v[174:177], v[182:185], v[70:73]
	v_mfma_f32_16x16x32_bf16 v[66:69], v[214:217], v[182:185], v[66:69]
	s_mov_b32 m0, s25
	v_lshl_add_u64 v[182:183], v[232:233], 0, s[66:67]
	s_barrier
	ds_read_b128 v[130:133], v225 offset:49152
	ds_read_b128 v[134:137], v225 offset:50176
	ds_read_b128 v[138:141], v225 offset:51200
	ds_read_b128 v[142:145], v225 offset:52224
	ds_read_b128 v[146:149], v225 offset:53248
	ds_read_b128 v[150:153], v225 offset:54272
	ds_read_b128 v[158:161], v225 offset:55296
	ds_read_b128 v[162:165], v225 offset:56320
	global_load_lds_dwordx4 v[182:183], off
	v_lshl_add_u64 v[182:183], v[236:237], 0, s[66:67]
	s_mov_b32 m0, s26
	s_nop 0
	global_load_lds_dwordx4 v[182:183], off
	s_barrier
; #define PG8_STAGE(bufoff, gbase, voff) do { _Pragma("unroll") for (int _i = 0; _i < 2; ++_i) \
;         __builtin_amdgcn_global_load_lds((const unsigned*)((const char*)(gbase) + (voff)[_i]), (LAS unsigned*)(lds + (bufoff) + ldsw + _i * 8192), 16, 0, 0); } while (0)
; #define PG8_LDA(dst, b, h) do { _Pragma("unroll") for (int m = 0; m < 4; ++m) _Pragma("unroll") for (int k = 0; k < 2; ++k) dst[m][k] = *(const LAS bf16x8*)(lds + PG8_SA(b, h) + aoff + m * 2048 + k * 1024); } while (0)
; #define PG8_WAIT_V(n) asm volatile("s_waitcnt vmcnt(" #n ")" ::: "memory")
; #define PG8_WAIT_L(n) asm volatile("s_waitcnt lgkmcnt(" #n ")" ::: "memory")
; #define PG8_BAR __builtin_amdgcn_s_barrier()
; #define PG8_SCHED __builtin_amdgcn_sched_barrier(0)
; template <class Epi>
; __device__ __forceinline__ void gemm_phase(LAS unsigned char* lds, const Gemm g, const StaticOrder& S, const Epi& E) {
;     ...
;             PG8_LDA(At, 1, 1); PG8_STAGE(PG8_SA(1, 0), a3, voffA);
;             PG8_BAR; PG8_WAIT_L(0); PG8_MMA(1, 0, At, B0); PG8_BAR; PG8_SCHED;
;             PG8_STAGE(PG8_SB(1, 1), b3 + hstep, voffB);
;             PG8_WAIT_V(6); PG8_BAR; PG8_MMA(1, 1, At, B1); PG8_BAR;
;     __device__ __forceinline__ void operator()(const f32x4 (&acc)[2][2][4][2], const Unit& u, int wr, int wc, int fr, int fq) const {
;         const int sect = u.pn >> 3;
;         bf16_t* base = R + (size_t)sect * ((size_t)T_TOK * DM);
;         const int row0 = u.pm * BM + wr * 64 + fr;
;         const int w = wc * 32 + 8 * fq, head2 = w >> 6, i0 = w & 63;
;         const int colbase = (u.pn & 7) * BM + head2 * 128 + i0;
;         float rqv[2][4];
; #pragma unroll
;         for (int ai = 0; ai < 2; ++ai)
; #pragma unroll
;             for (int m = 0; m < 4; ++m) rqv[ai][m] = rstd[row0 + ai * HALF + m * 16];
; #pragma unroll
;         for (int ai = 0; ai < 2; ++ai) {
;             f32x4 cs[4][4];
;             if (sect < 2) {
; #pragma unroll
;                 for (int m = 0; m < 4; ++m) { const int row = row0 + ai * HALF + m * 16; const int pos = row < TP ? row : ((row - TP) & 2047);
;                     cs[m][0] = *(const f32x4*)(rc + (size_t)pos * 64 + i0); cs[m][1] = *(const f32x4*)(rc + (size_t)pos * 64 + i0 + 4);
;                     cs[m][2] = *(const f32x4*)(rs + (size_t)pos * 64 + i0); cs[m][3] = *(const f32x4*)(rs + (size_t)pos * 64 + i0 + 4); }
	s_waitcnt lgkmcnt(0)
	s_waitcnt lgkmcnt(0)
	v_mfma_f32_16x16x32_bf16 v[62:65], v[102:105], v[130:133], v[62:65]
	v_mfma_f32_16x16x32_bf16 v[58:61], v[114:117], v[130:133], v[58:61]
	v_mfma_f32_16x16x32_bf16 v[46:49], v[102:105], v[138:141], v[46:49]
	v_mfma_f32_16x16x32_bf16 v[42:45], v[114:117], v[138:141], v[42:45]
	v_mfma_f32_16x16x32_bf16 v[30:33], v[102:105], v[146:149], v[30:33]
	v_mfma_f32_16x16x32_bf16 v[26:29], v[114:117], v[146:149], v[26:29]
	v_mfma_f32_16x16x32_bf16 v[14:17], v[102:105], v[158:161], v[14:17]
	v_mfma_f32_16x16x32_bf16 v[10:13], v[114:117], v[158:161], v[10:13]
	v_mfma_f32_16x16x32_bf16 v[62:65], v[110:113], v[134:137], v[62:65]
	v_mfma_f32_16x16x32_bf16 v[58:61], v[118:121], v[134:137], v[58:61]
	v_mfma_f32_16x16x32_bf16 v[46:49], v[110:113], v[142:145], v[46:49]
	v_mfma_f32_16x16x32_bf16 v[42:45], v[118:121], v[142:145], v[42:45]
	v_mfma_f32_16x16x32_bf16 v[30:33], v[110:113], v[150:153], v[30:33]
	v_mfma_f32_16x16x32_bf16 v[26:29], v[118:121], v[150:153], v[26:29]
	v_mfma_f32_16x16x32_bf16 v[14:17], v[110:113], v[162:165], v[14:17]
	v_mfma_f32_16x16x32_bf16 v[10:13], v[118:121], v[162:165], v[10:13]
	s_barrier
	s_add_u32 s16, s16, 0x80080
	s_addc_u32 s17, s17, 0
	s_add_i32 s18, s18, s20
	v_lshl_add_u64 v[102:103], s[16:17], 0, v[198:199]
	s_mov_b32 m0, s18
	s_nop 0
	global_load_lds_dwordx4 v[102:103], off
	v_lshl_add_u64 v[102:103], s[16:17], 0, v[194:195]
	s_add_i32 m0, s18, 0x2000
	s_nop 0
	global_load_lds_dwordx4 v[102:103], off
	s_waitcnt vmcnt(6)
	s_barrier
	v_mfma_f32_16x16x32_bf16 v[54:57], v[170:173], v[130:133], v[54:57]
	v_mfma_f32_16x16x32_bf16 v[50:53], v[190:193], v[130:133], v[50:53]
	v_mfma_f32_16x16x32_bf16 v[38:41], v[170:173], v[138:141], v[38:41]
	v_mfma_f32_16x16x32_bf16 v[34:37], v[190:193], v[138:141], v[34:37]
	v_mfma_f32_16x16x32_bf16 v[22:25], v[170:173], v[146:149], v[22:25]
	v_mfma_f32_16x16x32_bf16 v[18:21], v[190:193], v[146:149], v[18:21]
	v_mfma_f32_16x16x32_bf16 v[6:9], v[170:173], v[158:161], v[6:9]
	v_mfma_f32_16x16x32_bf16 v[2:5], v[190:193], v[158:161], v[2:5]
	v_mfma_f32_16x16x32_bf16 v[54:57], v[174:177], v[134:137], v[54:57]
	v_mfma_f32_16x16x32_bf16 v[50:53], v[214:217], v[134:137], v[50:53]
	v_mfma_f32_16x16x32_bf16 v[38:41], v[174:177], v[142:145], v[38:41]
	v_mfma_f32_16x16x32_bf16 v[34:37], v[214:217], v[142:145], v[34:37]
	v_mfma_f32_16x16x32_bf16 v[22:25], v[174:177], v[150:153], v[22:25]
	v_mfma_f32_16x16x32_bf16 v[18:21], v[214:217], v[150:153], v[18:21]
	v_mfma_f32_16x16x32_bf16 v[6:9], v[174:177], v[162:165], v[6:9]
	v_mfma_f32_16x16x32_bf16 v[2:5], v[214:217], v[162:165], v[2:5]
	s_add_i32 s36, s36, 2
	s_add_u32 s8, s8, 0x100
	s_addc_u32 s9, s9, 0
	s_add_u32 s34, s34, 0x100
	s_addc_u32 s35, s35, 0
	s_cmp_gt_u32 s36, 29
	s_barrier
	s_cbranch_scc0 .LBB0_582
	v_lshl_add_u32 v226, s29, 8, v219
	v_ashrrev_i32_e32 v227, 31, v226
	v_or_b32_e32 v236, 16, v226
	v_or_b32_e32 v232, 32, v226
	v_or_b32_e32 v228, 48, v226
	v_lshl_add_u64 v[102:103], v[226:227], 2, s[82:83]
	v_ashrrev_i32_e32 v237, 31, v236
	v_ashrrev_i32_e32 v233, 31, v232
	v_ashrrev_i32_e32 v229, 31, v228
	v_lshl_add_u64 v[104:105], v[236:237], 2, s[82:83]
	v_lshl_add_u64 v[110:111], v[232:233], 2, s[82:83]
	v_lshl_add_u64 v[112:113], v[228:229], 2, s[82:83]
	global_load_dword v0, v[102:103], off
	global_load_dword v238, v[104:105], off
	global_load_dword v234, v[110:111], off
	global_load_dword v230, v[112:113], off
	global_load_dword v224, v[102:103], off offset:512
	global_load_dword v222, v[102:103], off offset:576
	global_load_dword v220, v[102:103], off offset:640
	global_load_dword v218, v[102:103], off offset:704
	s_ashr_i32 s16, s28, 3
	s_cmp_lt_i32 s16, 2
	s_cselect_b64 s[18:19], -1, 0
	s_cmp_gt_i32 s16, 1
	s_cbranch_scc1 .LBB0_585
	s_movk_i32 s1, 0x4000
	v_and_b32_e32 v102, 0x7cf, v226
	v_cmp_gt_i32_e32 vcc, s1, v226
	s_nop 1
	v_cndmask_b32_e32 v102, v102, v226, vcc
	v_ashrrev_i32_e32 v103, 31, v102
	v_lshlrev_b64 v[102:103], 8, v[102:103]
	v_lshl_add_u64 v[104:105], v[202:203], 0, v[102:103]
	v_lshl_add_u64 v[102:103], v[204:205], 0, v[102:103]
	global_load_dwordx4 v[170:173], v[104:105], off offset:16
	global_load_dwordx4 v[174:177], v[104:105], off
	global_load_dwordx4 v[182:185], v[102:103], off offset:16
	global_load_dwordx4 v[190:193], v[102:103], off
	v_and_b32_e32 v102, 0x7df, v236
	v_cmp_gt_i32_e32 vcc, s1, v236
	s_nop 1
	v_cndmask_b32_e32 v102, v102, v236, vcc
	v_ashrrev_i32_e32 v103, 31, v102
	v_lshlrev_b64 v[102:103], 8, v[102:103]
	v_lshl_add_u64 v[104:105], v[202:203], 0, v[102:103]
	v_lshl_add_u64 v[102:103], v[204:205], 0, v[102:103]
	global_load_dwordx4 v[146:149], v[104:105], off offset:16
	global_load_dwordx4 v[150:153], v[104:105], off
	global_load_dwordx4 v[158:161], v[102:103], off offset:16
	global_load_dwordx4 v[162:165], v[102:103], off
	v_and_b32_e32 v102, 0x7ef, v232
	v_cmp_gt_i32_e32 vcc, s1, v232
	s_nop 1
	v_cndmask_b32_e32 v102, v102, v232, vcc
	v_ashrrev_i32_e32 v103, 31, v102
	v_lshlrev_b64 v[102:103], 8, v[102:103]
	v_lshl_add_u64 v[104:105], v[202:203], 0, v[102:103]
	v_lshl_add_u64 v[102:103], v[204:205], 0, v[102:103]
	global_load_dwordx4 v[130:133], v[104:105], off offset:16
	global_load_dwordx4 v[134:137], v[104:105], off
	global_load_dwordx4 v[138:141], v[102:103], off offset:16
	global_load_dwordx4 v[142:145], v[102:103], off
	v_and_b32_e32 v102, 0x7ff, v228
	v_cmp_gt_i32_e32 vcc, s1, v228
	s_nop 1
	v_cndmask_b32_e32 v102, v102, v228, vcc
	v_ashrrev_i32_e32 v103, 31, v102
	v_lshlrev_b64 v[114:115], 8, v[102:103]
	v_lshl_add_u64 v[110:111], v[202:203], 0, v[114:115]
	v_lshl_add_u64 v[118:119], v[204:205], 0, v[114:115]
	global_load_dwordx4 v[102:105], v[110:111], off offset:16
	s_nop 0
	global_load_dwordx4 v[110:113], v[110:111], off
	s_nop 0
	global_load_dwordx4 v[114:117], v[118:119], off offset:16
	s_nop 0
	global_load_dwordx4 v[118:121], v[118:119], off

; #define PG8_STAGE(bufoff, gbase, voff) do { _Pragma("unroll") for (int _i = 0; _i < 2; ++_i) \
;         __builtin_amdgcn_global_load_lds((const unsigned*)((const char*)(gbase) + (voff)[_i]), (LAS unsigned*)(lds + (bufoff) + ldsw + _i * 8192), 16, 0, 0); } while (0)
; #define PG8_LDA(dst, b, h) do { _Pragma("unroll") for (int m = 0; m < 4; ++m) _Pragma("unroll") for (int k = 0; k < 2; ++k) dst[m][k] = *(const LAS bf16x8*)(lds + PG8_SA(b, h) + aoff + m * 2048 + k * 1024); } while (0)
; #define PG8_LDB(dst, b, h) do { _Pragma("unroll") for (int n = 0; n < 2; ++n) _Pragma("unroll") for (int k = 0; k < 2; ++k) dst[n][k] = *(const LAS bf16x8*)(lds + PG8_SB(b, h) + boff + n * 2048 + k * 1024); } while (0)
; #define PG8_MMA(ai, bj, At, Bt) do { __builtin_amdgcn_s_setprio(1); _Pragma("unroll") for (int m = 0; m < 4; ++m) _Pragma("unroll") for (int n = 0; n < 2; ++n) _Pragma("unroll") for (int k = 0; k < 2; ++k) \
;         acc[ai][bj][m][n] = __builtin_amdgcn_mfma_f32_16x16x32_bf16(Bt[n][k], At[m][k], acc[ai][bj][m][n], 0, 0, 0); __builtin_amdgcn_s_setprio(0); } while (0)
; #define PG8_WAIT_L(n) asm volatile("s_waitcnt lgkmcnt(" #n ")" ::: "memory")
; #define PG8_BAR __builtin_amdgcn_s_barrier()
; #define PG8_SCHED __builtin_amdgcn_sched_barrier(0)
; template <class Epi>
; __device__ __forceinline__ void gemm_phase(LAS unsigned char* lds, const Gemm g, const StaticOrder& S, const Epi& E) {
;     ...
;             PG8_LDB(B0, 0, 0); PG8_SCHED; PG8_LDA(At, 0, 0); PG8_STAGE(PG8_SA(1, 1), a1 + hstep, voffA);
;             PG8_WAIT_L(8); PG8_BAR; PG8_WAIT_L(0); PG8_MMA(0, 0, At, B0); PG8_BAR; PG8_SCHED;
;             PG8_LDB(B1, 0, 1); PG8_STAGE(PG8_SB(0, 0), b2, voffB);
;             PG8_BAR; PG8_WAIT_L(0); PG8_MMA(0, 1, At, B1); PG8_BAR;
;             PG8_LDA(At, 0, 1); PG8_STAGE(PG8_SA(0, 0), a2, voffA);
;             PG8_BAR; PG8_WAIT_L(0); PG8_MMA(1, 0, At, B0); PG8_BAR; PG8_SCHED;
.LBB0_749:
	s_add_u32 s18, s10, 0xfff80080
	s_addc_u32 s19, s11, -1
	s_add_i32 s40, 0, 0x10000
	v_add_u32_e32 v118, s40, v229
	ds_read_b128 v[86:89], v118
	ds_read_b128 v[94:97], v118 offset:1024
	ds_read_b128 v[106:109], v118 offset:2048
	ds_read_b128 v[118:121], v118 offset:3072
	s_cmp_eq_u32 s39, 28
	s_cselect_b32 s21, s13, s19
	s_cselect_b32 s20, s35, s18
	s_cselect_b32 s19, s1, s38
	s_cselect_b32 s18, s36, s37
	v_lshl_add_u64 v[178:179], s[10:11], 0, v[196:197]
	s_add_i32 m0, s23, 0xc000
	ds_read_b128 v[130:133], v232
	ds_read_b128 v[142:145], v232 offset:1024
	ds_read_b128 v[154:157], v232 offset:2048
	ds_read_b128 v[158:161], v232 offset:3072
	ds_read_b128 v[162:165], v232 offset:4096
	ds_read_b128 v[166:169], v232 offset:5120
	ds_read_b128 v[170:173], v232 offset:6144
	ds_read_b128 v[174:177], v232 offset:7168
	global_load_lds_dwordx4 v[178:179], off
	v_lshl_add_u64 v[178:179], s[10:11], 0, v[198:199]
	s_add_i32 m0, s23, 0xe000
	s_nop 0
	global_load_lds_dwordx4 v[178:179], off
	s_waitcnt lgkmcnt(8)
	s_barrier
	s_waitcnt lgkmcnt(0)
	s_waitcnt lgkmcnt(0)
	v_mfma_f32_16x16x32_bf16 v[150:153], v[86:89], v[130:133], v[150:153]
	v_mfma_f32_16x16x32_bf16 v[146:149], v[106:109], v[130:133], v[146:149]
	v_mfma_f32_16x16x32_bf16 v[126:129], v[86:89], v[154:157], v[126:129]
	v_mfma_f32_16x16x32_bf16 v[122:125], v[106:109], v[154:157], v[122:125]
	v_mfma_f32_16x16x32_bf16 v[102:105], v[86:89], v[162:165], v[102:105]
	v_mfma_f32_16x16x32_bf16 v[98:101], v[106:109], v[162:165], v[98:101]
	v_mfma_f32_16x16x32_bf16 v[78:81], v[86:89], v[170:173], v[78:81]
	v_mfma_f32_16x16x32_bf16 v[74:77], v[106:109], v[170:173], v[74:77]
	v_mfma_f32_16x16x32_bf16 v[150:153], v[94:97], v[142:145], v[150:153]
	v_mfma_f32_16x16x32_bf16 v[146:149], v[118:121], v[142:145], v[146:149]
	v_mfma_f32_16x16x32_bf16 v[126:129], v[94:97], v[158:161], v[126:129]
	v_mfma_f32_16x16x32_bf16 v[122:125], v[118:121], v[158:161], v[122:125]
	v_mfma_f32_16x16x32_bf16 v[102:105], v[94:97], v[166:169], v[102:105]
	v_mfma_f32_16x16x32_bf16 v[98:101], v[118:121], v[166:169], v[98:101]
	v_mfma_f32_16x16x32_bf16 v[78:81], v[94:97], v[174:177], v[78:81]
	v_mfma_f32_16x16x32_bf16 v[74:77], v[118:121], v[174:177], v[74:77]
	s_barrier
	s_add_i32 s42, 0, 0x14000
	s_add_i32 s40, s40, s22
	v_add_u32_e32 v200, s42, v229
	v_lshl_add_u64 v[204:205], s[18:19], 0, v[0:1]
	s_mov_b32 m0, s40
	ds_read_b128 v[178:181], v200
	ds_read_b128 v[182:185], v200 offset:1024
	ds_read_b128 v[186:189], v200 offset:2048
	ds_read_b128 v[200:203], v200 offset:3072
	global_load_lds_dwordx4 v[204:205], off
	v_lshl_add_u64 v[206:207], s[18:19], 0, v[190:191]
	s_add_i32 m0, s40, 0x2000
	s_nop 0
	global_load_lds_dwordx4 v[206:207], off
	s_barrier
	s_waitcnt lgkmcnt(0)
	s_waitcnt lgkmcnt(0)
	v_mfma_f32_16x16x32_bf16 v[138:141], v[178:181], v[130:133], v[138:141]
	v_mfma_f32_16x16x32_bf16 v[114:117], v[178:181], v[154:157], v[114:117]
	v_mfma_f32_16x16x32_bf16 v[110:113], v[186:189], v[154:157], v[110:113]
	v_mfma_f32_16x16x32_bf16 v[90:93], v[178:181], v[162:165], v[90:93]
	v_mfma_f32_16x16x32_bf16 v[82:85], v[186:189], v[162:165], v[82:85]
	v_mfma_f32_16x16x32_bf16 v[70:73], v[178:181], v[170:173], v[70:73]
	v_mfma_f32_16x16x32_bf16 v[66:69], v[186:189], v[170:173], v[66:69]
	v_mfma_f32_16x16x32_bf16 v[138:141], v[182:185], v[142:145], v[138:141]
	v_mfma_f32_16x16x32_bf16 v[130:133], v[186:189], v[130:133], v[134:137]
	v_mfma_f32_16x16x32_bf16 v[114:117], v[182:185], v[158:161], v[114:117]
	v_mfma_f32_16x16x32_bf16 v[110:113], v[200:203], v[158:161], v[110:113]
	v_mfma_f32_16x16x32_bf16 v[90:93], v[182:185], v[166:169], v[90:93]
	v_mfma_f32_16x16x32_bf16 v[82:85], v[200:203], v[166:169], v[82:85]
	v_mfma_f32_16x16x32_bf16 v[70:73], v[182:185], v[174:177], v[70:73]
	v_mfma_f32_16x16x32_bf16 v[66:69], v[200:203], v[174:177], v[66:69]
	v_mfma_f32_16x16x32_bf16 v[130:133], v[200:203], v[142:145], v[130:133]
	s_mov_b32 m0, s23
	v_lshl_add_u64 v[208:209], s[20:21], 0, v[194:195]
	s_barrier
	ds_read_b128 v[134:137], v232 offset:16384
	ds_read_b128 v[142:145], v232 offset:17408
	ds_read_b128 v[154:157], v232 offset:18432
	ds_read_b128 v[158:161], v232 offset:19456
	ds_read_b128 v[162:165], v232 offset:20480
	ds_read_b128 v[166:169], v232 offset:21504
	ds_read_b128 v[170:173], v232 offset:22528
	ds_read_b128 v[174:177], v232 offset:23552
	global_load_lds_dwordx4 v[208:209], off
	v_lshl_add_u64 v[214:215], s[20:21], 0, v[192:193]
	s_mov_b32 m0, s24
	s_nop 0
	global_load_lds_dwordx4 v[214:215], off
	s_barrier
	s_waitcnt lgkmcnt(0)
	s_waitcnt lgkmcnt(0)
	v_mfma_f32_16x16x32_bf16 v[62:65], v[86:89], v[134:137], v[62:65]
	v_mfma_f32_16x16x32_bf16 v[58:61], v[106:109], v[134:137], v[58:61]
	v_mfma_f32_16x16x32_bf16 v[46:49], v[86:89], v[154:157], v[46:49]
	v_mfma_f32_16x16x32_bf16 v[42:45], v[106:109], v[154:157], v[42:45]
	v_mfma_f32_16x16x32_bf16 v[30:33], v[86:89], v[162:165], v[30:33]
	v_mfma_f32_16x16x32_bf16 v[26:29], v[106:109], v[162:165], v[26:29]
	v_mfma_f32_16x16x32_bf16 v[14:17], v[86:89], v[170:173], v[14:17]
	v_mfma_f32_16x16x32_bf16 v[10:13], v[106:109], v[170:173], v[10:13]
	v_mfma_f32_16x16x32_bf16 v[62:65], v[94:97], v[142:145], v[62:65]
	v_mfma_f32_16x16x32_bf16 v[58:61], v[118:121], v[142:145], v[58:61]
	v_mfma_f32_16x16x32_bf16 v[46:49], v[94:97], v[158:161], v[46:49]
	v_mfma_f32_16x16x32_bf16 v[42:45], v[118:121], v[158:161], v[42:45]
	v_mfma_f32_16x16x32_bf16 v[30:33], v[94:97], v[166:169], v[30:33]
	v_mfma_f32_16x16x32_bf16 v[26:29], v[118:121], v[166:169], v[26:29]
	v_mfma_f32_16x16x32_bf16 v[14:17], v[94:97], v[174:177], v[14:17]
	v_mfma_f32_16x16x32_bf16 v[10:13], v[118:121], v[174:177], v[10:13]
	s_barrier
; #define PG8_STAGE(bufoff, gbase, voff) do { _Pragma("unroll") for (int _i = 0; _i < 2; ++_i) \
;         __builtin_amdgcn_global_load_lds((const unsigned*)((const char*)(gbase) + (voff)[_i]), (LAS unsigned*)(lds + (bufoff) + ldsw + _i * 8192), 16, 0, 0); } while (0)
; #define PG8_LDA(dst, b, h) do { _Pragma("unroll") for (int m = 0; m < 4; ++m) _Pragma("unroll") for (int k = 0; k < 2; ++k) dst[m][k] = *(const LAS bf16x8*)(lds + PG8_SA(b, h) + aoff + m * 2048 + k * 1024); } while (0)
; #define PG8_LDB(dst, b, h) do { _Pragma("unroll") for (int n = 0; n < 2; ++n) _Pragma("unroll") for (int k = 0; k < 2; ++k) dst[n][k] = *(const LAS bf16x8*)(lds + PG8_SB(b, h) + boff + n * 2048 + k * 1024); } while (0)
; #define PG8_MMA(ai, bj, At, Bt) do { __builtin_amdgcn_s_setprio(1); _Pragma("unroll") for (int m = 0; m < 4; ++m) _Pragma("unroll") for (int n = 0; n < 2; ++n) _Pragma("unroll") for (int k = 0; k < 2; ++k) \
;         acc[ai][bj][m][n] = __builtin_amdgcn_mfma_f32_16x16x32_bf16(Bt[n][k], At[m][k], acc[ai][bj][m][n], 0, 0, 0); __builtin_amdgcn_s_setprio(0); } while (0)
; #define PG8_WAIT_V(n) asm volatile("s_waitcnt vmcnt(" #n ")" ::: "memory")
; #define PG8_WAIT_L(n) asm volatile("s_waitcnt lgkmcnt(" #n ")" ::: "memory")
; #define PG8_BAR __builtin_amdgcn_s_barrier()
; #define PG8_SCHED __builtin_amdgcn_sched_barrier(0)
; template <class Epi>
; __device__ __forceinline__ void gemm_phase(LAS unsigned char* lds, const Gemm g, const StaticOrder& S, const Epi& E) {
;     ...
;             PG8_STAGE(PG8_SB(0, 1), b2 + hstep, voffB);
;             PG8_WAIT_V(6); PG8_BAR; PG8_MMA(1, 1, At, B1); PG8_BAR;
;             PG8_LDB(B0, 1, 0); PG8_SCHED; PG8_LDA(At, 1, 0); PG8_STAGE(PG8_SA(0, 1), a2 + hstep, voffA);
;             PG8_WAIT_L(8); PG8_BAR; PG8_WAIT_L(0); PG8_MMA(0, 0, At, B0); PG8_BAR; PG8_SCHED;
;             PG8_LDB(B1, 1, 1); PG8_STAGE(PG8_SB(1, 0), b3, voffB);
;             PG8_BAR; PG8_WAIT_L(0); PG8_MMA(0, 1, At, B1); PG8_BAR;
	s_add_u32 s40, s18, 0x80000
	s_addc_u32 s41, s19, 0
	s_add_i32 s42, s42, s22
	v_lshl_add_u64 v[86:87], s[40:41], 0, v[0:1]
	s_mov_b32 m0, s42
	s_nop 0
	global_load_lds_dwordx4 v[86:87], off
	v_lshl_add_u64 v[86:87], s[40:41], 0, v[190:191]
	s_add_i32 m0, s42, 0x2000
	s_nop 0
	global_load_lds_dwordx4 v[86:87], off
	s_waitcnt vmcnt(6)
	s_barrier
	v_mfma_f32_16x16x32_bf16 v[54:57], v[178:181], v[134:137], v[54:57]
	v_mfma_f32_16x16x32_bf16 v[50:53], v[186:189], v[134:137], v[50:53]
	v_mfma_f32_16x16x32_bf16 v[38:41], v[178:181], v[154:157], v[38:41]
	v_mfma_f32_16x16x32_bf16 v[34:37], v[186:189], v[154:157], v[34:37]
	v_mfma_f32_16x16x32_bf16 v[22:25], v[178:181], v[162:165], v[22:25]
	v_mfma_f32_16x16x32_bf16 v[18:21], v[186:189], v[162:165], v[18:21]
	v_mfma_f32_16x16x32_bf16 v[6:9], v[178:181], v[170:173], v[6:9]
	v_mfma_f32_16x16x32_bf16 v[2:5], v[186:189], v[170:173], v[2:5]
	v_mfma_f32_16x16x32_bf16 v[54:57], v[182:185], v[142:145], v[54:57]
	v_mfma_f32_16x16x32_bf16 v[50:53], v[200:203], v[142:145], v[50:53]
	v_mfma_f32_16x16x32_bf16 v[38:41], v[182:185], v[158:161], v[38:41]
	v_mfma_f32_16x16x32_bf16 v[34:37], v[200:203], v[158:161], v[34:37]
	v_mfma_f32_16x16x32_bf16 v[22:25], v[182:185], v[166:169], v[22:25]
	v_mfma_f32_16x16x32_bf16 v[18:21], v[200:203], v[166:169], v[18:21]
	v_mfma_f32_16x16x32_bf16 v[6:9], v[182:185], v[174:177], v[6:9]
	v_mfma_f32_16x16x32_bf16 v[2:5], v[200:203], v[174:177], v[2:5]
	s_add_i32 s40, 0, 0x18000
	v_add_u32_e32 v118, s40, v229
	s_barrier
	ds_read_b128 v[86:89], v118
	ds_read_b128 v[94:97], v118 offset:1024
	ds_read_b128 v[106:109], v118 offset:2048
	ds_read_b128 v[118:121], v118 offset:3072
	s_add_u32 s20, s20, 0x80000
	s_addc_u32 s21, s21, 0
	s_mov_b32 m0, s25
	v_lshl_add_u64 v[178:179], s[20:21], 0, v[194:195]
	ds_read_b128 v[134:137], v232 offset:32768
	ds_read_b128 v[142:145], v232 offset:33792
	ds_read_b128 v[154:157], v232 offset:34816
	ds_read_b128 v[158:161], v232 offset:35840
	ds_read_b128 v[162:165], v232 offset:36864
	ds_read_b128 v[166:169], v232 offset:37888
	ds_read_b128 v[170:173], v232 offset:38912
	ds_read_b128 v[174:177], v232 offset:39936
	global_load_lds_dwordx4 v[178:179], off
	v_lshl_add_u64 v[178:179], s[20:21], 0, v[192:193]
	s_mov_b32 m0, s26
	s_nop 0
	global_load_lds_dwordx4 v[178:179], off
	s_waitcnt lgkmcnt(8)
	s_barrier
	s_waitcnt lgkmcnt(0)
	s_waitcnt lgkmcnt(0)
	v_mfma_f32_16x16x32_bf16 v[150:153], v[86:89], v[134:137], v[150:153]
	v_mfma_f32_16x16x32_bf16 v[146:149], v[106:109], v[134:137], v[146:149]
	v_mfma_f32_16x16x32_bf16 v[126:129], v[86:89], v[154:157], v[126:129]
	v_mfma_f32_16x16x32_bf16 v[122:125], v[106:109], v[154:157], v[122:125]
	v_mfma_f32_16x16x32_bf16 v[102:105], v[86:89], v[162:165], v[102:105]
	v_mfma_f32_16x16x32_bf16 v[98:101], v[106:109], v[162:165], v[98:101]
	v_mfma_f32_16x16x32_bf16 v[78:81], v[86:89], v[170:173], v[78:81]
	v_mfma_f32_16x16x32_bf16 v[74:77], v[106:109], v[170:173], v[74:77]
	v_mfma_f32_16x16x32_bf16 v[150:153], v[94:97], v[142:145], v[150:153]
	v_mfma_f32_16x16x32_bf16 v[146:149], v[118:121], v[142:145], v[146:149]
	v_mfma_f32_16x16x32_bf16 v[126:129], v[94:97], v[158:161], v[126:129]
	v_mfma_f32_16x16x32_bf16 v[122:125], v[118:121], v[158:161], v[122:125]
	v_mfma_f32_16x16x32_bf16 v[102:105], v[94:97], v[166:169], v[102:105]
	v_mfma_f32_16x16x32_bf16 v[98:101], v[118:121], v[166:169], v[98:101]
	v_mfma_f32_16x16x32_bf16 v[78:81], v[94:97], v[174:177], v[78:81]
	v_mfma_f32_16x16x32_bf16 v[74:77], v[118:121], v[174:177], v[74:77]
	s_barrier
	s_add_i32 s20, 0, 0x1c000
	s_add_i32 s21, s40, s22
	v_add_u32_e32 v200, s20, v229
	v_lshl_add_u64 v[204:205], v[204:205], 0, s[66:67]
	s_mov_b32 m0, s21
	ds_read_b128 v[178:181], v200
	ds_read_b128 v[182:185], v200 offset:1024
	ds_read_b128 v[186:189], v200 offset:2048
	ds_read_b128 v[200:203], v200 offset:3072
	global_load_lds_dwordx4 v[204:205], off
	v_lshl_add_u64 v[204:205], v[206:207], 0, s[66:67]
	s_add_i32 m0, s21, 0x2000
	s_nop 0
	global_load_lds_dwordx4 v[204:205], off
	s_barrier
	s_waitcnt lgkmcnt(0)
	s_waitcnt lgkmcnt(0)
	v_mfma_f32_16x16x32_bf16 v[138:141], v[178:181], v[134:137], v[138:141]
	v_mfma_f32_16x16x32_bf16 v[130:133], v[186:189], v[134:137], v[130:133]
	v_mfma_f32_16x16x32_bf16 v[114:117], v[178:181], v[154:157], v[114:117]
	v_mfma_f32_16x16x32_bf16 v[110:113], v[186:189], v[154:157], v[110:113]
	v_mfma_f32_16x16x32_bf16 v[90:93], v[178:181], v[162:165], v[90:93]
	v_mfma_f32_16x16x32_bf16 v[82:85], v[186:189], v[162:165], v[82:85]
	v_mfma_f32_16x16x32_bf16 v[70:73], v[178:181], v[170:173], v[70:73]
	v_mfma_f32_16x16x32_bf16 v[66:69], v[186:189], v[170:173], v[66:69]
	v_mfma_f32_16x16x32_bf16 v[138:141], v[182:185], v[142:145], v[138:141]
	v_mfma_f32_16x16x32_bf16 v[134:137], v[200:203], v[142:145], v[130:133]
	v_mfma_f32_16x16x32_bf16 v[114:117], v[182:185], v[158:161], v[114:117]
	v_mfma_f32_16x16x32_bf16 v[110:113], v[200:203], v[158:161], v[110:113]
	v_mfma_f32_16x16x32_bf16 v[90:93], v[182:185], v[166:169], v[90:93]
	v_mfma_f32_16x16x32_bf16 v[82:85], v[200:203], v[166:169], v[82:85]
	v_mfma_f32_16x16x32_bf16 v[70:73], v[182:185], v[174:177], v[70:73]
	v_mfma_f32_16x16x32_bf16 v[66:69], v[200:203], v[174:177], v[66:69]
	s_mov_b32 m0, s28
	v_lshl_add_u64 v[204:205], v[208:209], 0, s[66:67]
	s_barrier
	ds_read_b128 v[130:133], v232 offset:49152
	ds_read_b128 v[142:145], v232 offset:50176
	ds_read_b128 v[154:157], v232 offset:51200
	ds_read_b128 v[158:161], v232 offset:52224
	ds_read_b128 v[162:165], v232 offset:53248
	ds_read_b128 v[166:169], v232 offset:54272
	ds_read_b128 v[170:173], v232 offset:55296
	ds_read_b128 v[174:177], v232 offset:56320
	global_load_lds_dwordx4 v[204:205], off
	v_lshl_add_u64 v[204:205], v[214:215], 0, s[66:67]
	s_mov_b32 m0, s29
	s_nop 0
	global_load_lds_dwordx4 v[204:205], off
	s_barrier
; __device__ __forceinline__ float bflo(unsigned w) { return __uint_as_float(w << 16); }
; __device__ __forceinline__ float bfhi(unsigned w) { return __uint_as_float(w & 0xffff0000u); }
; #define PG8_STAGE(bufoff, gbase, voff) do { _Pragma("unroll") for (int _i = 0; _i < 2; ++_i) \
;         __builtin_amdgcn_global_load_lds((const unsigned*)((const char*)(gbase) + (voff)[_i]), (LAS unsigned*)(lds + (bufoff) + ldsw + _i * 8192), 16, 0, 0); } while (0)
; #define PG8_LDA(dst, b, h) do { _Pragma("unroll") for (int m = 0; m < 4; ++m) _Pragma("unroll") for (int k = 0; k < 2; ++k) dst[m][k] = *(const LAS bf16x8*)(lds + PG8_SA(b, h) + aoff + m * 2048 + k * 1024); } while (0)
; #define PG8_MMA(ai, bj, At, Bt) do { __builtin_amdgcn_s_setprio(1); _Pragma("unroll") for (int m = 0; m < 4; ++m) _Pragma("unroll") for (int n = 0; n < 2; ++n) _Pragma("unroll") for (int k = 0; k < 2; ++k) \
;         acc[ai][bj][m][n] = __builtin_amdgcn_mfma_f32_16x16x32_bf16(Bt[n][k], At[m][k], acc[ai][bj][m][n], 0, 0, 0); __builtin_amdgcn_s_setprio(0); } while (0)
; template <class Epi>
; __device__ __forceinline__ void gemm_phase(LAS unsigned char* lds, const Gemm g, const StaticOrder& S, const Epi& E) {
;     ...
;             PG8_BAR; PG8_WAIT_L(0); PG8_MMA(0, 1, At, B1); PG8_BAR;
;             PG8_LDA(At, 1, 1); PG8_STAGE(PG8_SA(1, 0), a3, voffA);
;             PG8_BAR; PG8_WAIT_L(0); PG8_MMA(1, 0, At, B0); PG8_BAR; PG8_SCHED;
;             PG8_STAGE(PG8_SB(1, 1), b3 + hstep, voffB);
;             PG8_WAIT_V(6); PG8_BAR; PG8_MMA(1, 1, At, B1); PG8_BAR;
;     __device__ __forceinline__ void operator()(const f32x4 (&acc)[2][2][4][2], const Unit& u, int wr, int wc, int fr, int fq) const {
;     ...
;                     for (int bj = 0; bj < 2; ++bj) xin[ai][m][bj] = *(const u32x4*)(Xb + (size_t)(row0 + ai * HALF + m * 16) * DM + col0 + bj * HALF);
; #pragma unroll
;             for (int ai = 0; ai < 2; ++ai)
; #pragma unroll
;                 for (int m = 0; m < 4; ++m) { const int row = row0 + ai * HALF + m * 16; bf16_t* op = Xb + (size_t)row * DM + col0; float ps = 0.f;
; #pragma unroll
;                     for (int bj = 0; bj < 2; ++bj) { const u32x4 x = xin[ai][m][bj];
;                         finish(acc[ai][bj][m][0], acc[ai][bj][m][1], (f32x4){bflo(x.x), bfhi(x.x), bflo(x.y), bfhi(x.y)}, (f32x4){bflo(x.z), bfhi(x.z), bflo(x.w), bfhi(x.w)}, op + bj * HALF, ps); }
	s_waitcnt lgkmcnt(0)
	s_waitcnt lgkmcnt(0)
	v_mfma_f32_16x16x32_bf16 v[62:65], v[86:89], v[130:133], v[62:65]
	v_mfma_f32_16x16x32_bf16 v[58:61], v[106:109], v[130:133], v[58:61]
	v_mfma_f32_16x16x32_bf16 v[46:49], v[86:89], v[154:157], v[46:49]
	v_mfma_f32_16x16x32_bf16 v[42:45], v[106:109], v[154:157], v[42:45]
	v_mfma_f32_16x16x32_bf16 v[30:33], v[86:89], v[162:165], v[30:33]
	v_mfma_f32_16x16x32_bf16 v[26:29], v[106:109], v[162:165], v[26:29]
	v_mfma_f32_16x16x32_bf16 v[14:17], v[86:89], v[170:173], v[14:17]
	v_mfma_f32_16x16x32_bf16 v[10:13], v[106:109], v[170:173], v[10:13]
	v_mfma_f32_16x16x32_bf16 v[62:65], v[94:97], v[142:145], v[62:65]
	v_mfma_f32_16x16x32_bf16 v[58:61], v[118:121], v[142:145], v[58:61]
	v_mfma_f32_16x16x32_bf16 v[46:49], v[94:97], v[158:161], v[46:49]
	v_mfma_f32_16x16x32_bf16 v[42:45], v[118:121], v[158:161], v[42:45]
	v_mfma_f32_16x16x32_bf16 v[30:33], v[94:97], v[166:169], v[30:33]
	v_mfma_f32_16x16x32_bf16 v[26:29], v[118:121], v[166:169], v[26:29]
	v_mfma_f32_16x16x32_bf16 v[14:17], v[94:97], v[174:177], v[14:17]
	v_mfma_f32_16x16x32_bf16 v[10:13], v[118:121], v[174:177], v[10:13]
	s_barrier
	s_add_u32 s18, s18, 0x80080
	s_addc_u32 s19, s19, 0
	s_add_i32 s20, s20, s22
	v_lshl_add_u64 v[86:87], s[18:19], 0, v[0:1]
	s_mov_b32 m0, s20
	s_nop 0
	global_load_lds_dwordx4 v[86:87], off
	v_lshl_add_u64 v[86:87], s[18:19], 0, v[190:191]
	s_add_i32 m0, s20, 0x2000
	s_nop 0
	global_load_lds_dwordx4 v[86:87], off
	s_waitcnt vmcnt(6)
	s_barrier
	v_mfma_f32_16x16x32_bf16 v[54:57], v[178:181], v[130:133], v[54:57]
	v_mfma_f32_16x16x32_bf16 v[50:53], v[186:189], v[130:133], v[50:53]
	v_mfma_f32_16x16x32_bf16 v[38:41], v[178:181], v[154:157], v[38:41]
	v_mfma_f32_16x16x32_bf16 v[34:37], v[186:189], v[154:157], v[34:37]
	v_mfma_f32_16x16x32_bf16 v[22:25], v[178:181], v[162:165], v[22:25]
	v_mfma_f32_16x16x32_bf16 v[18:21], v[186:189], v[162:165], v[18:21]
	v_mfma_f32_16x16x32_bf16 v[6:9], v[178:181], v[170:173], v[6:9]
	v_mfma_f32_16x16x32_bf16 v[2:5], v[186:189], v[170:173], v[2:5]
	v_mfma_f32_16x16x32_bf16 v[54:57], v[182:185], v[142:145], v[54:57]
	v_mfma_f32_16x16x32_bf16 v[50:53], v[200:203], v[142:145], v[50:53]
	v_mfma_f32_16x16x32_bf16 v[38:41], v[182:185], v[158:161], v[38:41]
	v_mfma_f32_16x16x32_bf16 v[34:37], v[200:203], v[158:161], v[34:37]
	v_mfma_f32_16x16x32_bf16 v[22:25], v[182:185], v[166:169], v[22:25]
	v_mfma_f32_16x16x32_bf16 v[18:21], v[200:203], v[166:169], v[18:21]
	v_mfma_f32_16x16x32_bf16 v[6:9], v[182:185], v[174:177], v[6:9]
	v_mfma_f32_16x16x32_bf16 v[2:5], v[200:203], v[174:177], v[2:5]
	s_add_i32 s39, s39, 2
	s_add_u32 s10, s10, 0x100
	s_addc_u32 s11, s11, 0
	s_add_u32 s37, s37, 0x100
	s_addc_u32 s38, s38, 0
	s_cmp_gt_u32 s39, 29
	s_barrier
	s_cbranch_scc0 .LBB0_749
	v_lshl_or_b32 v202, s31, 8, v230
	v_lshl_add_u32 v200, s34, 8, v228
	v_ashrrev_i32_e32 v203, 31, v202
	v_lshlrev_b64 v[226:227], 1, v[202:203]
	v_ashrrev_i32_e32 v201, 31, v200
	v_lshl_add_u64 v[86:87], s[94:95], 0, v[226:227]
	v_lshlrev_b64 v[236:237], 12, v[200:201]
	v_lshl_add_u64 v[88:89], v[86:87], 0, v[236:237]
	global_load_dwordx4 v[214:217], v[88:89], off
	global_load_dwordx4 v[186:189], v[88:89], off offset:256
	v_or_b32_e32 v88, 16, v200
	v_ashrrev_i32_e32 v89, 31, v88
	v_lshlrev_b64 v[224:225], 12, v[88:89]
	v_lshl_add_u64 v[88:89], v[86:87], 0, v[224:225]
	global_load_dwordx4 v[182:185], v[88:89], off
	global_load_dwordx4 v[178:181], v[88:89], off offset:256
	v_or_b32_e32 v88, 32, v200
	v_ashrrev_i32_e32 v89, 31, v88
	v_lshlrev_b64 v[222:223], 12, v[88:89]
	v_lshl_add_u64 v[88:89], v[86:87], 0, v[222:223]
	global_load_dwordx4 v[174:177], v[88:89], off
	global_load_dwordx4 v[170:173], v[88:89], off offset:256
	v_or_b32_e32 v88, 48, v200
	v_ashrrev_i32_e32 v89, 31, v88
	s_mov_b64 s[10:11], 0x80000
	v_lshlrev_b64 v[220:221], 12, v[88:89]
	v_lshl_add_u64 v[218:219], v[236:237], 0, s[10:11]
	s_mov_b64 s[10:11], 0x90000
	v_lshl_add_u64 v[88:89], v[86:87], 0, v[220:221]
	v_lshl_add_u64 v[208:209], v[236:237], 0, s[10:11]
	s_mov_b64 s[10:11], 0xa0000
	global_load_dwordx4 v[166:169], v[88:89], off
	global_load_dwordx4 v[162:165], v[88:89], off offset:256
	v_lshl_add_u64 v[88:89], v[86:87], 0, v[218:219]
	v_lshl_add_u64 v[206:207], v[236:237], 0, s[10:11]
	s_mov_b64 s[10:11], 0xb0000
	global_load_dwordx4 v[158:161], v[88:89], off
	global_load_dwordx4 v[154:157], v[88:89], off offset:256
	v_lshl_add_u64 v[88:89], v[86:87], 0, v[208:209]
	v_lshl_add_u64 v[204:205], v[236:237], 0, s[10:11]
	global_load_dwordx4 v[142:145], v[88:89], off
	global_load_dwordx4 v[130:133], v[88:89], off offset:256
	v_lshl_add_u64 v[88:89], v[86:87], 0, v[206:207]
	v_lshl_add_u64 v[86:87], v[86:87], 0, v[204:205]
	global_load_dwordx4 v[118:121], v[88:89], off
	global_load_dwordx4 v[106:109], v[88:89], off offset:256
	global_load_dwordx4 v[94:97], v[86:87], off
	s_nop 0
	global_load_dwordx4 v[86:89], v[86:87], off offset:256
	v_readlane_b32 s18, v253, 35
	v_lshl_add_u64 v[236:237], s[94:95], 0, v[236:237]
	v_readlane_b32 s19, v253, 36
	v_lshl_add_u64 v[226:227], v[236:237], 0, v[226:227]
	s_andn2_b64 vcc, exec, s[18:19]
	v_cndmask_b32_e64 v233, 0, 1, s[18:19]
	v_cmp_ne_u32_e64 s[10:11], 1, v233
	s_waitcnt vmcnt(0)
	v_lshlrev_b32_e32 v236, 16, v214
	v_and_b32_e32 v237, 0xffff0000, v214
	v_lshlrev_b32_e32 v214, 16, v215
	v_and_b32_e32 v215, 0xffff0000, v215
	v_lshlrev_b32_e32 v240, 16, v216
	v_and_b32_e32 v241, 0xffff0000, v216
	v_lshlrev_b32_e32 v216, 16, v217
	v_and_b32_e32 v217, 0xffff0000, v217
	v_pk_add_f32 v[152:153], v[152:153], v[214:215]
	v_pk_add_f32 v[150:151], v[150:151], v[236:237]
	v_pk_add_f32 v[214:215], v[148:149], v[216:217]
	v_pk_add_f32 v[148:149], v[146:147], v[240:241]
	v_cvt_pk_bf16_f32 v146, v150, v151
	v_cvt_pk_bf16_f32 v147, v152, v153
	v_cvt_pk_bf16_f32 v148, v148, v149
	v_cvt_pk_bf16_f32 v149, v214, v215
	v_mov_b32_e32 v150, 0
	global_store_dwordx4 v[226:227], v[146:149], off
	s_cbranch_vccnz .LBB0_752
	v_lshlrev_b32_e32 v150, 16, v146
	v_and_b32_e32 v151, 0xffff0000, v146
	v_pk_mul_f32 v[150:151], v[150:151], v[150:151]
	v_and_b32_e32 v146, 0xffff0000, v147
	v_lshlrev_b32_e32 v147, 16, v147
	v_pk_mul_f32 v[146:147], v[146:147], v[146:147]
	v_add_f32_e32 v150, v150, v151
	v_and_b32_e32 v152, 0xffff0000, v148
	v_lshlrev_b32_e32 v153, 16, v148
	v_add_f32_e32 v147, v147, v150
	v_pk_mul_f32 v[152:153], v[152:153], v[152:153]
	v_add_f32_e32 v146, v146, v147
	v_and_b32_e32 v148, 0xffff0000, v149
	v_lshlrev_b32_e32 v149, 16, v149
	v_add_f32_e32 v146, v153, v146
	v_pk_mul_f32 v[148:149], v[148:149], v[148:149]
	v_add_f32_e32 v146, v152, v146
	v_add_f32_e32 v146, v149, v146
	v_add_f32_e32 v150, v148, v146

; #define PG8_STAGE(bufoff, gbase, voff) do { _Pragma("unroll") for (int _i = 0; _i < 2; ++_i) \
;         __builtin_amdgcn_global_load_lds((const unsigned*)((const char*)(gbase) + (voff)[_i]), (LAS unsigned*)(lds + (bufoff) + ldsw + _i * 8192), 16, 0, 0); } while (0)
; #define PG8_LDA(dst, b, h) do { _Pragma("unroll") for (int m = 0; m < 4; ++m) _Pragma("unroll") for (int k = 0; k < 2; ++k) dst[m][k] = *(const LAS bf16x8*)(lds + PG8_SA(b, h) + aoff + m * 2048 + k * 1024); } while (0)
; #define PG8_LDB(dst, b, h) do { _Pragma("unroll") for (int n = 0; n < 2; ++n) _Pragma("unroll") for (int k = 0; k < 2; ++k) dst[n][k] = *(const LAS bf16x8*)(lds + PG8_SB(b, h) + boff + n * 2048 + k * 1024); } while (0)
; #define PG8_MMA(ai, bj, At, Bt) do { __builtin_amdgcn_s_setprio(1); _Pragma("unroll") for (int m = 0; m < 4; ++m) _Pragma("unroll") for (int n = 0; n < 2; ++n) _Pragma("unroll") for (int k = 0; k < 2; ++k) \
;         acc[ai][bj][m][n] = __builtin_amdgcn_mfma_f32_16x16x32_bf16(Bt[n][k], At[m][k], acc[ai][bj][m][n], 0, 0, 0); __builtin_amdgcn_s_setprio(0); } while (0)
; #define PG8_WAIT_V(n) asm volatile("s_waitcnt vmcnt(" #n ")" ::: "memory")
; #define PG8_WAIT_L(n) asm volatile("s_waitcnt lgkmcnt(" #n ")" ::: "memory")
; #define PG8_BAR __builtin_amdgcn_s_barrier()
; #define PG8_SCHED __builtin_amdgcn_sched_barrier(0)
; template <class Epi>
; __device__ __forceinline__ void gemm_phase(LAS unsigned char* lds, const Gemm g, const StaticOrder& S, const Epi& E) {
;     ...
;             PG8_LDB(B0, 0, 0); PG8_SCHED; PG8_LDA(At, 0, 0); PG8_STAGE(PG8_SA(1, 1), a1 + hstep, voffA);
;             PG8_WAIT_L(8); PG8_BAR; PG8_WAIT_L(0); PG8_MMA(0, 0, At, B0); PG8_BAR; PG8_SCHED;
;             PG8_LDB(B1, 0, 1); PG8_STAGE(PG8_SB(0, 0), b2, voffB);
;             PG8_BAR; PG8_WAIT_L(0); PG8_MMA(0, 1, At, B1); PG8_BAR;
;             PG8_LDA(At, 0, 1); PG8_STAGE(PG8_SA(0, 0), a2, voffA);
;             PG8_BAR; PG8_WAIT_L(0); PG8_MMA(1, 0, At, B0); PG8_BAR; PG8_SCHED;
;             PG8_STAGE(PG8_SB(0, 1), b2 + hstep, voffB);
;             PG8_WAIT_V(6); PG8_BAR; PG8_MMA(1, 1, At, B1); PG8_BAR;
.LBB0_917:
	s_add_u32 s20, s18, 0xfff80080
	s_addc_u32 s21, s19, -1
	s_add_i32 s43, 0, 0x10000
	v_add_u32_e32 v140, s43, v143
	ds_read_b128 v[150:153], v140
	ds_read_b128 v[154:157], v140 offset:1024
	ds_read_b128 v[158:161], v140 offset:2048
	ds_read_b128 v[162:165], v140 offset:3072
	s_cmp_eq_u32 s42, 28
	s_cselect_b32 s23, s9, s21
	s_cselect_b32 s22, s38, s20
	s_cselect_b32 s21, s1, s41
	s_cselect_b32 s20, s39, s40
	v_lshl_add_u64 v[144:145], s[18:19], 0, v[136:137]
	s_add_i32 m0, s27, 0xc000
	ds_read_b128 v[166:169], v149
	ds_read_b128 v[170:173], v149 offset:1024
	ds_read_b128 v[174:177], v149 offset:2048
	ds_read_b128 v[178:181], v149 offset:3072
	ds_read_b128 v[182:185], v149 offset:4096
	ds_read_b128 v[186:189], v149 offset:5120
	ds_read_b128 v[190:193], v149 offset:6144
	ds_read_b128 v[194:197], v149 offset:7168
	global_load_lds_dwordx4 v[144:145], off
	v_lshl_add_u64 v[144:145], s[18:19], 0, v[138:139]
	s_add_i32 m0, s27, 0xe000
	s_nop 0
	global_load_lds_dwordx4 v[144:145], off
	s_waitcnt lgkmcnt(8)
	s_barrier
	s_waitcnt lgkmcnt(0)
	s_waitcnt lgkmcnt(0)
	v_mfma_f32_16x16x32_bf16 v[126:129], v[150:153], v[166:169], v[126:129]
	v_mfma_f32_16x16x32_bf16 v[122:125], v[158:161], v[166:169], v[122:125]
	v_mfma_f32_16x16x32_bf16 v[110:113], v[150:153], v[174:177], v[110:113]
	v_mfma_f32_16x16x32_bf16 v[106:109], v[158:161], v[174:177], v[106:109]
	v_mfma_f32_16x16x32_bf16 v[94:97], v[150:153], v[182:185], v[94:97]
	v_mfma_f32_16x16x32_bf16 v[90:93], v[158:161], v[182:185], v[90:93]
	v_mfma_f32_16x16x32_bf16 v[78:81], v[150:153], v[190:193], v[78:81]
	v_mfma_f32_16x16x32_bf16 v[74:77], v[158:161], v[190:193], v[74:77]
	v_mfma_f32_16x16x32_bf16 v[126:129], v[154:157], v[170:173], v[126:129]
	v_mfma_f32_16x16x32_bf16 v[122:125], v[162:165], v[170:173], v[122:125]
	v_mfma_f32_16x16x32_bf16 v[110:113], v[154:157], v[178:181], v[110:113]
	v_mfma_f32_16x16x32_bf16 v[106:109], v[162:165], v[178:181], v[106:109]
	v_mfma_f32_16x16x32_bf16 v[94:97], v[154:157], v[186:189], v[94:97]
	v_mfma_f32_16x16x32_bf16 v[90:93], v[162:165], v[186:189], v[90:93]
	v_mfma_f32_16x16x32_bf16 v[78:81], v[154:157], v[194:197], v[78:81]
	v_mfma_f32_16x16x32_bf16 v[74:77], v[162:165], v[194:197], v[74:77]
	s_barrier
	s_add_i32 s46, 0, 0x14000
	s_add_i32 s43, s43, s26
	v_add_u32_e32 v140, s46, v143
	v_lshl_add_u64 v[144:145], s[20:21], 0, v[0:1]
	s_mov_b32 m0, s43
	ds_read_b128 v[198:201], v140
	ds_read_b128 v[202:205], v140 offset:1024
	ds_read_b128 v[206:209], v140 offset:2048
	ds_read_b128 v[214:217], v140 offset:3072
	global_load_lds_dwordx4 v[144:145], off
	v_lshl_add_u64 v[218:219], s[20:21], 0, v[130:131]
	s_add_i32 m0, s43, 0x2000
	s_nop 0
	global_load_lds_dwordx4 v[218:219], off
	s_barrier
	s_waitcnt lgkmcnt(0)
	s_waitcnt lgkmcnt(0)
	v_mfma_f32_16x16x32_bf16 v[118:121], v[198:201], v[166:169], v[118:121]
	v_mfma_f32_16x16x32_bf16 v[114:117], v[206:209], v[166:169], v[114:117]
	v_mfma_f32_16x16x32_bf16 v[102:105], v[198:201], v[174:177], v[102:105]
	v_mfma_f32_16x16x32_bf16 v[98:101], v[206:209], v[174:177], v[98:101]
	v_mfma_f32_16x16x32_bf16 v[86:89], v[198:201], v[182:185], v[86:89]
	v_mfma_f32_16x16x32_bf16 v[82:85], v[206:209], v[182:185], v[82:85]
	v_mfma_f32_16x16x32_bf16 v[70:73], v[198:201], v[190:193], v[70:73]
	v_mfma_f32_16x16x32_bf16 v[66:69], v[206:209], v[190:193], v[66:69]
	v_mfma_f32_16x16x32_bf16 v[118:121], v[202:205], v[170:173], v[118:121]
	v_mfma_f32_16x16x32_bf16 v[114:117], v[214:217], v[170:173], v[114:117]
	v_mfma_f32_16x16x32_bf16 v[102:105], v[202:205], v[178:181], v[102:105]
	v_mfma_f32_16x16x32_bf16 v[98:101], v[214:217], v[178:181], v[98:101]
	v_mfma_f32_16x16x32_bf16 v[86:89], v[202:205], v[186:189], v[86:89]
	v_mfma_f32_16x16x32_bf16 v[82:85], v[214:217], v[186:189], v[82:85]
	v_mfma_f32_16x16x32_bf16 v[70:73], v[202:205], v[194:197], v[70:73]
	v_mfma_f32_16x16x32_bf16 v[66:69], v[214:217], v[194:197], v[66:69]
	s_mov_b32 m0, s27
	v_lshl_add_u64 v[220:221], s[22:23], 0, v[134:135]
	s_barrier
	ds_read_b128 v[166:169], v149 offset:16384
	ds_read_b128 v[170:173], v149 offset:17408
	ds_read_b128 v[174:177], v149 offset:18432
	ds_read_b128 v[178:181], v149 offset:19456
	ds_read_b128 v[182:185], v149 offset:20480
	ds_read_b128 v[186:189], v149 offset:21504
	ds_read_b128 v[190:193], v149 offset:22528
	ds_read_b128 v[194:197], v149 offset:23552
	global_load_lds_dwordx4 v[220:221], off
	v_lshl_add_u64 v[222:223], s[22:23], 0, v[132:133]
	s_mov_b32 m0, s28
	s_nop 0
	global_load_lds_dwordx4 v[222:223], off
	s_barrier
	s_waitcnt lgkmcnt(0)
	s_waitcnt lgkmcnt(0)
	v_mfma_f32_16x16x32_bf16 v[62:65], v[150:153], v[166:169], v[62:65]
	v_mfma_f32_16x16x32_bf16 v[58:61], v[158:161], v[166:169], v[58:61]
	v_mfma_f32_16x16x32_bf16 v[46:49], v[150:153], v[174:177], v[46:49]
	v_mfma_f32_16x16x32_bf16 v[42:45], v[158:161], v[174:177], v[42:45]
	v_mfma_f32_16x16x32_bf16 v[30:33], v[150:153], v[182:185], v[30:33]
	v_mfma_f32_16x16x32_bf16 v[26:29], v[158:161], v[182:185], v[26:29]
	v_mfma_f32_16x16x32_bf16 v[14:17], v[150:153], v[190:193], v[14:17]
	v_mfma_f32_16x16x32_bf16 v[10:13], v[158:161], v[190:193], v[10:13]
	v_mfma_f32_16x16x32_bf16 v[62:65], v[154:157], v[170:173], v[62:65]
	v_mfma_f32_16x16x32_bf16 v[58:61], v[162:165], v[170:173], v[58:61]
	v_mfma_f32_16x16x32_bf16 v[46:49], v[154:157], v[178:181], v[46:49]
	v_mfma_f32_16x16x32_bf16 v[42:45], v[162:165], v[178:181], v[42:45]
	v_mfma_f32_16x16x32_bf16 v[30:33], v[154:157], v[186:189], v[30:33]
	v_mfma_f32_16x16x32_bf16 v[26:29], v[162:165], v[186:189], v[26:29]
	v_mfma_f32_16x16x32_bf16 v[14:17], v[154:157], v[194:197], v[14:17]
	v_mfma_f32_16x16x32_bf16 v[10:13], v[162:165], v[194:197], v[10:13]
	s_barrier
; #define PG8_STAGE(bufoff, gbase, voff) do { _Pragma("unroll") for (int _i = 0; _i < 2; ++_i) \
;         __builtin_amdgcn_global_load_lds((const unsigned*)((const char*)(gbase) + (voff)[_i]), (LAS unsigned*)(lds + (bufoff) + ldsw + _i * 8192), 16, 0, 0); } while (0)
; #define PG8_LDA(dst, b, h) do { _Pragma("unroll") for (int m = 0; m < 4; ++m) _Pragma("unroll") for (int k = 0; k < 2; ++k) dst[m][k] = *(const LAS bf16x8*)(lds + PG8_SA(b, h) + aoff + m * 2048 + k * 1024); } while (0)
; #define PG8_LDB(dst, b, h) do { _Pragma("unroll") for (int n = 0; n < 2; ++n) _Pragma("unroll") for (int k = 0; k < 2; ++k) dst[n][k] = *(const LAS bf16x8*)(lds + PG8_SB(b, h) + boff + n * 2048 + k * 1024); } while (0)
; #define PG8_MMA(ai, bj, At, Bt) do { __builtin_amdgcn_s_setprio(1); _Pragma("unroll") for (int m = 0; m < 4; ++m) _Pragma("unroll") for (int n = 0; n < 2; ++n) _Pragma("unroll") for (int k = 0; k < 2; ++k) \
;         acc[ai][bj][m][n] = __builtin_amdgcn_mfma_f32_16x16x32_bf16(Bt[n][k], At[m][k], acc[ai][bj][m][n], 0, 0, 0); __builtin_amdgcn_s_setprio(0); } while (0)
; #define PG8_WAIT_V(n) asm volatile("s_waitcnt vmcnt(" #n ")" ::: "memory")
; #define PG8_WAIT_L(n) asm volatile("s_waitcnt lgkmcnt(" #n ")" ::: "memory")
; #define PG8_BAR __builtin_amdgcn_s_barrier()
; #define PG8_SCHED __builtin_amdgcn_sched_barrier(0)
; template <class Epi>
; __device__ __forceinline__ void gemm_phase(LAS unsigned char* lds, const Gemm g, const StaticOrder& S, const Epi& E) {
;     ...
;             PG8_STAGE(PG8_SB(0, 1), b2 + hstep, voffB);
;             PG8_WAIT_V(6); PG8_BAR; PG8_MMA(1, 1, At, B1); PG8_BAR;
;             PG8_LDB(B0, 1, 0); PG8_SCHED; PG8_LDA(At, 1, 0); PG8_STAGE(PG8_SA(0, 1), a2 + hstep, voffA);
;             PG8_WAIT_L(8); PG8_BAR; PG8_WAIT_L(0); PG8_MMA(0, 0, At, B0); PG8_BAR; PG8_SCHED;
;             PG8_LDB(B1, 1, 1); PG8_STAGE(PG8_SB(1, 0), b3, voffB);
;             PG8_BAR; PG8_WAIT_L(0); PG8_MMA(0, 1, At, B1); PG8_BAR;
;             PG8_LDA(At, 1, 1); PG8_STAGE(PG8_SA(1, 0), a3, voffA);
;             PG8_BAR; PG8_WAIT_L(0); PG8_MMA(1, 0, At, B0); PG8_BAR; PG8_SCHED;
	s_add_u32 s44, s20, 0x80000
	s_addc_u32 s45, s21, 0
	s_add_i32 s43, s46, s26
	v_lshl_add_u64 v[150:151], s[44:45], 0, v[0:1]
	s_mov_b32 m0, s43
	s_nop 0
	global_load_lds_dwordx4 v[150:151], off
	v_lshl_add_u64 v[150:151], s[44:45], 0, v[130:131]
	s_add_i32 m0, s43, 0x2000
	s_nop 0
	global_load_lds_dwordx4 v[150:151], off
	s_waitcnt vmcnt(6)
	s_barrier
	v_mfma_f32_16x16x32_bf16 v[54:57], v[198:201], v[166:169], v[54:57]
	v_mfma_f32_16x16x32_bf16 v[50:53], v[206:209], v[166:169], v[50:53]
	v_mfma_f32_16x16x32_bf16 v[38:41], v[198:201], v[174:177], v[38:41]
	v_mfma_f32_16x16x32_bf16 v[34:37], v[206:209], v[174:177], v[34:37]
	v_mfma_f32_16x16x32_bf16 v[22:25], v[198:201], v[182:185], v[22:25]
	v_mfma_f32_16x16x32_bf16 v[18:21], v[206:209], v[182:185], v[18:21]
	v_mfma_f32_16x16x32_bf16 v[6:9], v[198:201], v[190:193], v[6:9]
	v_mfma_f32_16x16x32_bf16 v[2:5], v[206:209], v[190:193], v[2:5]
	v_mfma_f32_16x16x32_bf16 v[54:57], v[202:205], v[170:173], v[54:57]
	v_mfma_f32_16x16x32_bf16 v[50:53], v[214:217], v[170:173], v[50:53]
	v_mfma_f32_16x16x32_bf16 v[38:41], v[202:205], v[178:181], v[38:41]
	v_mfma_f32_16x16x32_bf16 v[34:37], v[214:217], v[178:181], v[34:37]
	v_mfma_f32_16x16x32_bf16 v[22:25], v[202:205], v[186:189], v[22:25]
	v_mfma_f32_16x16x32_bf16 v[18:21], v[214:217], v[186:189], v[18:21]
	v_mfma_f32_16x16x32_bf16 v[6:9], v[202:205], v[194:197], v[6:9]
	v_mfma_f32_16x16x32_bf16 v[2:5], v[214:217], v[194:197], v[2:5]
	s_add_i32 s43, 0, 0x18000
	v_add_u32_e32 v140, s43, v143
	s_barrier
	ds_read_b128 v[150:153], v140
	ds_read_b128 v[154:157], v140 offset:1024
	ds_read_b128 v[158:161], v140 offset:2048
	ds_read_b128 v[162:165], v140 offset:3072
	s_add_u32 s22, s22, 0x80000
	s_addc_u32 s23, s23, 0
	s_mov_b32 m0, s29
	v_lshl_add_u64 v[198:199], s[22:23], 0, v[134:135]
	ds_read_b128 v[166:169], v149 offset:32768
	ds_read_b128 v[170:173], v149 offset:33792
	ds_read_b128 v[174:177], v149 offset:34816
	ds_read_b128 v[178:181], v149 offset:35840
	ds_read_b128 v[182:185], v149 offset:36864
	ds_read_b128 v[186:189], v149 offset:37888
	ds_read_b128 v[190:193], v149 offset:38912
	ds_read_b128 v[194:197], v149 offset:39936
	global_load_lds_dwordx4 v[198:199], off
	v_lshl_add_u64 v[198:199], s[22:23], 0, v[132:133]
	s_mov_b32 m0, s30
	s_nop 0
	global_load_lds_dwordx4 v[198:199], off
	s_waitcnt lgkmcnt(8)
	s_barrier
	s_waitcnt lgkmcnt(0)
	s_waitcnt lgkmcnt(0)
	v_mfma_f32_16x16x32_bf16 v[126:129], v[150:153], v[166:169], v[126:129]
	v_mfma_f32_16x16x32_bf16 v[122:125], v[158:161], v[166:169], v[122:125]
	v_mfma_f32_16x16x32_bf16 v[110:113], v[150:153], v[174:177], v[110:113]
	v_mfma_f32_16x16x32_bf16 v[106:109], v[158:161], v[174:177], v[106:109]
	v_mfma_f32_16x16x32_bf16 v[94:97], v[150:153], v[182:185], v[94:97]
	v_mfma_f32_16x16x32_bf16 v[90:93], v[158:161], v[182:185], v[90:93]
	v_mfma_f32_16x16x32_bf16 v[78:81], v[150:153], v[190:193], v[78:81]
	v_mfma_f32_16x16x32_bf16 v[74:77], v[158:161], v[190:193], v[74:77]
	v_mfma_f32_16x16x32_bf16 v[126:129], v[154:157], v[170:173], v[126:129]
	v_mfma_f32_16x16x32_bf16 v[122:125], v[162:165], v[170:173], v[122:125]
	v_mfma_f32_16x16x32_bf16 v[110:113], v[154:157], v[178:181], v[110:113]
	v_mfma_f32_16x16x32_bf16 v[106:109], v[162:165], v[178:181], v[106:109]
	v_mfma_f32_16x16x32_bf16 v[94:97], v[154:157], v[186:189], v[94:97]
	v_mfma_f32_16x16x32_bf16 v[90:93], v[162:165], v[186:189], v[90:93]
	v_mfma_f32_16x16x32_bf16 v[78:81], v[154:157], v[194:197], v[78:81]
	v_mfma_f32_16x16x32_bf16 v[74:77], v[162:165], v[194:197], v[74:77]
	s_barrier
	s_add_i32 s22, 0, 0x1c000
	s_add_i32 s23, s43, s26
	v_add_u32_e32 v140, s22, v143
	v_lshl_add_u64 v[144:145], v[144:145], 0, s[66:67]
	s_mov_b32 m0, s23
	ds_read_b128 v[198:201], v140
	ds_read_b128 v[202:205], v140 offset:1024
	ds_read_b128 v[206:209], v140 offset:2048
	ds_read_b128 v[214:217], v140 offset:3072
	global_load_lds_dwordx4 v[144:145], off
	v_lshl_add_u64 v[144:145], v[218:219], 0, s[66:67]
	s_add_i32 m0, s23, 0x2000
	s_nop 0
	global_load_lds_dwordx4 v[144:145], off
	s_barrier
	s_waitcnt lgkmcnt(0)
	s_waitcnt lgkmcnt(0)
	v_mfma_f32_16x16x32_bf16 v[118:121], v[198:201], v[166:169], v[118:121]
	v_mfma_f32_16x16x32_bf16 v[114:117], v[206:209], v[166:169], v[114:117]
	v_mfma_f32_16x16x32_bf16 v[102:105], v[198:201], v[174:177], v[102:105]
	v_mfma_f32_16x16x32_bf16 v[98:101], v[206:209], v[174:177], v[98:101]
	v_mfma_f32_16x16x32_bf16 v[86:89], v[198:201], v[182:185], v[86:89]
	v_mfma_f32_16x16x32_bf16 v[82:85], v[206:209], v[182:185], v[82:85]
	v_mfma_f32_16x16x32_bf16 v[70:73], v[198:201], v[190:193], v[70:73]
	v_mfma_f32_16x16x32_bf16 v[66:69], v[206:209], v[190:193], v[66:69]
	v_mfma_f32_16x16x32_bf16 v[118:121], v[202:205], v[170:173], v[118:121]
	v_mfma_f32_16x16x32_bf16 v[114:117], v[214:217], v[170:173], v[114:117]
	v_mfma_f32_16x16x32_bf16 v[102:105], v[202:205], v[178:181], v[102:105]
	v_mfma_f32_16x16x32_bf16 v[98:101], v[214:217], v[178:181], v[98:101]
	v_mfma_f32_16x16x32_bf16 v[86:89], v[202:205], v[186:189], v[86:89]
	v_mfma_f32_16x16x32_bf16 v[82:85], v[214:217], v[186:189], v[82:85]
	v_mfma_f32_16x16x32_bf16 v[70:73], v[202:205], v[194:197], v[70:73]
	v_mfma_f32_16x16x32_bf16 v[66:69], v[214:217], v[194:197], v[66:69]
	s_mov_b32 m0, s31
	v_lshl_add_u64 v[144:145], v[220:221], 0, s[66:67]
	s_barrier
	ds_read_b128 v[166:169], v149 offset:49152
	ds_read_b128 v[170:173], v149 offset:50176
	ds_read_b128 v[174:177], v149 offset:51200
	ds_read_b128 v[178:181], v149 offset:52224
	ds_read_b128 v[182:185], v149 offset:53248
	ds_read_b128 v[186:189], v149 offset:54272
	ds_read_b128 v[190:193], v149 offset:55296
	ds_read_b128 v[194:197], v149 offset:56320
	global_load_lds_dwordx4 v[144:145], off
	v_lshl_add_u64 v[144:145], v[222:223], 0, s[66:67]
	s_mov_b32 m0, s34
	s_nop 0
	global_load_lds_dwordx4 v[144:145], off
	s_barrier
; __device__ __forceinline__ float silu_f(float x) { return x * __builtin_amdgcn_rcpf(1.f + __expf(-x)); }
; #define PG8_STAGE(bufoff, gbase, voff) do { _Pragma("unroll") for (int _i = 0; _i < 2; ++_i) \
;         __builtin_amdgcn_global_load_lds((const unsigned*)((const char*)(gbase) + (voff)[_i]), (LAS unsigned*)(lds + (bufoff) + ldsw + _i * 8192), 16, 0, 0); } while (0)
; #define PG8_MMA(ai, bj, At, Bt) do { __builtin_amdgcn_s_setprio(1); _Pragma("unroll") for (int m = 0; m < 4; ++m) _Pragma("unroll") for (int n = 0; n < 2; ++n) _Pragma("unroll") for (int k = 0; k < 2; ++k) \
;         acc[ai][bj][m][n] = __builtin_amdgcn_mfma_f32_16x16x32_bf16(Bt[n][k], At[m][k], acc[ai][bj][m][n], 0, 0, 0); __builtin_amdgcn_s_setprio(0); } while (0)
; #define PG8_WAIT_V(n) asm volatile("s_waitcnt vmcnt(" #n ")" ::: "memory")
; #define PG8_WAIT_L(n) asm volatile("s_waitcnt lgkmcnt(" #n ")" ::: "memory")
; #define PG8_BAR __builtin_amdgcn_s_barrier()
; #define PG8_SCHED __builtin_amdgcn_sched_barrier(0)
; template <class Epi>
; __device__ __forceinline__ void gemm_phase(LAS unsigned char* lds, const Gemm g, const StaticOrder& S, const Epi& E) {
;     ...
;             PG8_BAR; PG8_WAIT_L(0); PG8_MMA(1, 0, At, B0); PG8_BAR; PG8_SCHED;
;             PG8_STAGE(PG8_SB(1, 1), b3 + hstep, voffB);
;             PG8_WAIT_V(6); PG8_BAR; PG8_MMA(1, 1, At, B1); PG8_BAR;
;     __device__ __forceinline__ void operator()(const f32x4 (&acc)[2][2][4][2], const Unit& u, int wr, int wc, int fr, int fq) const {
;     ...
;         float rsv[2][4];
; #pragma unroll
;         for (int ai = 0; ai < 2; ++ai)
; #pragma unroll
;             for (int m = 0; m < 4; ++m) rsv[ai][m] = rstd[row0 + ai * HALF + m * 16];
; #pragma unroll
;         for (int ai = 0; ai < 2; ++ai)
; #pragma unroll
;             for (int m = 0; m < 4; ++m) { bf16_t* rowp = H + (size_t)(row0 + ai * HALF + m * 16) * DFF + col0;
;                 const float rs = rsv[ai][m];
;                 f32x4 h0, h1;
; #pragma unroll
;                 for (int j = 0; j < 4; ++j) { h0[j] = silu_f(acc[ai][0][m][0][j] * rs) * (acc[ai][1][m][0][j] * rs); h1[j] = silu_f(acc[ai][0][m][1][j] * rs) * (acc[ai][1][m][1][j] * rs); }
	s_waitcnt lgkmcnt(0)
	s_waitcnt lgkmcnt(0)
	v_mfma_f32_16x16x32_bf16 v[62:65], v[150:153], v[166:169], v[62:65]
	v_mfma_f32_16x16x32_bf16 v[58:61], v[158:161], v[166:169], v[58:61]
	v_mfma_f32_16x16x32_bf16 v[46:49], v[150:153], v[174:177], v[46:49]
	v_mfma_f32_16x16x32_bf16 v[42:45], v[158:161], v[174:177], v[42:45]
	v_mfma_f32_16x16x32_bf16 v[30:33], v[150:153], v[182:185], v[30:33]
	v_mfma_f32_16x16x32_bf16 v[26:29], v[158:161], v[182:185], v[26:29]
	v_mfma_f32_16x16x32_bf16 v[14:17], v[150:153], v[190:193], v[14:17]
	v_mfma_f32_16x16x32_bf16 v[10:13], v[158:161], v[190:193], v[10:13]
	v_mfma_f32_16x16x32_bf16 v[62:65], v[154:157], v[170:173], v[62:65]
	v_mfma_f32_16x16x32_bf16 v[58:61], v[162:165], v[170:173], v[58:61]
	v_mfma_f32_16x16x32_bf16 v[46:49], v[154:157], v[178:181], v[46:49]
	v_mfma_f32_16x16x32_bf16 v[42:45], v[162:165], v[178:181], v[42:45]
	v_mfma_f32_16x16x32_bf16 v[30:33], v[154:157], v[186:189], v[30:33]
	v_mfma_f32_16x16x32_bf16 v[26:29], v[162:165], v[186:189], v[26:29]
	v_mfma_f32_16x16x32_bf16 v[14:17], v[154:157], v[194:197], v[14:17]
	v_mfma_f32_16x16x32_bf16 v[10:13], v[162:165], v[194:197], v[10:13]
	s_barrier
	s_add_u32 s20, s20, 0x80080
	s_addc_u32 s21, s21, 0
	s_add_i32 s22, s22, s26
	v_lshl_add_u64 v[144:145], s[20:21], 0, v[0:1]
	s_mov_b32 m0, s22
	s_nop 0
	global_load_lds_dwordx4 v[144:145], off
	v_lshl_add_u64 v[144:145], s[20:21], 0, v[130:131]
	s_add_i32 m0, s22, 0x2000
	s_nop 0
	global_load_lds_dwordx4 v[144:145], off
	s_waitcnt vmcnt(6)
	s_barrier
	v_mfma_f32_16x16x32_bf16 v[54:57], v[198:201], v[166:169], v[54:57]
	v_mfma_f32_16x16x32_bf16 v[50:53], v[206:209], v[166:169], v[50:53]
	v_mfma_f32_16x16x32_bf16 v[38:41], v[198:201], v[174:177], v[38:41]
	v_mfma_f32_16x16x32_bf16 v[34:37], v[206:209], v[174:177], v[34:37]
	v_mfma_f32_16x16x32_bf16 v[22:25], v[198:201], v[182:185], v[22:25]
	v_mfma_f32_16x16x32_bf16 v[18:21], v[206:209], v[182:185], v[18:21]
	v_mfma_f32_16x16x32_bf16 v[6:9], v[198:201], v[190:193], v[6:9]
	v_mfma_f32_16x16x32_bf16 v[2:5], v[206:209], v[190:193], v[2:5]
	v_mfma_f32_16x16x32_bf16 v[54:57], v[202:205], v[170:173], v[54:57]
	v_mfma_f32_16x16x32_bf16 v[50:53], v[214:217], v[170:173], v[50:53]
	v_mfma_f32_16x16x32_bf16 v[38:41], v[202:205], v[178:181], v[38:41]
	v_mfma_f32_16x16x32_bf16 v[34:37], v[214:217], v[178:181], v[34:37]
	v_mfma_f32_16x16x32_bf16 v[22:25], v[202:205], v[186:189], v[22:25]
	v_mfma_f32_16x16x32_bf16 v[18:21], v[214:217], v[186:189], v[18:21]
	v_mfma_f32_16x16x32_bf16 v[6:9], v[202:205], v[194:197], v[6:9]
	v_mfma_f32_16x16x32_bf16 v[2:5], v[214:217], v[194:197], v[2:5]
	s_add_i32 s42, s42, 2
	s_add_u32 s18, s18, 0x100
	s_addc_u32 s19, s19, 0
	s_add_u32 s40, s40, 0x100
	s_addc_u32 s41, s41, 0
	s_cmp_gt_u32 s42, 29
	s_barrier
	s_cbranch_scc0 .LBB0_917
	v_lshl_add_u32 v164, s37, 8, v141
	v_ashrrev_i32_e32 v165, 31, v164
	v_lshl_add_u64 v[144:145], v[164:165], 2, s[82:83]
	global_load_dword v166, v[144:145], off
	global_load_dword v148, v[144:145], off offset:512
	global_load_dword v146, v[144:145], off offset:576
	global_load_dword v142, v[144:145], off offset:640
	global_load_dword v140, v[144:145], off offset:704
	v_or_b32_e32 v160, 16, v164
	v_ashrrev_i32_e32 v161, 31, v160
	v_lshl_add_u64 v[150:151], v[160:161], 2, s[82:83]
	global_load_dword v158, v[150:151], off
	v_or_b32_e32 v156, 32, v164
	v_ashrrev_i32_e32 v157, 31, v156
	v_lshl_add_u64 v[150:151], v[156:157], 2, s[82:83]
	global_load_dword v154, v[150:151], off
	v_or_b32_e32 v152, 48, v164
	v_ashrrev_i32_e32 v153, 31, v152
	v_lshl_or_b32 v162, s36, 7, v147
	v_lshl_add_u64 v[150:151], v[152:153], 2, s[82:83]
	v_ashrrev_i32_e32 v163, 31, v162
	v_mov_b64_e32 v[144:145], s[96:97]
	global_load_dword v150, v[150:151], off
	v_add_u32_e32 v157, 0x80, v164
	v_add_u32_e32 v155, 0x90, v164
	v_add_u32_e32 v153, 0xa0, v164
	v_add_u32_e32 v151, 0xb0, v164
	v_mad_i64_i32 v[164:165], s[18:19], v164, s3, v[144:145]
	s_and_b64 vcc, exec, s[6:7]
	s_mov_b32 s36, s0
	s_mov_b32 s37, s8
	s_mov_b64 s[20:21], s[16:17]
	s_waitcnt vmcnt(0)
	v_pk_mul_f32 v[126:127], v[126:127], v[166:167] op_sel_hi:[1,0]
	s_nop 0
	v_mul_f32_e32 v159, 0xbfb8aa3b, v126
	v_exp_f32_e32 v159, v159
	v_pk_mul_f32 v[118:119], v[118:119], v[166:167] op_sel_hi:[1,0]
	v_pk_mul_f32 v[122:123], v[122:123], v[166:167] op_sel_hi:[1,0]
	v_pk_mul_f32 v[114:115], v[114:115], v[166:167] op_sel_hi:[1,0]
	v_add_f32_e32 v159, 1.0, v159
	v_rcp_f32_e32 v168, v159
	v_mul_f32_e32 v159, 0xbfb8aa3b, v127
	v_exp_f32_e32 v159, v159
	v_pk_mul_f32 v[120:121], v[120:121], v[166:167] op_sel_hi:[1,0]
	v_pk_mul_f32 v[116:117], v[116:117], v[166:167] op_sel_hi:[1,0]
	v_pk_mul_f32 v[94:95], v[94:95], v[154:155] op_sel_hi:[1,0]
	v_add_f32_e32 v159, 1.0, v159
	v_rcp_f32_e32 v169, v159
	v_pk_mul_f32 v[110:111], v[110:111], v[158:159] op_sel_hi:[1,0]
	v_pk_mul_f32 v[102:103], v[102:103], v[158:159] op_sel_hi:[1,0]
	v_pk_mul_f32 v[106:107], v[106:107], v[158:159] op_sel_hi:[1,0]
	v_pk_mul_f32 v[126:127], v[126:127], v[168:169]
	v_pk_mul_f32 v[98:99], v[98:99], v[158:159] op_sel_hi:[1,0]
	v_pk_mul_f32 v[118:119], v[118:119], v[126:127]
	v_mul_f32_e32 v126, 0xbfb8aa3b, v122
	v_mul_f32_e32 v127, 0xbfb8aa3b, v123
	v_exp_f32_e32 v126, v126
	v_exp_f32_e32 v127, v127
	v_pk_mul_f32 v[104:105], v[104:105], v[158:159] op_sel_hi:[1,0]
	v_pk_mul_f32 v[100:101], v[100:101], v[158:159] op_sel_hi:[1,0]
	v_add_f32_e32 v126, 1.0, v126
	v_add_f32_e32 v127, 1.0, v127
	v_rcp_f32_e32 v126, v126
	v_rcp_f32_e32 v127, v127
	v_pk_mul_f32 v[86:87], v[86:87], v[154:155] op_sel_hi:[1,0]
	v_pk_mul_f32 v[90:91], v[90:91], v[154:155] op_sel_hi:[1,0]
	v_pk_mul_f32 v[82:83], v[82:83], v[154:155] op_sel_hi:[1,0]
; __device__ __forceinline__ unsigned cvt_pk_bf16(float lo, float hi) { const f32v2_t v = {lo, hi}; const bf16v2_t b = __builtin_convertvector(v, bf16v2_t); return __builtin_bit_cast(unsigned, b); }
; __device__ __forceinline__ float silu_f(float x) { return x * __builtin_amdgcn_rcpf(1.f + __expf(-x)); }
;     __device__ __forceinline__ void operator()(const f32x4 (&acc)[2][2][4][2], const Unit& u, int wr, int wc, int fr, int fq) const {
;     ...
;         for (int ai = 0; ai < 2; ++ai)
; #pragma unroll
;             for (int m = 0; m < 4; ++m) { bf16_t* rowp = H + (size_t)(row0 + ai * HALF + m * 16) * DFF + col0;
;                 const float rs = rsv[ai][m];
;                 f32x4 h0, h1;
; #pragma unroll
;                 for (int j = 0; j < 4; ++j) { h0[j] = silu_f(acc[ai][0][m][0][j] * rs) * (acc[ai][1][m][0][j] * rs); h1[j] = silu_f(acc[ai][0][m][1][j] * rs) * (acc[ai][1][m][1][j] * rs); }
;                 u32x4 w; w.x = cvt_pk_bf16(h0[0], h0[1]); w.y = cvt_pk_bf16(h0[2], h0[3]); w.z = cvt_pk_bf16(h1[0], h1[1]); w.w = cvt_pk_bf16(h1[2], h1[3]);
;                 *(u32x4*)rowp = w; }
	v_pk_mul_f32 v[122:123], v[122:123], v[126:127]
	v_pk_mul_f32 v[88:89], v[88:89], v[154:155] op_sel_hi:[1,0]
	v_pk_mul_f32 v[122:123], v[114:115], v[122:123]
	v_pk_mul_f32 v[114:115], v[128:129], v[166:167] op_sel_hi:[1,0]
	v_pk_mul_f32 v[84:85], v[84:85], v[154:155] op_sel_hi:[1,0]
	v_mul_f32_e32 v126, 0xbfb8aa3b, v114
	v_mul_f32_e32 v127, 0xbfb8aa3b, v115
	v_exp_f32_e32 v126, v126
	v_exp_f32_e32 v127, v127
	v_pk_mul_f32 v[78:79], v[78:79], v[150:151] op_sel_hi:[1,0]
	v_pk_mul_f32 v[70:71], v[70:71], v[150:151] op_sel_hi:[1,0]
	v_add_f32_e32 v126, 1.0, v126
	v_add_f32_e32 v127, 1.0, v127
	v_rcp_f32_e32 v126, v126
	v_rcp_f32_e32 v127, v127
	v_pk_mul_f32 v[74:75], v[74:75], v[150:151] op_sel_hi:[1,0]
	v_pk_mul_f32 v[66:67], v[66:67], v[150:151] op_sel_hi:[1,0]
	v_pk_mul_f32 v[72:73], v[72:73], v[150:151] op_sel_hi:[1,0]
	v_pk_mul_f32 v[114:115], v[114:115], v[126:127]
	v_pk_mul_f32 v[68:69], v[68:69], v[150:151] op_sel_hi:[1,0]
	v_pk_mul_f32 v[120:121], v[120:121], v[114:115]
	v_pk_mul_f32 v[114:115], v[124:125], v[166:167] op_sel_hi:[1,0]
	v_pk_mul_f32 v[62:63], v[62:63], v[148:149] op_sel_hi:[1,0]
	v_mul_f32_e32 v124, 0xbfb8aa3b, v114
	v_mul_f32_e32 v125, 0xbfb8aa3b, v115
	v_exp_f32_e32 v124, v124
	v_exp_f32_e32 v125, v125
	v_pk_mul_f32 v[54:55], v[54:55], v[148:149] op_sel_hi:[1,0]
	v_pk_mul_f32 v[58:59], v[58:59], v[148:149] op_sel_hi:[1,0]
	v_add_f32_e32 v124, 1.0, v124
	v_add_f32_e32 v125, 1.0, v125
	v_rcp_f32_e32 v124, v124
	v_rcp_f32_e32 v125, v125
	v_pk_mul_f32 v[50:51], v[50:51], v[148:149] op_sel_hi:[1,0]
	v_pk_mul_f32 v[56:57], v[56:57], v[148:149] op_sel_hi:[1,0]
	v_pk_mul_f32 v[52:53], v[52:53], v[148:149] op_sel_hi:[1,0]
	v_pk_mul_f32 v[114:115], v[114:115], v[124:125]
	v_pk_mul_f32 v[46:47], v[46:47], v[146:147] op_sel_hi:[1,0]
	v_pk_mul_f32 v[124:125], v[116:117], v[114:115]
	v_lshlrev_b64 v[114:115], 1, v[162:163]
	v_lshl_add_u64 v[126:127], v[164:165], 0, v[114:115]
	v_cvt_pk_bf16_f32 v116, v118, v119
	v_cvt_pk_bf16_f32 v117, v120, v121
	v_cvt_pk_bf16_f32 v118, v122, v123
	v_cvt_pk_bf16_f32 v119, v124, v125
	global_store_dwordx4 v[126:127], v[116:119], off
	v_pk_mul_f32 v[38:39], v[38:39], v[146:147] op_sel_hi:[1,0]
	v_pk_mul_f32 v[42:43], v[42:43], v[146:147] op_sel_hi:[1,0]
	v_mul_f32_e32 v118, 0xbfb8aa3b, v110
	v_mul_f32_e32 v119, 0xbfb8aa3b, v111
	v_exp_f32_e32 v118, v118
	v_exp_f32_e32 v119, v119
	v_mad_i64_i32 v[116:117], s[18:19], v160, s3, v[144:145]
	v_add_f32_e32 v118, 1.0, v118
	v_add_f32_e32 v119, 1.0, v119
	v_rcp_f32_e32 v118, v118
	v_rcp_f32_e32 v119, v119
	v_pk_mul_f32 v[34:35], v[34:35], v[146:147] op_sel_hi:[1,0]
	v_pk_mul_f32 v[40:41], v[40:41], v[146:147] op_sel_hi:[1,0]
	v_pk_mul_f32 v[36:37], v[36:37], v[146:147] op_sel_hi:[1,0]
	v_pk_mul_f32 v[110:111], v[110:111], v[118:119]
	v_pk_mul_f32 v[30:31], v[30:31], v[142:143] op_sel_hi:[1,0]
	v_pk_mul_f32 v[102:103], v[102:103], v[110:111]
	v_mul_f32_e32 v110, 0xbfb8aa3b, v106
	v_mul_f32_e32 v111, 0xbfb8aa3b, v107
	v_exp_f32_e32 v110, v110
	v_exp_f32_e32 v111, v111
	v_pk_mul_f32 v[22:23], v[22:23], v[142:143] op_sel_hi:[1,0]
	v_pk_mul_f32 v[26:27], v[26:27], v[142:143] op_sel_hi:[1,0]
	v_add_f32_e32 v110, 1.0, v110
	v_add_f32_e32 v111, 1.0, v111
	v_rcp_f32_e32 v110, v110
	v_rcp_f32_e32 v111, v111
	v_pk_mul_f32 v[18:19], v[18:19], v[142:143] op_sel_hi:[1,0]
	v_pk_mul_f32 v[24:25], v[24:25], v[142:143] op_sel_hi:[1,0]
	v_pk_mul_f32 v[20:21], v[20:21], v[142:143] op_sel_hi:[1,0]
	v_pk_mul_f32 v[106:107], v[106:107], v[110:111]
	v_pk_mul_f32 v[14:15], v[14:15], v[140:141] op_sel_hi:[1,0]
	v_pk_mul_f32 v[106:107], v[98:99], v[106:107]
	v_pk_mul_f32 v[98:99], v[112:113], v[158:159] op_sel_hi:[1,0]
	v_pk_mul_f32 v[6:7], v[6:7], v[140:141] op_sel_hi:[1,0]
	v_mul_f32_e32 v110, 0xbfb8aa3b, v98
	v_mul_f32_e32 v111, 0xbfb8aa3b, v99
	v_exp_f32_e32 v110, v110
	v_exp_f32_e32 v111, v111
	v_pk_mul_f32 v[10:11], v[10:11], v[140:141] op_sel_hi:[1,0]
	v_pk_mul_f32 v[2:3], v[2:3], v[140:141] op_sel_hi:[1,0]
	v_add_f32_e32 v110, 1.0, v110
	v_add_f32_e32 v111, 1.0, v111
	v_rcp_f32_e32 v110, v110
	v_rcp_f32_e32 v111, v111
	v_pk_mul_f32 v[8:9], v[8:9], v[140:141] op_sel_hi:[1,0]
	v_pk_mul_f32 v[4:5], v[4:5], v[140:141] op_sel_hi:[1,0]
	v_pk_mul_f32 v[98:99], v[98:99], v[110:111]
	s_nop 0
	v_pk_mul_f32 v[104:105], v[104:105], v[98:99]
	v_pk_mul_f32 v[98:99], v[108:109], v[158:159] op_sel_hi:[1,0]
	v_lshl_add_u64 v[110:111], v[116:117], 0, v[114:115]
	v_mul_f32_e32 v108, 0xbfb8aa3b, v98
	v_mul_f32_e32 v109, 0xbfb8aa3b, v99
	v_exp_f32_e32 v108, v108
	v_exp_f32_e32 v109, v109
	v_add_f32_e32 v108, 1.0, v108
	v_add_f32_e32 v109, 1.0, v109
	v_rcp_f32_e32 v108, v108
	v_rcp_f32_e32 v109, v109
	s_nop 0
	v_pk_mul_f32 v[98:99], v[98:99], v[108:109]
	s_nop 0
	v_pk_mul_f32 v[108:109], v[100:101], v[98:99]
	v_cvt_pk_bf16_f32 v98, v102, v103
	v_cvt_pk_bf16_f32 v99, v104, v105
	v_cvt_pk_bf16_f32 v100, v106, v107
	v_cvt_pk_bf16_f32 v101, v108, v109
	global_store_dwordx4 v[110:111], v[98:101], off
	s_nop 1
	v_mul_f32_e32 v100, 0xbfb8aa3b, v94
	v_mul_f32_e32 v101, 0xbfb8aa3b, v95
	v_exp_f32_e32 v100, v100
	v_exp_f32_e32 v101, v101
	v_mad_i64_i32 v[98:99], s[18:19], v156, s3, v[144:145]
	v_add_f32_e32 v100, 1.0, v100
	v_add_f32_e32 v101, 1.0, v101
	v_rcp_f32_e32 v100, v100
	v_rcp_f32_e32 v101, v101
	s_nop 0
	v_pk_mul_f32 v[94:95], v[94:95], v[100:101]
	s_nop 0
	v_pk_mul_f32 v[86:87], v[86:87], v[94:95]
	v_mul_f32_e32 v94, 0xbfb8aa3b, v90
	v_mul_f32_e32 v95, 0xbfb8aa3b, v91
	v_exp_f32_e32 v94, v94
	v_exp_f32_e32 v95, v95
	v_add_f32_e32 v94, 1.0, v94
	v_add_f32_e32 v95, 1.0, v95
	v_rcp_f32_e32 v94, v94
	v_rcp_f32_e32 v95, v95
	s_nop 0
	v_pk_mul_f32 v[90:91], v[90:91], v[94:95]
	s_nop 0
; __device__ __forceinline__ unsigned cvt_pk_bf16(float lo, float hi) { const f32v2_t v = {lo, hi}; const bf16v2_t b = __builtin_convertvector(v, bf16v2_t); return __builtin_bit_cast(unsigned, b); }
; __device__ __forceinline__ float silu_f(float x) { return x * __builtin_amdgcn_rcpf(1.f + __expf(-x)); }
;     __device__ __forceinline__ void operator()(const f32x4 (&acc)[2][2][4][2], const Unit& u, int wr, int wc, int fr, int fq) const {
;     ...
;         for (int ai = 0; ai < 2; ++ai)
; #pragma unroll
;             for (int m = 0; m < 4; ++m) { bf16_t* rowp = H + (size_t)(row0 + ai * HALF + m * 16) * DFF + col0;
;                 const float rs = rsv[ai][m];
;                 f32x4 h0, h1;
; #pragma unroll
;                 for (int j = 0; j < 4; ++j) { h0[j] = silu_f(acc[ai][0][m][0][j] * rs) * (acc[ai][1][m][0][j] * rs); h1[j] = silu_f(acc[ai][0][m][1][j] * rs) * (acc[ai][1][m][1][j] * rs); }
;                 u32x4 w; w.x = cvt_pk_bf16(h0[0], h0[1]); w.y = cvt_pk_bf16(h0[2], h0[3]); w.z = cvt_pk_bf16(h1[0], h1[1]); w.w = cvt_pk_bf16(h1[2], h1[3]);
;                 *(u32x4*)rowp = w; }
	v_pk_mul_f32 v[90:91], v[82:83], v[90:91]
	v_pk_mul_f32 v[82:83], v[96:97], v[154:155] op_sel_hi:[1,0]
	s_nop 0
	v_mul_f32_e32 v94, 0xbfb8aa3b, v82
	v_mul_f32_e32 v95, 0xbfb8aa3b, v83
	v_exp_f32_e32 v94, v94
	v_exp_f32_e32 v95, v95
	v_add_f32_e32 v94, 1.0, v94
	v_add_f32_e32 v95, 1.0, v95
	v_rcp_f32_e32 v94, v94
	v_rcp_f32_e32 v95, v95
	s_nop 0
	v_pk_mul_f32 v[82:83], v[82:83], v[94:95]
	s_nop 0
	v_pk_mul_f32 v[88:89], v[88:89], v[82:83]
	v_pk_mul_f32 v[82:83], v[92:93], v[154:155] op_sel_hi:[1,0]
	v_lshl_add_u64 v[94:95], v[98:99], 0, v[114:115]
	v_mul_f32_e32 v92, 0xbfb8aa3b, v82
	v_mul_f32_e32 v93, 0xbfb8aa3b, v83
	v_exp_f32_e32 v92, v92
	v_exp_f32_e32 v93, v93
	v_add_f32_e32 v92, 1.0, v92
	v_add_f32_e32 v93, 1.0, v93
	v_rcp_f32_e32 v92, v92
	v_rcp_f32_e32 v93, v93
	s_nop 0
	v_pk_mul_f32 v[82:83], v[82:83], v[92:93]
	s_nop 0
	v_pk_mul_f32 v[92:93], v[84:85], v[82:83]
	v_cvt_pk_bf16_f32 v82, v86, v87
	v_cvt_pk_bf16_f32 v83, v88, v89
	v_cvt_pk_bf16_f32 v84, v90, v91
	v_cvt_pk_bf16_f32 v85, v92, v93
	global_store_dwordx4 v[94:95], v[82:85], off
	s_nop 1
	v_mul_f32_e32 v84, 0xbfb8aa3b, v78
	v_mul_f32_e32 v85, 0xbfb8aa3b, v79
	v_exp_f32_e32 v84, v84
	v_exp_f32_e32 v85, v85
	v_mad_i64_i32 v[82:83], s[18:19], v152, s3, v[144:145]
	v_add_f32_e32 v84, 1.0, v84
	v_add_f32_e32 v85, 1.0, v85
	v_rcp_f32_e32 v84, v84
	v_rcp_f32_e32 v85, v85
	s_nop 0
	v_pk_mul_f32 v[78:79], v[78:79], v[84:85]
	s_nop 0
	v_pk_mul_f32 v[70:71], v[70:71], v[78:79]
	v_mul_f32_e32 v78, 0xbfb8aa3b, v74
	v_mul_f32_e32 v79, 0xbfb8aa3b, v75
	v_exp_f32_e32 v78, v78
	v_exp_f32_e32 v79, v79
	v_add_f32_e32 v78, 1.0, v78
	v_add_f32_e32 v79, 1.0, v79
	v_rcp_f32_e32 v78, v78
	v_rcp_f32_e32 v79, v79
	s_nop 0
	v_pk_mul_f32 v[74:75], v[74:75], v[78:79]
	s_nop 0
	v_pk_mul_f32 v[74:75], v[66:67], v[74:75]
	v_pk_mul_f32 v[66:67], v[80:81], v[150:151] op_sel_hi:[1,0]
	s_nop 0
	v_mul_f32_e32 v78, 0xbfb8aa3b, v66
	v_mul_f32_e32 v79, 0xbfb8aa3b, v67
	v_exp_f32_e32 v78, v78
	v_exp_f32_e32 v79, v79
	v_add_f32_e32 v78, 1.0, v78
	v_add_f32_e32 v79, 1.0, v79
	v_rcp_f32_e32 v78, v78
	v_rcp_f32_e32 v79, v79
	s_nop 0
	v_pk_mul_f32 v[66:67], v[66:67], v[78:79]
	s_nop 0
	v_pk_mul_f32 v[72:73], v[72:73], v[66:67]
	v_pk_mul_f32 v[66:67], v[76:77], v[150:151] op_sel_hi:[1,0]
	v_lshl_add_u64 v[78:79], v[82:83], 0, v[114:115]
	v_mul_f32_e32 v76, 0xbfb8aa3b, v66
	v_mul_f32_e32 v77, 0xbfb8aa3b, v67
	v_exp_f32_e32 v76, v76
	v_exp_f32_e32 v77, v77
	v_add_f32_e32 v76, 1.0, v76
	v_add_f32_e32 v77, 1.0, v77
	v_rcp_f32_e32 v76, v76
	v_rcp_f32_e32 v77, v77
	s_nop 0
	v_pk_mul_f32 v[66:67], v[66:67], v[76:77]
	s_nop 0
	v_pk_mul_f32 v[76:77], v[68:69], v[66:67]
	v_cvt_pk_bf16_f32 v66, v70, v71
	v_cvt_pk_bf16_f32 v67, v72, v73
	v_cvt_pk_bf16_f32 v68, v74, v75
	v_cvt_pk_bf16_f32 v69, v76, v77
	global_store_dwordx4 v[78:79], v[66:69], off
	s_nop 1
	v_mul_f32_e32 v68, 0xbfb8aa3b, v62
	v_mul_f32_e32 v69, 0xbfb8aa3b, v63
	v_exp_f32_e32 v68, v68
	v_exp_f32_e32 v69, v69
	v_mad_i64_i32 v[66:67], s[18:19], v157, s3, v[144:145]
	v_add_f32_e32 v68, 1.0, v68
	v_add_f32_e32 v69, 1.0, v69
	v_rcp_f32_e32 v68, v68
	v_rcp_f32_e32 v69, v69
	s_nop 0
	v_pk_mul_f32 v[62:63], v[62:63], v[68:69]
	s_nop 0
	v_pk_mul_f32 v[54:55], v[54:55], v[62:63]
	v_mul_f32_e32 v62, 0xbfb8aa3b, v58
	v_mul_f32_e32 v63, 0xbfb8aa3b, v59
	v_exp_f32_e32 v62, v62
	v_exp_f32_e32 v63, v63
	v_add_f32_e32 v62, 1.0, v62
	v_add_f32_e32 v63, 1.0, v63
	v_rcp_f32_e32 v62, v62
	v_rcp_f32_e32 v63, v63
	s_nop 0
	v_pk_mul_f32 v[58:59], v[58:59], v[62:63]
	s_nop 0
	v_pk_mul_f32 v[58:59], v[50:51], v[58:59]
	v_pk_mul_f32 v[50:51], v[64:65], v[148:149] op_sel_hi:[1,0]
	s_nop 0
	v_mul_f32_e32 v62, 0xbfb8aa3b, v50
	v_mul_f32_e32 v63, 0xbfb8aa3b, v51
	v_exp_f32_e32 v62, v62
	v_exp_f32_e32 v63, v63
	v_add_f32_e32 v62, 1.0, v62
	v_add_f32_e32 v63, 1.0, v63
	v_rcp_f32_e32 v62, v62
	v_rcp_f32_e32 v63, v63
	s_nop 0
	v_pk_mul_f32 v[50:51], v[50:51], v[62:63]
	s_nop 0
	v_pk_mul_f32 v[56:57], v[56:57], v[50:51]
	v_pk_mul_f32 v[50:51], v[60:61], v[148:149] op_sel_hi:[1,0]
	v_lshl_add_u64 v[62:63], v[66:67], 0, v[114:115]
	v_mul_f32_e32 v60, 0xbfb8aa3b, v50
	v_mul_f32_e32 v61, 0xbfb8aa3b, v51
	v_exp_f32_e32 v60, v60
	v_exp_f32_e32 v61, v61
	v_add_f32_e32 v60, 1.0, v60
	v_add_f32_e32 v61, 1.0, v61
	v_rcp_f32_e32 v60, v60
	v_rcp_f32_e32 v61, v61
	s_nop 0
	v_pk_mul_f32 v[50:51], v[50:51], v[60:61]
	s_nop 0
	v_pk_mul_f32 v[60:61], v[52:53], v[50:51]
	v_cvt_pk_bf16_f32 v50, v54, v55
	v_cvt_pk_bf16_f32 v51, v56, v57
	v_cvt_pk_bf16_f32 v52, v58, v59
	v_cvt_pk_bf16_f32 v53, v60, v61
	global_store_dwordx4 v[62:63], v[50:53], off
	s_nop 1
	v_mul_f32_e32 v52, 0xbfb8aa3b, v46
	v_mul_f32_e32 v53, 0xbfb8aa3b, v47
	v_exp_f32_e32 v52, v52
	v_exp_f32_e32 v53, v53
	v_mad_i64_i32 v[50:51], s[18:19], v155, s3, v[144:145]
	v_add_f32_e32 v52, 1.0, v52
	v_add_f32_e32 v53, 1.0, v53
	v_rcp_f32_e32 v52, v52
	v_rcp_f32_e32 v53, v53
	s_nop 0
	v_pk_mul_f32 v[46:47], v[46:47], v[52:53]
	s_nop 0
	v_pk_mul_f32 v[38:39], v[38:39], v[46:47]
; __device__ __forceinline__ unsigned cvt_pk_bf16(float lo, float hi) { const f32v2_t v = {lo, hi}; const bf16v2_t b = __builtin_convertvector(v, bf16v2_t); return __builtin_bit_cast(unsigned, b); }
; __device__ __forceinline__ float silu_f(float x) { return x * __builtin_amdgcn_rcpf(1.f + __expf(-x)); }
; template <class Epi>
; __device__ __forceinline__ void gemm_phase(LAS unsigned char* lds, const Gemm g, const StaticOrder& S, const Epi& E) {
;     ...
;         E(acc, cur, wr, wc, fr, fq);
;         if (!has_next) break;
;     __device__ __forceinline__ void operator()(const f32x4 (&acc)[2][2][4][2], const Unit& u, int wr, int wc, int fr, int fq) const {
;     ...
;         for (int ai = 0; ai < 2; ++ai)
; #pragma unroll
;             for (int m = 0; m < 4; ++m) { bf16_t* rowp = H + (size_t)(row0 + ai * HALF + m * 16) * DFF + col0;
;                 const float rs = rsv[ai][m];
;                 f32x4 h0, h1;
; #pragma unroll
;                 for (int j = 0; j < 4; ++j) { h0[j] = silu_f(acc[ai][0][m][0][j] * rs) * (acc[ai][1][m][0][j] * rs); h1[j] = silu_f(acc[ai][0][m][1][j] * rs) * (acc[ai][1][m][1][j] * rs); }
;                 u32x4 w; w.x = cvt_pk_bf16(h0[0], h0[1]); w.y = cvt_pk_bf16(h0[2], h0[3]); w.z = cvt_pk_bf16(h1[0], h1[1]); w.w = cvt_pk_bf16(h1[2], h1[3]);
;                 *(u32x4*)rowp = w; }
	v_mul_f32_e32 v46, 0xbfb8aa3b, v42
	v_mul_f32_e32 v47, 0xbfb8aa3b, v43
	v_exp_f32_e32 v46, v46
	v_exp_f32_e32 v47, v47
	v_add_f32_e32 v46, 1.0, v46
	v_add_f32_e32 v47, 1.0, v47
	v_rcp_f32_e32 v46, v46
	v_rcp_f32_e32 v47, v47
	s_nop 0
	v_pk_mul_f32 v[42:43], v[42:43], v[46:47]
	s_nop 0
	v_pk_mul_f32 v[42:43], v[34:35], v[42:43]
	v_pk_mul_f32 v[34:35], v[48:49], v[146:147] op_sel_hi:[1,0]
	s_nop 0
	v_mul_f32_e32 v46, 0xbfb8aa3b, v34
	v_mul_f32_e32 v47, 0xbfb8aa3b, v35
	v_exp_f32_e32 v46, v46
	v_exp_f32_e32 v47, v47
	v_add_f32_e32 v46, 1.0, v46
	v_add_f32_e32 v47, 1.0, v47
	v_rcp_f32_e32 v46, v46
	v_rcp_f32_e32 v47, v47
	s_nop 0
	v_pk_mul_f32 v[34:35], v[34:35], v[46:47]
	s_nop 0
	v_pk_mul_f32 v[40:41], v[40:41], v[34:35]
	v_pk_mul_f32 v[34:35], v[44:45], v[146:147] op_sel_hi:[1,0]
	v_lshl_add_u64 v[46:47], v[50:51], 0, v[114:115]
	v_mul_f32_e32 v44, 0xbfb8aa3b, v34
	v_mul_f32_e32 v45, 0xbfb8aa3b, v35
	v_exp_f32_e32 v44, v44
	v_exp_f32_e32 v45, v45
	v_add_f32_e32 v44, 1.0, v44
	v_add_f32_e32 v45, 1.0, v45
	v_rcp_f32_e32 v44, v44
	v_rcp_f32_e32 v45, v45
	s_nop 0
	v_pk_mul_f32 v[34:35], v[34:35], v[44:45]
	s_nop 0
	v_pk_mul_f32 v[44:45], v[36:37], v[34:35]
	v_cvt_pk_bf16_f32 v34, v38, v39
	v_cvt_pk_bf16_f32 v35, v40, v41
	v_cvt_pk_bf16_f32 v36, v42, v43
	v_cvt_pk_bf16_f32 v37, v44, v45
	global_store_dwordx4 v[46:47], v[34:37], off
	s_nop 1
	v_mul_f32_e32 v36, 0xbfb8aa3b, v30
	v_mul_f32_e32 v37, 0xbfb8aa3b, v31
	v_exp_f32_e32 v36, v36
	v_exp_f32_e32 v37, v37
	v_mad_i64_i32 v[34:35], s[18:19], v153, s3, v[144:145]
	v_add_f32_e32 v36, 1.0, v36
	v_add_f32_e32 v37, 1.0, v37
	v_rcp_f32_e32 v36, v36
	v_rcp_f32_e32 v37, v37
	s_nop 0
	v_pk_mul_f32 v[30:31], v[30:31], v[36:37]
	s_nop 0
	v_pk_mul_f32 v[22:23], v[22:23], v[30:31]
	v_mul_f32_e32 v30, 0xbfb8aa3b, v26
	v_mul_f32_e32 v31, 0xbfb8aa3b, v27
	v_exp_f32_e32 v30, v30
	v_exp_f32_e32 v31, v31
	v_add_f32_e32 v30, 1.0, v30
	v_add_f32_e32 v31, 1.0, v31
	v_rcp_f32_e32 v30, v30
	v_rcp_f32_e32 v31, v31
	s_nop 0
	v_pk_mul_f32 v[26:27], v[26:27], v[30:31]
	s_nop 0
	v_pk_mul_f32 v[26:27], v[18:19], v[26:27]
	v_pk_mul_f32 v[18:19], v[32:33], v[142:143] op_sel_hi:[1,0]
	s_nop 0
	v_mul_f32_e32 v30, 0xbfb8aa3b, v18
	v_mul_f32_e32 v31, 0xbfb8aa3b, v19
	v_exp_f32_e32 v30, v30
	v_exp_f32_e32 v31, v31
	v_add_f32_e32 v30, 1.0, v30
	v_add_f32_e32 v31, 1.0, v31
	v_rcp_f32_e32 v30, v30
	v_rcp_f32_e32 v31, v31
	s_nop 0
	v_pk_mul_f32 v[18:19], v[18:19], v[30:31]
	s_nop 0
	v_pk_mul_f32 v[24:25], v[24:25], v[18:19]
	v_pk_mul_f32 v[18:19], v[28:29], v[142:143] op_sel_hi:[1,0]
	v_lshl_add_u64 v[30:31], v[34:35], 0, v[114:115]
	v_mul_f32_e32 v28, 0xbfb8aa3b, v18
	v_mul_f32_e32 v29, 0xbfb8aa3b, v19
	v_exp_f32_e32 v28, v28
	v_exp_f32_e32 v29, v29
	v_add_f32_e32 v28, 1.0, v28
	v_add_f32_e32 v29, 1.0, v29
	v_rcp_f32_e32 v28, v28
	v_rcp_f32_e32 v29, v29
	s_nop 0
	v_pk_mul_f32 v[18:19], v[18:19], v[28:29]
	s_nop 0
	v_pk_mul_f32 v[28:29], v[20:21], v[18:19]
	v_cvt_pk_bf16_f32 v18, v22, v23
	v_cvt_pk_bf16_f32 v19, v24, v25
	v_cvt_pk_bf16_f32 v20, v26, v27
	v_cvt_pk_bf16_f32 v21, v28, v29
	global_store_dwordx4 v[30:31], v[18:21], off
	s_nop 1
	v_mul_f32_e32 v20, 0xbfb8aa3b, v14
	v_mul_f32_e32 v21, 0xbfb8aa3b, v15
	v_exp_f32_e32 v20, v20
	v_exp_f32_e32 v21, v21
	v_mad_i64_i32 v[18:19], s[18:19], v151, s3, v[144:145]
	v_add_f32_e32 v20, 1.0, v20
	v_add_f32_e32 v21, 1.0, v21
	v_rcp_f32_e32 v20, v20
	v_rcp_f32_e32 v21, v21
	s_mov_b64 s[18:19], s[10:11]
	v_pk_mul_f32 v[14:15], v[14:15], v[20:21]
	s_nop 0
	v_pk_mul_f32 v[6:7], v[6:7], v[14:15]
	v_mul_f32_e32 v14, 0xbfb8aa3b, v10
	v_mul_f32_e32 v15, 0xbfb8aa3b, v11
	v_exp_f32_e32 v14, v14
	v_exp_f32_e32 v15, v15
	v_add_f32_e32 v14, 1.0, v14
	v_add_f32_e32 v15, 1.0, v15
	v_rcp_f32_e32 v14, v14
	v_rcp_f32_e32 v15, v15
	s_nop 0
	v_pk_mul_f32 v[10:11], v[10:11], v[14:15]
	s_nop 0
	v_pk_mul_f32 v[10:11], v[2:3], v[10:11]
	v_pk_mul_f32 v[2:3], v[16:17], v[140:141] op_sel_hi:[1,0]
	s_nop 0
	v_mul_f32_e32 v14, 0xbfb8aa3b, v2
	v_mul_f32_e32 v15, 0xbfb8aa3b, v3
	v_exp_f32_e32 v14, v14
	v_exp_f32_e32 v15, v15
	v_add_f32_e32 v14, 1.0, v14
	v_add_f32_e32 v15, 1.0, v15
	v_rcp_f32_e32 v14, v14
	v_rcp_f32_e32 v15, v15
	s_nop 0
	v_pk_mul_f32 v[2:3], v[2:3], v[14:15]
	s_nop 0
	v_pk_mul_f32 v[8:9], v[8:9], v[2:3]
	v_pk_mul_f32 v[2:3], v[12:13], v[140:141] op_sel_hi:[1,0]
	v_lshl_add_u64 v[14:15], v[18:19], 0, v[114:115]
	v_mul_f32_e32 v12, 0xbfb8aa3b, v2
	v_mul_f32_e32 v13, 0xbfb8aa3b, v3
	v_exp_f32_e32 v12, v12
	v_exp_f32_e32 v13, v13
	v_add_f32_e32 v12, 1.0, v12
	v_add_f32_e32 v13, 1.0, v13
	v_rcp_f32_e32 v12, v12
	v_rcp_f32_e32 v13, v13
	s_nop 0
	v_pk_mul_f32 v[2:3], v[2:3], v[12:13]
	s_nop 0
	v_pk_mul_f32 v[12:13], v[4:5], v[2:3]
	v_cvt_pk_bf16_f32 v2, v6, v7
	v_cvt_pk_bf16_f32 v3, v8, v9
	v_cvt_pk_bf16_f32 v4, v10, v11
	v_cvt_pk_bf16_f32 v5, v12, v13
	global_store_dwordx4 v[14:15], v[2:5], off
	s_cbranch_vccz .LBB0_914
	s_waitcnt vmcnt(0)
	s_cmpk_gt_u32 s2, 0xff
	s_cbranch_scc1 .LBB0_921
	s_barrier

; #define PG8_STAGE(bufoff, gbase, voff) do { _Pragma("unroll") for (int _i = 0; _i < 2; ++_i) \
;         __builtin_amdgcn_global_load_lds((const unsigned*)((const char*)(gbase) + (voff)[_i]), (LAS unsigned*)(lds + (bufoff) + ldsw + _i * 8192), 16, 0, 0); } while (0)
; #define PG8_LDA(dst, b, h) do { _Pragma("unroll") for (int m = 0; m < 4; ++m) _Pragma("unroll") for (int k = 0; k < 2; ++k) dst[m][k] = *(const LAS bf16x8*)(lds + PG8_SA(b, h) + aoff + m * 2048 + k * 1024); } while (0)
; #define PG8_LDB(dst, b, h) do { _Pragma("unroll") for (int n = 0; n < 2; ++n) _Pragma("unroll") for (int k = 0; k < 2; ++k) dst[n][k] = *(const LAS bf16x8*)(lds + PG8_SB(b, h) + boff + n * 2048 + k * 1024); } while (0)
; #define PG8_MMA(ai, bj, At, Bt) do { __builtin_amdgcn_s_setprio(1); _Pragma("unroll") for (int m = 0; m < 4; ++m) _Pragma("unroll") for (int n = 0; n < 2; ++n) _Pragma("unroll") for (int k = 0; k < 2; ++k) \
;         acc[ai][bj][m][n] = __builtin_amdgcn_mfma_f32_16x16x32_bf16(Bt[n][k], At[m][k], acc[ai][bj][m][n], 0, 0, 0); __builtin_amdgcn_s_setprio(0); } while (0)
; #define PG8_WAIT_V(n) asm volatile("s_waitcnt vmcnt(" #n ")" ::: "memory")
; #define PG8_WAIT_L(n) asm volatile("s_waitcnt lgkmcnt(" #n ")" ::: "memory")
; #define PG8_BAR __builtin_amdgcn_s_barrier()
; #define PG8_SCHED __builtin_amdgcn_sched_barrier(0)
; template <class Epi>
; __device__ __forceinline__ void gemm_phase(LAS unsigned char* lds, const Gemm g, const StaticOrder& S, const Epi& E) {
;     ...
;             PG8_LDB(B0, 0, 0); PG8_SCHED; PG8_LDA(At, 0, 0); PG8_STAGE(PG8_SA(1, 1), a1 + hstep, voffA);
;             PG8_WAIT_L(8); PG8_BAR; PG8_WAIT_L(0); PG8_MMA(0, 0, At, B0); PG8_BAR; PG8_SCHED;
;             PG8_LDB(B1, 0, 1); PG8_STAGE(PG8_SB(0, 0), b2, voffB);
;             PG8_BAR; PG8_WAIT_L(0); PG8_MMA(0, 1, At, B1); PG8_BAR;
;             PG8_LDA(At, 0, 1); PG8_STAGE(PG8_SA(0, 0), a2, voffA);
;             PG8_BAR; PG8_WAIT_L(0); PG8_MMA(1, 0, At, B0); PG8_BAR; PG8_SCHED;
;             PG8_STAGE(PG8_SB(0, 1), b2 + hstep, voffB);
;             PG8_WAIT_V(6); PG8_BAR; PG8_MMA(1, 1, At, B1); PG8_BAR;
.LBB0_991:
	s_add_u32 s10, s20, 0x100
	s_addc_u32 s11, s21, 0
	s_add_i32 s46, 0, 0x10000
	v_add_u32_e32 v118, s46, v229
	ds_read_b128 v[86:89], v118
	ds_read_b128 v[94:97], v118 offset:1024
	ds_read_b128 v[106:109], v118 offset:2048
	ds_read_b128 v[118:121], v118 offset:3072
	s_cmpk_eq_i32 s45, 0x54
	s_cselect_b32 s25, s1, s11
	s_cselect_b32 s24, s0, s10
	s_cselect_b32 s23, s19, s44
	s_cselect_b32 s22, s18, s43
	v_lshl_add_u64 v[178:179], s[20:21], 0, v[196:197]
	s_add_i32 m0, s29, 0xc000
	ds_read_b128 v[130:133], v232
	ds_read_b128 v[142:145], v232 offset:1024
	ds_read_b128 v[154:157], v232 offset:2048
	ds_read_b128 v[158:161], v232 offset:3072
	ds_read_b128 v[162:165], v232 offset:4096
	ds_read_b128 v[166:169], v232 offset:5120
	ds_read_b128 v[170:173], v232 offset:6144
	ds_read_b128 v[174:177], v232 offset:7168
	global_load_lds_dwordx4 v[178:179], off
	v_lshl_add_u64 v[178:179], s[20:21], 0, v[198:199]
	s_add_i32 m0, s29, 0xe000
	s_nop 0
	global_load_lds_dwordx4 v[178:179], off
	s_waitcnt lgkmcnt(8)
	s_barrier
	s_waitcnt lgkmcnt(0)
	s_waitcnt lgkmcnt(0)
	v_mfma_f32_16x16x32_bf16 v[150:153], v[86:89], v[130:133], v[150:153]
	v_mfma_f32_16x16x32_bf16 v[146:149], v[106:109], v[130:133], v[146:149]
	v_mfma_f32_16x16x32_bf16 v[126:129], v[86:89], v[154:157], v[126:129]
	v_mfma_f32_16x16x32_bf16 v[122:125], v[106:109], v[154:157], v[122:125]
	v_mfma_f32_16x16x32_bf16 v[102:105], v[86:89], v[162:165], v[102:105]
	v_mfma_f32_16x16x32_bf16 v[98:101], v[106:109], v[162:165], v[98:101]
	v_mfma_f32_16x16x32_bf16 v[78:81], v[86:89], v[170:173], v[78:81]
	v_mfma_f32_16x16x32_bf16 v[74:77], v[106:109], v[170:173], v[74:77]
	v_mfma_f32_16x16x32_bf16 v[150:153], v[94:97], v[142:145], v[150:153]
	v_mfma_f32_16x16x32_bf16 v[146:149], v[118:121], v[142:145], v[146:149]
	v_mfma_f32_16x16x32_bf16 v[126:129], v[94:97], v[158:161], v[126:129]
	v_mfma_f32_16x16x32_bf16 v[122:125], v[118:121], v[158:161], v[122:125]
	v_mfma_f32_16x16x32_bf16 v[102:105], v[94:97], v[166:169], v[102:105]
	v_mfma_f32_16x16x32_bf16 v[98:101], v[118:121], v[166:169], v[98:101]
	v_mfma_f32_16x16x32_bf16 v[78:81], v[94:97], v[174:177], v[78:81]
	v_mfma_f32_16x16x32_bf16 v[74:77], v[118:121], v[174:177], v[74:77]
	s_barrier
	s_add_i32 s47, 0, 0x14000
	s_add_i32 s20, s46, s28
	v_add_u32_e32 v200, s47, v229
	v_lshl_add_u64 v[204:205], s[22:23], 0, v[0:1]
	s_mov_b32 m0, s20
	ds_read_b128 v[178:181], v200
	ds_read_b128 v[182:185], v200 offset:1024
	ds_read_b128 v[186:189], v200 offset:2048
	ds_read_b128 v[200:203], v200 offset:3072
	global_load_lds_dwordx4 v[204:205], off
	v_lshl_add_u64 v[206:207], s[22:23], 0, v[190:191]
	s_add_i32 m0, s20, 0x2000
	s_nop 0
	global_load_lds_dwordx4 v[206:207], off
	s_barrier
	s_waitcnt lgkmcnt(0)
	s_waitcnt lgkmcnt(0)
	v_mfma_f32_16x16x32_bf16 v[138:141], v[178:181], v[130:133], v[138:141]
	v_mfma_f32_16x16x32_bf16 v[114:117], v[178:181], v[154:157], v[114:117]
	v_mfma_f32_16x16x32_bf16 v[110:113], v[186:189], v[154:157], v[110:113]
	v_mfma_f32_16x16x32_bf16 v[90:93], v[178:181], v[162:165], v[90:93]
	v_mfma_f32_16x16x32_bf16 v[82:85], v[186:189], v[162:165], v[82:85]
	v_mfma_f32_16x16x32_bf16 v[70:73], v[178:181], v[170:173], v[70:73]
	v_mfma_f32_16x16x32_bf16 v[66:69], v[186:189], v[170:173], v[66:69]
	v_mfma_f32_16x16x32_bf16 v[138:141], v[182:185], v[142:145], v[138:141]
	v_mfma_f32_16x16x32_bf16 v[130:133], v[186:189], v[130:133], v[134:137]
	v_mfma_f32_16x16x32_bf16 v[114:117], v[182:185], v[158:161], v[114:117]
	v_mfma_f32_16x16x32_bf16 v[110:113], v[200:203], v[158:161], v[110:113]
	v_mfma_f32_16x16x32_bf16 v[90:93], v[182:185], v[166:169], v[90:93]
	v_mfma_f32_16x16x32_bf16 v[82:85], v[200:203], v[166:169], v[82:85]
	v_mfma_f32_16x16x32_bf16 v[70:73], v[182:185], v[174:177], v[70:73]
	v_mfma_f32_16x16x32_bf16 v[66:69], v[200:203], v[174:177], v[66:69]
	v_mfma_f32_16x16x32_bf16 v[130:133], v[200:203], v[142:145], v[130:133]
	s_mov_b32 m0, s29
	v_lshl_add_u64 v[208:209], s[24:25], 0, v[194:195]
	s_barrier
	ds_read_b128 v[134:137], v232 offset:16384
	ds_read_b128 v[142:145], v232 offset:17408
	ds_read_b128 v[154:157], v232 offset:18432
	ds_read_b128 v[158:161], v232 offset:19456
	ds_read_b128 v[162:165], v232 offset:20480
	ds_read_b128 v[166:169], v232 offset:21504
	ds_read_b128 v[170:173], v232 offset:22528
	ds_read_b128 v[174:177], v232 offset:23552
	global_load_lds_dwordx4 v[208:209], off
	v_lshl_add_u64 v[214:215], s[24:25], 0, v[192:193]
	s_mov_b32 m0, s30
	s_nop 0
	global_load_lds_dwordx4 v[214:215], off
	s_barrier
	s_waitcnt lgkmcnt(0)
	s_waitcnt lgkmcnt(0)
	v_mfma_f32_16x16x32_bf16 v[62:65], v[86:89], v[134:137], v[62:65]
	v_mfma_f32_16x16x32_bf16 v[58:61], v[106:109], v[134:137], v[58:61]
	v_mfma_f32_16x16x32_bf16 v[46:49], v[86:89], v[154:157], v[46:49]
	v_mfma_f32_16x16x32_bf16 v[42:45], v[106:109], v[154:157], v[42:45]
	v_mfma_f32_16x16x32_bf16 v[30:33], v[86:89], v[162:165], v[30:33]
	v_mfma_f32_16x16x32_bf16 v[26:29], v[106:109], v[162:165], v[26:29]
	v_mfma_f32_16x16x32_bf16 v[14:17], v[86:89], v[170:173], v[14:17]
	v_mfma_f32_16x16x32_bf16 v[10:13], v[106:109], v[170:173], v[10:13]
	v_mfma_f32_16x16x32_bf16 v[62:65], v[94:97], v[142:145], v[62:65]
	v_mfma_f32_16x16x32_bf16 v[58:61], v[118:121], v[142:145], v[58:61]
	v_mfma_f32_16x16x32_bf16 v[46:49], v[94:97], v[158:161], v[46:49]
	v_mfma_f32_16x16x32_bf16 v[42:45], v[118:121], v[158:161], v[42:45]
	v_mfma_f32_16x16x32_bf16 v[30:33], v[94:97], v[166:169], v[30:33]
	v_mfma_f32_16x16x32_bf16 v[26:29], v[118:121], v[166:169], v[26:29]
	v_mfma_f32_16x16x32_bf16 v[14:17], v[94:97], v[174:177], v[14:17]
	v_mfma_f32_16x16x32_bf16 v[10:13], v[118:121], v[174:177], v[10:13]
	s_barrier
; #define PG8_STAGE(bufoff, gbase, voff) do { _Pragma("unroll") for (int _i = 0; _i < 2; ++_i) \
;         __builtin_amdgcn_global_load_lds((const unsigned*)((const char*)(gbase) + (voff)[_i]), (LAS unsigned*)(lds + (bufoff) + ldsw + _i * 8192), 16, 0, 0); } while (0)
; #define PG8_LDA(dst, b, h) do { _Pragma("unroll") for (int m = 0; m < 4; ++m) _Pragma("unroll") for (int k = 0; k < 2; ++k) dst[m][k] = *(const LAS bf16x8*)(lds + PG8_SA(b, h) + aoff + m * 2048 + k * 1024); } while (0)
; #define PG8_LDB(dst, b, h) do { _Pragma("unroll") for (int n = 0; n < 2; ++n) _Pragma("unroll") for (int k = 0; k < 2; ++k) dst[n][k] = *(const LAS bf16x8*)(lds + PG8_SB(b, h) + boff + n * 2048 + k * 1024); } while (0)
; #define PG8_MMA(ai, bj, At, Bt) do { __builtin_amdgcn_s_setprio(1); _Pragma("unroll") for (int m = 0; m < 4; ++m) _Pragma("unroll") for (int n = 0; n < 2; ++n) _Pragma("unroll") for (int k = 0; k < 2; ++k) \
;         acc[ai][bj][m][n] = __builtin_amdgcn_mfma_f32_16x16x32_bf16(Bt[n][k], At[m][k], acc[ai][bj][m][n], 0, 0, 0); __builtin_amdgcn_s_setprio(0); } while (0)
; #define PG8_WAIT_V(n) asm volatile("s_waitcnt vmcnt(" #n ")" ::: "memory")
; #define PG8_WAIT_L(n) asm volatile("s_waitcnt lgkmcnt(" #n ")" ::: "memory")
; #define PG8_BAR __builtin_amdgcn_s_barrier()
; #define PG8_SCHED __builtin_amdgcn_sched_barrier(0)
; template <class Epi>
; __device__ __forceinline__ void gemm_phase(LAS unsigned char* lds, const Gemm g, const StaticOrder& S, const Epi& E) {
;     ...
;             PG8_STAGE(PG8_SB(0, 1), b2 + hstep, voffB);
;             PG8_WAIT_V(6); PG8_BAR; PG8_MMA(1, 1, At, B1); PG8_BAR;
;             PG8_LDB(B0, 1, 0); PG8_SCHED; PG8_LDA(At, 1, 0); PG8_STAGE(PG8_SA(0, 1), a2 + hstep, voffA);
;             PG8_WAIT_L(8); PG8_BAR; PG8_WAIT_L(0); PG8_MMA(0, 0, At, B0); PG8_BAR; PG8_SCHED;
;             PG8_LDB(B1, 1, 1); PG8_STAGE(PG8_SB(1, 0), b3, voffB);
;             PG8_BAR; PG8_WAIT_L(0); PG8_MMA(0, 1, At, B1); PG8_BAR;
;             PG8_LDA(At, 1, 1); PG8_STAGE(PG8_SA(1, 0), a3, voffA);
	s_add_u32 s20, s22, 0x160000
	s_addc_u32 s21, s23, 0
	s_add_i32 s46, s47, s28
	v_lshl_add_u64 v[86:87], s[20:21], 0, v[0:1]
	s_mov_b32 m0, s46
	s_nop 0
	global_load_lds_dwordx4 v[86:87], off
	v_lshl_add_u64 v[86:87], s[20:21], 0, v[190:191]
	s_add_i32 m0, s46, 0x2000
	s_nop 0
	global_load_lds_dwordx4 v[86:87], off
	s_waitcnt vmcnt(6)
	s_barrier
	v_mfma_f32_16x16x32_bf16 v[54:57], v[178:181], v[134:137], v[54:57]
	v_mfma_f32_16x16x32_bf16 v[50:53], v[186:189], v[134:137], v[50:53]
	v_mfma_f32_16x16x32_bf16 v[38:41], v[178:181], v[154:157], v[38:41]
	v_mfma_f32_16x16x32_bf16 v[34:37], v[186:189], v[154:157], v[34:37]
	v_mfma_f32_16x16x32_bf16 v[22:25], v[178:181], v[162:165], v[22:25]
	v_mfma_f32_16x16x32_bf16 v[18:21], v[186:189], v[162:165], v[18:21]
	v_mfma_f32_16x16x32_bf16 v[6:9], v[178:181], v[170:173], v[6:9]
	v_mfma_f32_16x16x32_bf16 v[2:5], v[186:189], v[170:173], v[2:5]
	v_mfma_f32_16x16x32_bf16 v[54:57], v[182:185], v[142:145], v[54:57]
	v_mfma_f32_16x16x32_bf16 v[50:53], v[200:203], v[142:145], v[50:53]
	v_mfma_f32_16x16x32_bf16 v[38:41], v[182:185], v[158:161], v[38:41]
	v_mfma_f32_16x16x32_bf16 v[34:37], v[200:203], v[158:161], v[34:37]
	v_mfma_f32_16x16x32_bf16 v[22:25], v[182:185], v[166:169], v[22:25]
	v_mfma_f32_16x16x32_bf16 v[18:21], v[200:203], v[166:169], v[18:21]
	v_mfma_f32_16x16x32_bf16 v[6:9], v[182:185], v[174:177], v[6:9]
	v_mfma_f32_16x16x32_bf16 v[2:5], v[200:203], v[174:177], v[2:5]
	s_add_i32 s46, 0, 0x18000
	v_add_u32_e32 v118, s46, v229
	s_barrier
	ds_read_b128 v[86:89], v118
	ds_read_b128 v[94:97], v118 offset:1024
	ds_read_b128 v[106:109], v118 offset:2048
	ds_read_b128 v[118:121], v118 offset:3072
	s_add_u32 s20, s24, 0x160000
	s_addc_u32 s21, s25, 0
	s_mov_b32 m0, s31
	v_lshl_add_u64 v[178:179], s[20:21], 0, v[194:195]
	ds_read_b128 v[134:137], v232 offset:32768
	ds_read_b128 v[142:145], v232 offset:33792
	ds_read_b128 v[154:157], v232 offset:34816
	ds_read_b128 v[158:161], v232 offset:35840
	ds_read_b128 v[162:165], v232 offset:36864
	ds_read_b128 v[166:169], v232 offset:37888
	ds_read_b128 v[170:173], v232 offset:38912
	ds_read_b128 v[174:177], v232 offset:39936
	global_load_lds_dwordx4 v[178:179], off
	v_lshl_add_u64 v[178:179], s[20:21], 0, v[192:193]
	s_mov_b32 m0, s34
	s_nop 0
	global_load_lds_dwordx4 v[178:179], off
	s_waitcnt lgkmcnt(8)
	s_barrier
	s_waitcnt lgkmcnt(0)
	s_waitcnt lgkmcnt(0)
	v_mfma_f32_16x16x32_bf16 v[150:153], v[86:89], v[134:137], v[150:153]
	v_mfma_f32_16x16x32_bf16 v[146:149], v[106:109], v[134:137], v[146:149]
	v_mfma_f32_16x16x32_bf16 v[126:129], v[86:89], v[154:157], v[126:129]
	v_mfma_f32_16x16x32_bf16 v[122:125], v[106:109], v[154:157], v[122:125]
	v_mfma_f32_16x16x32_bf16 v[102:105], v[86:89], v[162:165], v[102:105]
	v_mfma_f32_16x16x32_bf16 v[98:101], v[106:109], v[162:165], v[98:101]
	v_mfma_f32_16x16x32_bf16 v[78:81], v[86:89], v[170:173], v[78:81]
	v_mfma_f32_16x16x32_bf16 v[74:77], v[106:109], v[170:173], v[74:77]
	v_mfma_f32_16x16x32_bf16 v[150:153], v[94:97], v[142:145], v[150:153]
	v_mfma_f32_16x16x32_bf16 v[146:149], v[118:121], v[142:145], v[146:149]
	v_mfma_f32_16x16x32_bf16 v[126:129], v[94:97], v[158:161], v[126:129]
	v_mfma_f32_16x16x32_bf16 v[122:125], v[118:121], v[158:161], v[122:125]
	v_mfma_f32_16x16x32_bf16 v[102:105], v[94:97], v[166:169], v[102:105]
	v_mfma_f32_16x16x32_bf16 v[98:101], v[118:121], v[166:169], v[98:101]
	v_mfma_f32_16x16x32_bf16 v[78:81], v[94:97], v[174:177], v[78:81]
	v_mfma_f32_16x16x32_bf16 v[74:77], v[118:121], v[174:177], v[74:77]
	s_barrier
	s_add_i32 s24, 0, 0x1c000
	s_add_i32 s20, s46, s28
	v_add_u32_e32 v200, s24, v229
	v_lshl_add_u64 v[204:205], v[204:205], 0, s[66:67]
	s_mov_b32 m0, s20
	ds_read_b128 v[178:181], v200
	ds_read_b128 v[182:185], v200 offset:1024
	ds_read_b128 v[186:189], v200 offset:2048
	ds_read_b128 v[200:203], v200 offset:3072
	global_load_lds_dwordx4 v[204:205], off
	v_lshl_add_u64 v[204:205], v[206:207], 0, s[66:67]
	s_add_i32 m0, s20, 0x2000
	s_nop 0
	global_load_lds_dwordx4 v[204:205], off
	s_barrier
	s_waitcnt lgkmcnt(0)
	s_waitcnt lgkmcnt(0)
	v_mfma_f32_16x16x32_bf16 v[138:141], v[178:181], v[134:137], v[138:141]
	v_mfma_f32_16x16x32_bf16 v[130:133], v[186:189], v[134:137], v[130:133]
	v_mfma_f32_16x16x32_bf16 v[114:117], v[178:181], v[154:157], v[114:117]
	v_mfma_f32_16x16x32_bf16 v[110:113], v[186:189], v[154:157], v[110:113]
	v_mfma_f32_16x16x32_bf16 v[90:93], v[178:181], v[162:165], v[90:93]
	v_mfma_f32_16x16x32_bf16 v[82:85], v[186:189], v[162:165], v[82:85]
	v_mfma_f32_16x16x32_bf16 v[70:73], v[178:181], v[170:173], v[70:73]
	v_mfma_f32_16x16x32_bf16 v[66:69], v[186:189], v[170:173], v[66:69]
	v_mfma_f32_16x16x32_bf16 v[138:141], v[182:185], v[142:145], v[138:141]
	v_mfma_f32_16x16x32_bf16 v[134:137], v[200:203], v[142:145], v[130:133]
	v_mfma_f32_16x16x32_bf16 v[114:117], v[182:185], v[158:161], v[114:117]
	v_mfma_f32_16x16x32_bf16 v[110:113], v[200:203], v[158:161], v[110:113]
	v_mfma_f32_16x16x32_bf16 v[90:93], v[182:185], v[166:169], v[90:93]
	v_mfma_f32_16x16x32_bf16 v[82:85], v[200:203], v[166:169], v[82:85]
	v_mfma_f32_16x16x32_bf16 v[70:73], v[182:185], v[174:177], v[70:73]
	v_mfma_f32_16x16x32_bf16 v[66:69], v[200:203], v[174:177], v[66:69]
	s_mov_b32 m0, s36
	v_lshl_add_u64 v[204:205], v[208:209], 0, s[66:67]
	s_barrier
	ds_read_b128 v[130:133], v232 offset:49152
	ds_read_b128 v[142:145], v232 offset:50176
	ds_read_b128 v[154:157], v232 offset:51200
	ds_read_b128 v[158:161], v232 offset:52224
	ds_read_b128 v[162:165], v232 offset:53248
	ds_read_b128 v[166:169], v232 offset:54272
	ds_read_b128 v[170:173], v232 offset:55296
	ds_read_b128 v[174:177], v232 offset:56320
	global_load_lds_dwordx4 v[204:205], off
	v_lshl_add_u64 v[204:205], v[214:215], 0, s[66:67]
	s_mov_b32 m0, s37
	s_nop 0
	global_load_lds_dwordx4 v[204:205], off
	s_barrier
; __device__ __forceinline__ float bflo(unsigned w) { return __uint_as_float(w << 16); }
; __device__ __forceinline__ float bfhi(unsigned w) { return __uint_as_float(w & 0xffff0000u); }
; #define PG8_STAGE(bufoff, gbase, voff) do { _Pragma("unroll") for (int _i = 0; _i < 2; ++_i) \
;         __builtin_amdgcn_global_load_lds((const unsigned*)((const char*)(gbase) + (voff)[_i]), (LAS unsigned*)(lds + (bufoff) + ldsw + _i * 8192), 16, 0, 0); } while (0)
; #define PG8_LDA(dst, b, h) do { _Pragma("unroll") for (int m = 0; m < 4; ++m) _Pragma("unroll") for (int k = 0; k < 2; ++k) dst[m][k] = *(const LAS bf16x8*)(lds + PG8_SA(b, h) + aoff + m * 2048 + k * 1024); } while (0)
; #define PG8_MMA(ai, bj, At, Bt) do { __builtin_amdgcn_s_setprio(1); _Pragma("unroll") for (int m = 0; m < 4; ++m) _Pragma("unroll") for (int n = 0; n < 2; ++n) _Pragma("unroll") for (int k = 0; k < 2; ++k) \
;         acc[ai][bj][m][n] = __builtin_amdgcn_mfma_f32_16x16x32_bf16(Bt[n][k], At[m][k], acc[ai][bj][m][n], 0, 0, 0); __builtin_amdgcn_s_setprio(0); } while (0)
; template <class Epi>
; __device__ __forceinline__ void gemm_phase(LAS unsigned char* lds, const Gemm g, const StaticOrder& S, const Epi& E) {
;     ...
;             PG8_BAR; PG8_WAIT_L(0); PG8_MMA(0, 1, At, B1); PG8_BAR;
;             PG8_LDA(At, 1, 1); PG8_STAGE(PG8_SA(1, 0), a3, voffA);
;             PG8_BAR; PG8_WAIT_L(0); PG8_MMA(1, 0, At, B0); PG8_BAR; PG8_SCHED;
;             PG8_STAGE(PG8_SB(1, 1), b3 + hstep, voffB);
;             PG8_WAIT_V(6); PG8_BAR; PG8_MMA(1, 1, At, B1); PG8_BAR;
;     __device__ __forceinline__ void operator()(const f32x4 (&acc)[2][2][4][2], const Unit& u, int wr, int wc, int fr, int fq) const {
;     ...
;                     for (int bj = 0; bj < 2; ++bj) xin[ai][m][bj] = *(const u32x4*)(Xb + (size_t)(row0 + ai * HALF + m * 16) * DM + col0 + bj * HALF);
; #pragma unroll
;             for (int ai = 0; ai < 2; ++ai)
; #pragma unroll
;                 for (int m = 0; m < 4; ++m) { const int row = row0 + ai * HALF + m * 16; bf16_t* op = Xb + (size_t)row * DM + col0; float ps = 0.f;
; #pragma unroll
;                     for (int bj = 0; bj < 2; ++bj) { const u32x4 x = xin[ai][m][bj];
;                         finish(acc[ai][bj][m][0], acc[ai][bj][m][1], (f32x4){bflo(x.x), bfhi(x.x), bflo(x.y), bfhi(x.y)}, (f32x4){bflo(x.z), bfhi(x.z), bflo(x.w), bfhi(x.w)}, op + bj * HALF, ps); }
	s_waitcnt lgkmcnt(0)
	s_waitcnt lgkmcnt(0)
	v_mfma_f32_16x16x32_bf16 v[62:65], v[86:89], v[130:133], v[62:65]
	v_mfma_f32_16x16x32_bf16 v[58:61], v[106:109], v[130:133], v[58:61]
	v_mfma_f32_16x16x32_bf16 v[46:49], v[86:89], v[154:157], v[46:49]
	v_mfma_f32_16x16x32_bf16 v[42:45], v[106:109], v[154:157], v[42:45]
	v_mfma_f32_16x16x32_bf16 v[30:33], v[86:89], v[162:165], v[30:33]
	v_mfma_f32_16x16x32_bf16 v[26:29], v[106:109], v[162:165], v[26:29]
	v_mfma_f32_16x16x32_bf16 v[14:17], v[86:89], v[170:173], v[14:17]
	v_mfma_f32_16x16x32_bf16 v[10:13], v[106:109], v[170:173], v[10:13]
	v_mfma_f32_16x16x32_bf16 v[62:65], v[94:97], v[142:145], v[62:65]
	v_mfma_f32_16x16x32_bf16 v[58:61], v[118:121], v[142:145], v[58:61]
	v_mfma_f32_16x16x32_bf16 v[46:49], v[94:97], v[158:161], v[46:49]
	v_mfma_f32_16x16x32_bf16 v[42:45], v[118:121], v[158:161], v[42:45]
	v_mfma_f32_16x16x32_bf16 v[30:33], v[94:97], v[166:169], v[30:33]
	v_mfma_f32_16x16x32_bf16 v[26:29], v[118:121], v[166:169], v[26:29]
	v_mfma_f32_16x16x32_bf16 v[14:17], v[94:97], v[174:177], v[14:17]
	v_mfma_f32_16x16x32_bf16 v[10:13], v[118:121], v[174:177], v[10:13]
	s_barrier
	s_add_u32 s20, s22, 0x160080
	s_addc_u32 s21, s23, 0
	s_add_i32 s22, s24, s28
	v_lshl_add_u64 v[86:87], s[20:21], 0, v[0:1]
	s_mov_b32 m0, s22
	s_nop 0
	global_load_lds_dwordx4 v[86:87], off
	v_lshl_add_u64 v[86:87], s[20:21], 0, v[190:191]
	s_add_i32 m0, s22, 0x2000
	s_nop 0
	global_load_lds_dwordx4 v[86:87], off
	s_waitcnt vmcnt(6)
	s_barrier
	v_mfma_f32_16x16x32_bf16 v[54:57], v[178:181], v[130:133], v[54:57]
	v_mfma_f32_16x16x32_bf16 v[50:53], v[186:189], v[130:133], v[50:53]
	v_mfma_f32_16x16x32_bf16 v[38:41], v[178:181], v[154:157], v[38:41]
	v_mfma_f32_16x16x32_bf16 v[34:37], v[186:189], v[154:157], v[34:37]
	v_mfma_f32_16x16x32_bf16 v[22:25], v[178:181], v[162:165], v[22:25]
	v_mfma_f32_16x16x32_bf16 v[18:21], v[186:189], v[162:165], v[18:21]
	v_mfma_f32_16x16x32_bf16 v[6:9], v[178:181], v[170:173], v[6:9]
	v_mfma_f32_16x16x32_bf16 v[2:5], v[186:189], v[170:173], v[2:5]
	v_mfma_f32_16x16x32_bf16 v[54:57], v[182:185], v[142:145], v[54:57]
	v_mfma_f32_16x16x32_bf16 v[50:53], v[200:203], v[142:145], v[50:53]
	v_mfma_f32_16x16x32_bf16 v[38:41], v[182:185], v[158:161], v[38:41]
	v_mfma_f32_16x16x32_bf16 v[34:37], v[200:203], v[158:161], v[34:37]
	v_mfma_f32_16x16x32_bf16 v[22:25], v[182:185], v[166:169], v[22:25]
	v_mfma_f32_16x16x32_bf16 v[18:21], v[200:203], v[166:169], v[18:21]
	v_mfma_f32_16x16x32_bf16 v[6:9], v[182:185], v[174:177], v[6:9]
	v_mfma_f32_16x16x32_bf16 v[2:5], v[200:203], v[174:177], v[2:5]
	s_add_i32 s45, s45, 2
	s_add_u32 s43, s43, 0x100
	s_addc_u32 s44, s44, 0
	s_cmpk_gt_u32 s45, 0x55
	s_mov_b64 s[20:21], s[10:11]
	s_barrier
	s_cbranch_scc0 .LBB0_991
	v_lshl_or_b32 v202, s41, 8, v230
	v_lshl_add_u32 v200, s42, 8, v228
	v_ashrrev_i32_e32 v203, 31, v202
	v_lshlrev_b64 v[226:227], 1, v[202:203]
	v_ashrrev_i32_e32 v201, 31, v200
	v_lshl_add_u64 v[86:87], s[94:95], 0, v[226:227]
	v_lshlrev_b64 v[236:237], 12, v[200:201]
	v_lshl_add_u64 v[88:89], v[86:87], 0, v[236:237]
	global_load_dwordx4 v[214:217], v[88:89], off
	global_load_dwordx4 v[186:189], v[88:89], off offset:256
	v_or_b32_e32 v88, 16, v200
	v_ashrrev_i32_e32 v89, 31, v88
	v_lshlrev_b64 v[224:225], 12, v[88:89]
	v_lshl_add_u64 v[88:89], v[86:87], 0, v[224:225]
	global_load_dwordx4 v[182:185], v[88:89], off
	global_load_dwordx4 v[178:181], v[88:89], off offset:256
	v_or_b32_e32 v88, 32, v200
	v_ashrrev_i32_e32 v89, 31, v88
	v_lshlrev_b64 v[222:223], 12, v[88:89]
	v_lshl_add_u64 v[88:89], v[86:87], 0, v[222:223]
	global_load_dwordx4 v[174:177], v[88:89], off
	global_load_dwordx4 v[170:173], v[88:89], off offset:256
	v_or_b32_e32 v88, 48, v200
	v_ashrrev_i32_e32 v89, 31, v88
	s_mov_b64 s[10:11], 0x80000
	v_lshlrev_b64 v[220:221], 12, v[88:89]
	v_lshl_add_u64 v[218:219], v[236:237], 0, s[10:11]
	s_mov_b64 s[10:11], 0x90000
	v_lshl_add_u64 v[88:89], v[86:87], 0, v[220:221]
	v_lshl_add_u64 v[208:209], v[236:237], 0, s[10:11]
	s_mov_b64 s[10:11], 0xa0000
	global_load_dwordx4 v[166:169], v[88:89], off
	global_load_dwordx4 v[162:165], v[88:89], off offset:256
	v_lshl_add_u64 v[88:89], v[86:87], 0, v[218:219]
	v_lshl_add_u64 v[206:207], v[236:237], 0, s[10:11]
	s_mov_b64 s[10:11], 0xb0000
	global_load_dwordx4 v[158:161], v[88:89], off
	global_load_dwordx4 v[154:157], v[88:89], off offset:256
	v_lshl_add_u64 v[88:89], v[86:87], 0, v[208:209]
	v_lshl_add_u64 v[204:205], v[236:237], 0, s[10:11]
	global_load_dwordx4 v[142:145], v[88:89], off
	global_load_dwordx4 v[130:133], v[88:89], off offset:256
	v_lshl_add_u64 v[88:89], v[86:87], 0, v[206:207]
	v_lshl_add_u64 v[86:87], v[86:87], 0, v[204:205]
	global_load_dwordx4 v[118:121], v[88:89], off
	global_load_dwordx4 v[106:109], v[88:89], off offset:256
	global_load_dwordx4 v[94:97], v[86:87], off
	s_nop 0
	global_load_dwordx4 v[86:89], v[86:87], off offset:256
	v_lshl_add_u64 v[236:237], s[94:95], 0, v[236:237]
	v_lshl_add_u64 v[226:227], v[236:237], 0, v[226:227]
	v_cndmask_b32_e64 v233, 0, 1, s[16:17]
	v_cmp_ne_u32_e64 s[10:11], 1, v233
	s_andn2_b64 vcc, exec, s[16:17]
	s_waitcnt vmcnt(0)
	v_lshlrev_b32_e32 v236, 16, v214
	v_and_b32_e32 v237, 0xffff0000, v214
	v_lshlrev_b32_e32 v214, 16, v215
	v_and_b32_e32 v215, 0xffff0000, v215
	v_lshlrev_b32_e32 v240, 16, v216
	v_and_b32_e32 v241, 0xffff0000, v216
	v_lshlrev_b32_e32 v216, 16, v217
	v_and_b32_e32 v217, 0xffff0000, v217
	v_pk_add_f32 v[152:153], v[152:153], v[214:215]
	v_pk_add_f32 v[150:151], v[150:151], v[236:237]
	v_pk_add_f32 v[214:215], v[148:149], v[216:217]
	v_pk_add_f32 v[148:149], v[146:147], v[240:241]
	v_cvt_pk_bf16_f32 v146, v150, v151
	v_cvt_pk_bf16_f32 v147, v152, v153
	v_cvt_pk_bf16_f32 v148, v148, v149
	v_cvt_pk_bf16_f32 v149, v214, v215
	v_mov_b32_e32 v150, 0
	global_store_dwordx4 v[226:227], v[146:149], off
	s_cbranch_vccnz .LBB0_994
	v_lshlrev_b32_e32 v150, 16, v146
	v_and_b32_e32 v151, 0xffff0000, v146
	v_pk_mul_f32 v[150:151], v[150:151], v[150:151]
	v_and_b32_e32 v146, 0xffff0000, v147
	v_lshlrev_b32_e32 v147, 16, v147
	v_pk_mul_f32 v[146:147], v[146:147], v[146:147]
	v_add_f32_e32 v150, v150, v151
	v_and_b32_e32 v152, 0xffff0000, v148
	v_lshlrev_b32_e32 v153, 16, v148
	v_add_f32_e32 v147, v147, v150
	v_pk_mul_f32 v[152:153], v[152:153], v[152:153]
	v_add_f32_e32 v146, v146, v147
	v_and_b32_e32 v148, 0xffff0000, v149
	v_lshlrev_b32_e32 v149, 16, v149
	v_add_f32_e32 v146, v153, v146
	v_pk_mul_f32 v[148:149], v[148:149], v[148:149]
	v_add_f32_e32 v146, v152, v146
	v_add_f32_e32 v146, v149, v146
	v_add_f32_e32 v150, v148, v146
